# GEMM K-loops: waves 4-7 issue their LDS-DMA burst after G2 (waves 0-3 at loop top) so VMEM-issue stalls of SIMD partners do not coincide; plus static prio
# speedup vs baseline: 1.0297x; 1.0094x over previous
.LBB0_237:
	s_or_b64 exec, exec, s[2:3]
	s_ashr_i32 s3, s9, 2
	s_lshr_b32 s2, s30, 3
	s_lshl_b32 s36, s3, 2
	s_ashr_i32 s23, s22, 31
	s_and_b32 s7, s29, 56
	s_and_b32 s31, s2, 3
	s_sub_i32 s8, s8, s36
	s_lshl_b64 s[2:3], s[22:23], 19
	s_add_u32 s2, s16, s2
	s_addc_u32 s3, s17, s3
	s_ashr_i32 s9, s8, 31
	v_mov_b32_e32 v8, v190
	s_lshl_b64 s[22:23], s[8:9], 19
	s_mov_b32 s9, 0x1ffff80
	v_and_b32_e32 v0, 15, v8
	v_lshrrev_b32_e32 v2, 1, v8
	v_and_or_b32 v0, v2, s9, v0
	v_bfe_u32 v1, v8, 4, 2
	v_lshlrev_b32_e32 v132, 7, v0
	v_bfe_u32 v0, v8, 1, 3
	v_bitop3_b32 v0, v1, v0, 4 bitop3:0x36
	v_lshlrev_b32_e32 v133, 4, v0
	v_lshlrev_b32_e32 v0, 7, v8
	v_and_b32_e32 v134, 0x6780, v0
	v_ashrrev_i32_e32 v0, 3, v8
	v_bitop3_b32 v2, v2, v1, 7 bitop3:0x6c
	v_ashrrev_i32_e32 v1, 31, v0
	v_lshrrev_b32_e32 v9, 4, v8
	v_lshlrev_b64 v[0:1], 11, v[0:1]
	s_add_u32 s34, s25, s22
	v_lshlrev_b32_e32 v135, 4, v2
	v_xor_b32_e32 v4, v9, v8
	v_lshl_add_u64 v[2:3], s[2:3], 0, v[0:1]
	v_readfirstlane_b32 s2, v8
	s_addc_u32 s35, s26, s23
	v_lshlrev_b32_e32 v4, 4, v4
	s_lshl_b32 s2, s2, 4
	v_and_b32_e32 v144, 0x70, v4
	s_and_b32 s2, s2, 0xfffffc00
	v_lshl_add_u64 v[2:3], v[2:3], 0, v[144:145]
	s_mov_b32 m0, s2
	s_mov_b64 s[38:39], 0x20000
	v_lshl_add_u64 v[4:5], s[34:35], 0, v[0:1]
	s_waitcnt lgkmcnt(0)
	s_barrier
	global_load_lds_dwordx4 v[2:3], off
	v_lshl_add_u64 v[6:7], v[2:3], 0, s[38:39]
	s_add_i32 m0, s2, 0x2000
	s_mov_b64 s[34:35], 0x40000
	global_load_lds_dwordx4 v[6:7], off
	v_lshl_add_u64 v[6:7], v[2:3], 0, s[34:35]
	s_add_i32 m0, s2, 0x4000
	s_mov_b64 s[40:41], 0x60000
	global_load_lds_dwordx4 v[6:7], off
	v_lshl_add_u64 v[2:3], v[2:3], 0, s[40:41]
	s_add_i32 m0, s2, 0x6000
	v_lshl_add_u64 v[4:5], v[4:5], 0, v[144:145]
	global_load_lds_dwordx4 v[2:3], off
	s_add_i32 m0, s2, 0x8000
	v_lshl_add_u64 v[2:3], v[4:5], 0, s[38:39]
	global_load_lds_dwordx4 v[4:5], off
	s_add_i32 m0, s2, 0xa000
	s_add_i32 s7, s7, s36
	global_load_lds_dwordx4 v[2:3], off
	v_lshl_add_u64 v[2:3], v[4:5], 0, s[34:35]
	s_add_i32 m0, s2, 0xc000
	v_mov_b32_e32 v88, 0
	global_load_lds_dwordx4 v[2:3], off
	v_lshl_add_u64 v[2:3], v[4:5], 0, s[40:41]
	s_add_i32 m0, s2, 0xe000
	v_bitop3_b32 v4, v9, 7, v8 bitop3:0x48
	global_load_lds_dwordx4 v[2:3], off
	v_lshl_add_u64 v[2:3], s[22:23], 0, v[0:1]
	s_or_b32 s22, s7, s31
	s_ashr_i32 s23, s22, 31
	s_lshl_b64 s[22:23], s[22:23], 19
	s_waitcnt vmcnt(0)
	v_lshlrev_b32_e32 v4, 4, v4
	v_lshl_add_u64 v[0:1], s[22:23], 0, v[0:1]
	v_or_b32_e32 v2, v2, v4
	v_or_b32_e32 v0, v0, v4
	s_mov_b64 s[86:87], 0x20000
	v_lshl_add_u64 v[128:129], s[14:15], 0, v[2:3]
	v_lshl_add_u64 v[130:131], s[14:15], 0, v[0:1]
	s_mov_b64 s[22:23], 0
	s_mov_b32 s3, 0
	v_mov_b32_e32 v89, v88
	v_mov_b32_e32 v90, v88
	v_mov_b32_e32 v91, v88
	v_mov_b32_e32 v0, v88
	v_mov_b32_e32 v1, v88
	v_mov_b32_e32 v2, v88
	v_mov_b32_e32 v3, v88
	v_mov_b32_e32 v4, v88
	v_mov_b32_e32 v5, v88
	v_mov_b32_e32 v6, v88
	v_mov_b32_e32 v7, v88
	v_mov_b32_e32 v8, v88
	v_mov_b32_e32 v9, v88
	v_mov_b32_e32 v10, v88
	v_mov_b32_e32 v11, v88
	v_mov_b32_e32 v12, v88
	v_mov_b32_e32 v13, v88
	v_mov_b32_e32 v14, v88
	v_mov_b32_e32 v15, v88
	v_mov_b32_e32 v16, v88
	v_mov_b32_e32 v17, v88
	v_mov_b32_e32 v18, v88
	v_mov_b32_e32 v19, v88
	v_mov_b32_e32 v20, v88
	v_mov_b32_e32 v21, v88
	v_mov_b32_e32 v22, v88
	v_mov_b32_e32 v23, v88
	v_mov_b32_e32 v24, v88
	v_mov_b32_e32 v25, v88
	v_mov_b32_e32 v26, v88
	v_mov_b32_e32 v27, v88
	v_mov_b32_e32 v28, v88
	v_mov_b32_e32 v29, v88
	v_mov_b32_e32 v30, v88
	v_mov_b32_e32 v31, v88
	v_mov_b32_e32 v32, v88
	v_mov_b32_e32 v33, v88
	v_mov_b32_e32 v34, v88
	v_mov_b32_e32 v35, v88
	v_mov_b32_e32 v36, v88
	v_mov_b32_e32 v37, v88
	v_mov_b32_e32 v38, v88
	v_mov_b32_e32 v39, v88
	v_mov_b32_e32 v40, v88
	v_mov_b32_e32 v41, v88
	v_mov_b32_e32 v42, v88
	v_mov_b32_e32 v43, v88
	v_mov_b32_e32 v44, v88
	v_mov_b32_e32 v45, v88
	v_mov_b32_e32 v46, v88
	v_mov_b32_e32 v47, v88
	v_mov_b32_e32 v48, v88
	v_mov_b32_e32 v49, v88
	v_mov_b32_e32 v50, v88
	v_mov_b32_e32 v51, v88
	v_mov_b32_e32 v52, v88
	v_mov_b32_e32 v53, v88
	v_mov_b32_e32 v54, v88
	v_mov_b32_e32 v55, v88
	v_mov_b32_e32 v56, v88
	v_mov_b32_e32 v57, v88
	v_mov_b32_e32 v58, v88
	v_mov_b32_e32 v59, v88
	v_mov_b32_e32 v60, v88
	v_mov_b32_e32 v61, v88
	v_mov_b32_e32 v62, v88
	v_mov_b32_e32 v63, v88
	v_mov_b32_e32 v64, v88
	v_mov_b32_e32 v65, v88
	v_mov_b32_e32 v66, v88
	v_mov_b32_e32 v67, v88
	v_mov_b32_e32 v68, v88
	v_mov_b32_e32 v69, v88
	v_mov_b32_e32 v70, v88
	v_mov_b32_e32 v71, v88
	v_mov_b32_e32 v72, v88
	v_mov_b32_e32 v73, v88
	v_mov_b32_e32 v74, v88
	v_mov_b32_e32 v75, v88
	v_mov_b32_e32 v76, v88
	v_mov_b32_e32 v77, v88
	v_mov_b32_e32 v78, v88
	v_mov_b32_e32 v79, v88
	v_mov_b32_e32 v80, v88
	v_mov_b32_e32 v81, v88
	v_mov_b32_e32 v82, v88
	v_mov_b32_e32 v83, v88
	v_mov_b32_e32 v84, v88
	v_mov_b32_e32 v85, v88
	v_mov_b32_e32 v86, v88
	v_mov_b32_e32 v87, v88
	v_mov_b32_e32 v92, v88
	v_mov_b32_e32 v93, v88
	v_mov_b32_e32 v94, v88
	v_mov_b32_e32 v95, v88
	v_mov_b32_e32 v96, v88
	v_mov_b32_e32 v97, v88
	v_mov_b32_e32 v98, v88
	v_mov_b32_e32 v99, v88
	v_mov_b32_e32 v100, v88
	v_mov_b32_e32 v101, v88
	v_mov_b32_e32 v102, v88
	v_mov_b32_e32 v103, v88
	v_mov_b32_e32 v104, v88
	v_mov_b32_e32 v105, v88
	v_mov_b32_e32 v106, v88
	v_mov_b32_e32 v107, v88
	v_mov_b32_e32 v108, v88
	v_mov_b32_e32 v109, v88
	v_mov_b32_e32 v110, v88
	v_mov_b32_e32 v111, v88
	v_mov_b32_e32 v112, v88
	v_mov_b32_e32 v113, v88
	v_mov_b32_e32 v114, v88
	v_mov_b32_e32 v115, v88
	v_mov_b32_e32 v116, v88
	v_mov_b32_e32 v117, v88
	v_mov_b32_e32 v118, v88
	v_mov_b32_e32 v119, v88
	v_mov_b32_e32 v120, v88
	v_mov_b32_e32 v121, v88
	v_mov_b32_e32 v122, v88
	v_mov_b32_e32 v123, v88
	v_mov_b32_e32 v124, v88
	v_mov_b32_e32 v125, v88
	v_mov_b32_e32 v126, v88
	v_mov_b32_e32 v127, v88
	s_mov_b64 s[36:37], 0x3a20080
	s_mov_b64 s[38:39], 0x3a40080
	s_waitcnt vmcnt(0) lgkmcnt(0)
	s_barrier
	s_bitcmp1_b32 s2, 12
	s_cbranch_scc1 .Lkb_238
.LBB0_238:
	s_add_i32 s7, s3, 0x10000
	s_and_b32 s9, s7, 0x10000
	s_add_i32 s9, s2, s9
	v_lshl_add_u64 v[136:137], v[130:131], 0, s[22:23]
	v_lshl_add_u64 v[138:139], v[136:137], 0, s[44:45]
	s_mov_b32 m0, s9
	s_mov_b64 s[34:35], 0x2100080
	global_load_lds_dwordx4 v[138:139], off
	v_lshl_add_u64 v[138:139], v[136:137], 0, s[46:47]
	s_add_i32 m0, s9, 0x2000
	s_nop 0
	global_load_lds_dwordx4 v[138:139], off
	v_lshl_add_u64 v[138:139], v[136:137], 0, s[36:37]
	s_add_i32 m0, s9, 0x4000
	v_lshl_add_u64 v[136:137], v[136:137], 0, s[38:39]
	global_load_lds_dwordx4 v[138:139], off
	s_add_i32 m0, s9, 0x6000
	s_nop 0
	global_load_lds_dwordx4 v[136:137], off
	v_lshl_add_u64 v[136:137], v[128:129], 0, s[22:23]
	v_lshl_add_u64 v[138:139], v[136:137], 0, s[34:35]
	s_add_i32 m0, s9, 0x8000
	s_mov_b64 s[34:35], 0x2120080
	global_load_lds_dwordx4 v[138:139], off
	v_lshl_add_u64 v[138:139], v[136:137], 0, s[34:35]
	s_add_i32 m0, s9, 0xa000
	s_mov_b64 s[34:35], 0x2140080
	global_load_lds_dwordx4 v[138:139], off
	v_lshl_add_u64 v[138:139], v[136:137], 0, s[34:35]
	s_add_i32 m0, s9, 0xc000
	s_mov_b64 s[34:35], 0x2160080
	global_load_lds_dwordx4 v[138:139], off
	v_lshl_add_u64 v[136:137], v[136:137], 0, s[34:35]
	s_add_i32 m0, s9, 0xe000
	s_nop 0
	global_load_lds_dwordx4 v[136:137], off
	s_and_b32 s3, s3, 0x10000
	v_or_b32_e32 v144, s3, v135
	v_add_u32_e32 v151, v144, v134
	v_add_u32_e32 v144, v144, v132
	ds_read_b128 v[136:139], v151 offset:32768
	ds_read_b128 v[140:143], v151 offset:34816
	ds_read_b128 v[146:149], v151 offset:36864
	ds_read_b128 v[154:157], v151 offset:38912
	ds_read_b128 v[158:161], v144
	ds_read_b128 v[162:165], v144 offset:2048
	ds_read_b128 v[166:169], v144 offset:4096
	ds_read_b128 v[170:173], v144 offset:6144
	ds_read_b128 v[174:177], v144 offset:8192
	ds_read_b128 v[178:181], v144 offset:10240
	ds_read_b128 v[182:185], v144 offset:12288
	ds_read_b128 v[186:189], v144 offset:14336
	s_waitcnt lgkmcnt(0)
	v_mfma_f32_16x16x32_bf16 v[124:127], v[136:139], v[158:161], v[124:127]
	v_mfma_f32_16x16x32_bf16 v[120:123], v[140:143], v[158:161], v[120:123]
	v_mfma_f32_16x16x32_bf16 v[116:119], v[146:149], v[158:161], v[116:119]
	v_mfma_f32_16x16x32_bf16 v[112:115], v[154:157], v[158:161], v[112:115]
	v_mfma_f32_16x16x32_bf16 v[108:111], v[136:139], v[162:165], v[108:111]
	v_mfma_f32_16x16x32_bf16 v[104:107], v[140:143], v[162:165], v[104:107]
	v_mfma_f32_16x16x32_bf16 v[100:103], v[146:149], v[162:165], v[100:103]
	v_mfma_f32_16x16x32_bf16 v[96:99], v[154:157], v[162:165], v[96:99]
	v_mfma_f32_16x16x32_bf16 v[92:95], v[136:139], v[166:169], v[92:95]
	v_mfma_f32_16x16x32_bf16 v[84:87], v[140:143], v[166:169], v[84:87]
	v_mfma_f32_16x16x32_bf16 v[80:83], v[146:149], v[166:169], v[80:83]
	v_mfma_f32_16x16x32_bf16 v[76:79], v[154:157], v[166:169], v[76:79]
	v_mfma_f32_16x16x32_bf16 v[72:75], v[136:139], v[170:173], v[72:75]
	v_mfma_f32_16x16x32_bf16 v[68:71], v[140:143], v[170:173], v[68:71]
	v_mfma_f32_16x16x32_bf16 v[64:67], v[146:149], v[170:173], v[64:67]
	v_mfma_f32_16x16x32_bf16 v[60:63], v[154:157], v[170:173], v[60:63]
	v_or_b32_e32 v144, s3, v133
	v_add_u32_e32 v151, v144, v134
	v_add_u32_e32 v144, v144, v132
	ds_read_b128 v[158:161], v151 offset:32768
	ds_read_b128 v[162:165], v151 offset:34816
	ds_read_b128 v[166:169], v151 offset:36864
	ds_read_b128 v[170:173], v151 offset:38912
	ds_read_b128 v[206:209], v144
	ds_read_b128 v[216:219], v144 offset:2048
	ds_read_b128 v[220:223], v144 offset:4096
	ds_read_b128 v[224:227], v144 offset:6144
	v_mfma_f32_16x16x32_bf16 v[56:59], v[136:139], v[174:177], v[56:59]
	v_mfma_f32_16x16x32_bf16 v[52:55], v[140:143], v[174:177], v[52:55]
	v_mfma_f32_16x16x32_bf16 v[48:51], v[146:149], v[174:177], v[48:51]
	v_mfma_f32_16x16x32_bf16 v[44:47], v[154:157], v[174:177], v[44:47]
	v_mfma_f32_16x16x32_bf16 v[40:43], v[136:139], v[178:181], v[40:43]
	v_mfma_f32_16x16x32_bf16 v[36:39], v[140:143], v[178:181], v[36:39]
	v_mfma_f32_16x16x32_bf16 v[32:35], v[146:149], v[178:181], v[32:35]
	v_mfma_f32_16x16x32_bf16 v[28:31], v[154:157], v[178:181], v[28:31]
	v_mfma_f32_16x16x32_bf16 v[24:27], v[136:139], v[182:185], v[24:27]
	v_mfma_f32_16x16x32_bf16 v[20:23], v[140:143], v[182:185], v[20:23]
	v_mfma_f32_16x16x32_bf16 v[16:19], v[146:149], v[182:185], v[16:19]
	v_mfma_f32_16x16x32_bf16 v[12:15], v[154:157], v[182:185], v[12:15]
	v_mfma_f32_16x16x32_bf16 v[8:11], v[136:139], v[186:189], v[8:11]
	v_mfma_f32_16x16x32_bf16 v[4:7], v[140:143], v[186:189], v[4:7]
	v_mfma_f32_16x16x32_bf16 v[0:3], v[146:149], v[186:189], v[0:3]
	v_mfma_f32_16x16x32_bf16 v[88:91], v[154:157], v[186:189], v[88:91]
	ds_read_b128 v[136:139], v144 offset:8192
	ds_read_b128 v[140:143], v144 offset:10240
	ds_read_b128 v[146:149], v144 offset:12288
	ds_read_b128 v[154:157], v144 offset:14336
	s_waitcnt lgkmcnt(0)
	v_mfma_f32_16x16x32_bf16 v[124:127], v[158:161], v[206:209], v[124:127]
	v_mfma_f32_16x16x32_bf16 v[120:123], v[162:165], v[206:209], v[120:123]
	v_mfma_f32_16x16x32_bf16 v[116:119], v[166:169], v[206:209], v[116:119]
	v_mfma_f32_16x16x32_bf16 v[112:115], v[170:173], v[206:209], v[112:115]
	v_mfma_f32_16x16x32_bf16 v[108:111], v[158:161], v[216:219], v[108:111]
	v_mfma_f32_16x16x32_bf16 v[104:107], v[162:165], v[216:219], v[104:107]
	v_mfma_f32_16x16x32_bf16 v[100:103], v[166:169], v[216:219], v[100:103]
	v_mfma_f32_16x16x32_bf16 v[96:99], v[170:173], v[216:219], v[96:99]
	v_mfma_f32_16x16x32_bf16 v[92:95], v[158:161], v[220:223], v[92:95]
	v_mfma_f32_16x16x32_bf16 v[84:87], v[162:165], v[220:223], v[84:87]
	v_mfma_f32_16x16x32_bf16 v[80:83], v[166:169], v[220:223], v[80:83]
	v_mfma_f32_16x16x32_bf16 v[76:79], v[170:173], v[220:223], v[76:79]
	v_mfma_f32_16x16x32_bf16 v[72:75], v[158:161], v[224:227], v[72:75]
	v_mfma_f32_16x16x32_bf16 v[68:71], v[162:165], v[224:227], v[68:71]
	v_mfma_f32_16x16x32_bf16 v[64:67], v[166:169], v[224:227], v[64:67]
	v_mfma_f32_16x16x32_bf16 v[60:63], v[170:173], v[224:227], v[60:63]
	v_mfma_f32_16x16x32_bf16 v[56:59], v[158:161], v[136:139], v[56:59]
	s_waitcnt vmcnt(0)
	s_add_u32 s22, s22, 0x80
	s_addc_u32 s23, s23, 0
	v_mfma_f32_16x16x32_bf16 v[52:55], v[162:165], v[136:139], v[52:55]
	s_cmpk_eq_i32 s22, 0x780
	s_mov_b32 s3, s7
	s_waitcnt vmcnt(0)
	v_mfma_f32_16x16x32_bf16 v[48:51], v[166:169], v[136:139], v[48:51]
	s_barrier
	v_mfma_f32_16x16x32_bf16 v[44:47], v[170:173], v[136:139], v[44:47]
	v_mfma_f32_16x16x32_bf16 v[40:43], v[158:161], v[140:143], v[40:43]
	v_mfma_f32_16x16x32_bf16 v[36:39], v[162:165], v[140:143], v[36:39]
	v_mfma_f32_16x16x32_bf16 v[32:35], v[166:169], v[140:143], v[32:35]
	v_mfma_f32_16x16x32_bf16 v[28:31], v[170:173], v[140:143], v[28:31]
	v_mfma_f32_16x16x32_bf16 v[24:27], v[158:161], v[146:149], v[24:27]
	v_mfma_f32_16x16x32_bf16 v[20:23], v[162:165], v[146:149], v[20:23]
	v_mfma_f32_16x16x32_bf16 v[16:19], v[166:169], v[146:149], v[16:19]
	v_mfma_f32_16x16x32_bf16 v[12:15], v[170:173], v[146:149], v[12:15]
	v_mfma_f32_16x16x32_bf16 v[8:11], v[158:161], v[154:157], v[8:11]
	v_mfma_f32_16x16x32_bf16 v[4:7], v[162:165], v[154:157], v[4:7]
	v_mfma_f32_16x16x32_bf16 v[0:3], v[166:169], v[154:157], v[0:3]
	v_mfma_f32_16x16x32_bf16 v[88:91], v[170:173], v[154:157], v[88:91]
	s_cbranch_scc0 .LBB0_238
	s_branch .Lkx_238
.Lkb_238:
	s_add_i32 s7, s3, 0x10000
	s_and_b32 s9, s7, 0x10000
	s_add_i32 s9, s2, s9
	s_and_b32 s3, s3, 0x10000
	v_or_b32_e32 v144, s3, v135
	v_add_u32_e32 v151, v144, v134
	v_add_u32_e32 v144, v144, v132
	ds_read_b128 v[136:139], v151 offset:32768
	ds_read_b128 v[140:143], v151 offset:34816
	ds_read_b128 v[146:149], v151 offset:36864
	ds_read_b128 v[154:157], v151 offset:38912
	ds_read_b128 v[158:161], v144
	ds_read_b128 v[162:165], v144 offset:2048
	ds_read_b128 v[166:169], v144 offset:4096
	ds_read_b128 v[170:173], v144 offset:6144
	ds_read_b128 v[174:177], v144 offset:8192
	ds_read_b128 v[178:181], v144 offset:10240
	ds_read_b128 v[182:185], v144 offset:12288
	ds_read_b128 v[186:189], v144 offset:14336
	s_waitcnt lgkmcnt(0)
	v_mfma_f32_16x16x32_bf16 v[124:127], v[136:139], v[158:161], v[124:127]
	v_mfma_f32_16x16x32_bf16 v[120:123], v[140:143], v[158:161], v[120:123]
	v_mfma_f32_16x16x32_bf16 v[116:119], v[146:149], v[158:161], v[116:119]
	v_mfma_f32_16x16x32_bf16 v[112:115], v[154:157], v[158:161], v[112:115]
	v_mfma_f32_16x16x32_bf16 v[108:111], v[136:139], v[162:165], v[108:111]
	v_mfma_f32_16x16x32_bf16 v[104:107], v[140:143], v[162:165], v[104:107]
	v_mfma_f32_16x16x32_bf16 v[100:103], v[146:149], v[162:165], v[100:103]
	v_mfma_f32_16x16x32_bf16 v[96:99], v[154:157], v[162:165], v[96:99]
	v_mfma_f32_16x16x32_bf16 v[92:95], v[136:139], v[166:169], v[92:95]
	v_mfma_f32_16x16x32_bf16 v[84:87], v[140:143], v[166:169], v[84:87]
	v_mfma_f32_16x16x32_bf16 v[80:83], v[146:149], v[166:169], v[80:83]
	v_mfma_f32_16x16x32_bf16 v[76:79], v[154:157], v[166:169], v[76:79]
	v_mfma_f32_16x16x32_bf16 v[72:75], v[136:139], v[170:173], v[72:75]
	v_mfma_f32_16x16x32_bf16 v[68:71], v[140:143], v[170:173], v[68:71]
	v_mfma_f32_16x16x32_bf16 v[64:67], v[146:149], v[170:173], v[64:67]
	v_mfma_f32_16x16x32_bf16 v[60:63], v[154:157], v[170:173], v[60:63]
	v_or_b32_e32 v144, s3, v133
	v_add_u32_e32 v151, v144, v134
	v_add_u32_e32 v144, v144, v132
	ds_read_b128 v[158:161], v151 offset:32768
	ds_read_b128 v[162:165], v151 offset:34816
	ds_read_b128 v[166:169], v151 offset:36864
	ds_read_b128 v[170:173], v151 offset:38912
	ds_read_b128 v[206:209], v144
	ds_read_b128 v[216:219], v144 offset:2048
	ds_read_b128 v[220:223], v144 offset:4096
	ds_read_b128 v[224:227], v144 offset:6144
	v_mfma_f32_16x16x32_bf16 v[56:59], v[136:139], v[174:177], v[56:59]
	v_mfma_f32_16x16x32_bf16 v[52:55], v[140:143], v[174:177], v[52:55]
	v_mfma_f32_16x16x32_bf16 v[48:51], v[146:149], v[174:177], v[48:51]
	v_mfma_f32_16x16x32_bf16 v[44:47], v[154:157], v[174:177], v[44:47]
	v_mfma_f32_16x16x32_bf16 v[40:43], v[136:139], v[178:181], v[40:43]
	v_mfma_f32_16x16x32_bf16 v[36:39], v[140:143], v[178:181], v[36:39]
	v_mfma_f32_16x16x32_bf16 v[32:35], v[146:149], v[178:181], v[32:35]
	v_mfma_f32_16x16x32_bf16 v[28:31], v[154:157], v[178:181], v[28:31]
	v_mfma_f32_16x16x32_bf16 v[24:27], v[136:139], v[182:185], v[24:27]
	v_mfma_f32_16x16x32_bf16 v[20:23], v[140:143], v[182:185], v[20:23]
	v_mfma_f32_16x16x32_bf16 v[16:19], v[146:149], v[182:185], v[16:19]
	v_mfma_f32_16x16x32_bf16 v[12:15], v[154:157], v[182:185], v[12:15]
	v_mfma_f32_16x16x32_bf16 v[8:11], v[136:139], v[186:189], v[8:11]
	v_mfma_f32_16x16x32_bf16 v[4:7], v[140:143], v[186:189], v[4:7]
	v_mfma_f32_16x16x32_bf16 v[0:3], v[146:149], v[186:189], v[0:3]
	v_mfma_f32_16x16x32_bf16 v[88:91], v[154:157], v[186:189], v[88:91]
	v_lshl_add_u64 v[244:245], v[130:131], 0, s[22:23]
	v_lshl_add_u64 v[246:247], v[244:245], 0, s[44:45]
	s_mov_b32 m0, s9
	s_mov_b64 s[34:35], 0x2100080
	global_load_lds_dwordx4 v[246:247], off
	v_lshl_add_u64 v[246:247], v[244:245], 0, s[46:47]
	s_add_i32 m0, s9, 0x2000
	s_nop 0
	global_load_lds_dwordx4 v[246:247], off
	v_lshl_add_u64 v[246:247], v[244:245], 0, s[36:37]
	s_add_i32 m0, s9, 0x4000
	v_lshl_add_u64 v[244:245], v[244:245], 0, s[38:39]
	global_load_lds_dwordx4 v[246:247], off
	s_add_i32 m0, s9, 0x6000
	s_nop 0
	global_load_lds_dwordx4 v[244:245], off
	v_lshl_add_u64 v[244:245], v[128:129], 0, s[22:23]
	v_lshl_add_u64 v[246:247], v[244:245], 0, s[34:35]
	s_add_i32 m0, s9, 0x8000
	s_mov_b64 s[34:35], 0x2120080
	global_load_lds_dwordx4 v[246:247], off
	v_lshl_add_u64 v[246:247], v[244:245], 0, s[34:35]
	s_add_i32 m0, s9, 0xa000
	s_mov_b64 s[34:35], 0x2140080
	global_load_lds_dwordx4 v[246:247], off
	v_lshl_add_u64 v[246:247], v[244:245], 0, s[34:35]
	s_add_i32 m0, s9, 0xc000
	s_mov_b64 s[34:35], 0x2160080
	global_load_lds_dwordx4 v[246:247], off
	v_lshl_add_u64 v[244:245], v[244:245], 0, s[34:35]
	s_add_i32 m0, s9, 0xe000
	s_nop 0
	global_load_lds_dwordx4 v[244:245], off
	ds_read_b128 v[136:139], v144 offset:8192
	ds_read_b128 v[140:143], v144 offset:10240
	ds_read_b128 v[146:149], v144 offset:12288
	ds_read_b128 v[154:157], v144 offset:14336
	s_waitcnt lgkmcnt(0)
	v_mfma_f32_16x16x32_bf16 v[124:127], v[158:161], v[206:209], v[124:127]
	v_mfma_f32_16x16x32_bf16 v[120:123], v[162:165], v[206:209], v[120:123]
	v_mfma_f32_16x16x32_bf16 v[116:119], v[166:169], v[206:209], v[116:119]
	v_mfma_f32_16x16x32_bf16 v[112:115], v[170:173], v[206:209], v[112:115]
	v_mfma_f32_16x16x32_bf16 v[108:111], v[158:161], v[216:219], v[108:111]
	v_mfma_f32_16x16x32_bf16 v[104:107], v[162:165], v[216:219], v[104:107]
	v_mfma_f32_16x16x32_bf16 v[100:103], v[166:169], v[216:219], v[100:103]
	v_mfma_f32_16x16x32_bf16 v[96:99], v[170:173], v[216:219], v[96:99]
	v_mfma_f32_16x16x32_bf16 v[92:95], v[158:161], v[220:223], v[92:95]
	v_mfma_f32_16x16x32_bf16 v[84:87], v[162:165], v[220:223], v[84:87]
	v_mfma_f32_16x16x32_bf16 v[80:83], v[166:169], v[220:223], v[80:83]
	v_mfma_f32_16x16x32_bf16 v[76:79], v[170:173], v[220:223], v[76:79]
	v_mfma_f32_16x16x32_bf16 v[72:75], v[158:161], v[224:227], v[72:75]
	v_mfma_f32_16x16x32_bf16 v[68:71], v[162:165], v[224:227], v[68:71]
	v_mfma_f32_16x16x32_bf16 v[64:67], v[166:169], v[224:227], v[64:67]
	v_mfma_f32_16x16x32_bf16 v[60:63], v[170:173], v[224:227], v[60:63]
	v_mfma_f32_16x16x32_bf16 v[56:59], v[158:161], v[136:139], v[56:59]
	s_add_u32 s22, s22, 0x80
	s_addc_u32 s23, s23, 0
	v_mfma_f32_16x16x32_bf16 v[52:55], v[162:165], v[136:139], v[52:55]
	s_cmpk_eq_i32 s22, 0x780
	s_mov_b32 s3, s7
	s_waitcnt vmcnt(0)
	v_mfma_f32_16x16x32_bf16 v[48:51], v[166:169], v[136:139], v[48:51]
	s_barrier
	v_mfma_f32_16x16x32_bf16 v[44:47], v[170:173], v[136:139], v[44:47]
	v_mfma_f32_16x16x32_bf16 v[40:43], v[158:161], v[140:143], v[40:43]
	v_mfma_f32_16x16x32_bf16 v[36:39], v[162:165], v[140:143], v[36:39]
	v_mfma_f32_16x16x32_bf16 v[32:35], v[166:169], v[140:143], v[32:35]
	v_mfma_f32_16x16x32_bf16 v[28:31], v[170:173], v[140:143], v[28:31]
	v_mfma_f32_16x16x32_bf16 v[24:27], v[158:161], v[146:149], v[24:27]
	v_mfma_f32_16x16x32_bf16 v[20:23], v[162:165], v[146:149], v[20:23]
	v_mfma_f32_16x16x32_bf16 v[16:19], v[166:169], v[146:149], v[16:19]
	v_mfma_f32_16x16x32_bf16 v[12:15], v[170:173], v[146:149], v[12:15]
	v_mfma_f32_16x16x32_bf16 v[8:11], v[158:161], v[154:157], v[8:11]
	v_mfma_f32_16x16x32_bf16 v[4:7], v[162:165], v[154:157], v[4:7]
	v_mfma_f32_16x16x32_bf16 v[0:3], v[166:169], v[154:157], v[0:3]
	v_mfma_f32_16x16x32_bf16 v[88:91], v[170:173], v[154:157], v[88:91]
	s_cbranch_scc0 .Lkb_238
.Lkx_238:
	s_mov_b32 s2, 0x18000
	v_add3_u32 v144, v134, v135, s2
	v_add3_u32 v135, v132, v135, s81
	ds_read_b128 v[128:131], v144
	ds_read_b128 v[136:139], v144 offset:2048
	ds_read_b128 v[140:143], v144 offset:4096
	ds_read_b128 v[146:149], v144 offset:6144
	ds_read_b128 v[154:157], v135
	ds_read_b128 v[158:161], v135 offset:2048
	ds_read_b128 v[162:165], v135 offset:4096
	ds_read_b128 v[166:169], v135 offset:6144
	ds_read_b128 v[170:173], v135 offset:8192
	ds_read_b128 v[174:177], v135 offset:10240
	ds_read_b128 v[178:181], v135 offset:12288
	ds_read_b128 v[182:185], v135 offset:14336
	s_waitcnt lgkmcnt(7)
	v_mfma_f32_16x16x32_bf16 v[124:127], v[128:131], v[154:157], v[124:127]
	v_mfma_f32_16x16x32_bf16 v[120:123], v[136:139], v[154:157], v[120:123]
	v_mfma_f32_16x16x32_bf16 v[116:119], v[140:143], v[154:157], v[116:119]
	v_mfma_f32_16x16x32_bf16 v[112:115], v[146:149], v[154:157], v[112:115]
	s_waitcnt lgkmcnt(6)
	v_mfma_f32_16x16x32_bf16 v[108:111], v[128:131], v[158:161], v[108:111]
	v_mfma_f32_16x16x32_bf16 v[104:107], v[136:139], v[158:161], v[104:107]
	v_mfma_f32_16x16x32_bf16 v[100:103], v[140:143], v[158:161], v[100:103]
	v_mfma_f32_16x16x32_bf16 v[96:99], v[146:149], v[158:161], v[96:99]
	s_waitcnt lgkmcnt(5)
	v_mfma_f32_16x16x32_bf16 v[92:95], v[128:131], v[162:165], v[92:95]
	v_mfma_f32_16x16x32_bf16 v[84:87], v[136:139], v[162:165], v[84:87]
	v_mfma_f32_16x16x32_bf16 v[80:83], v[140:143], v[162:165], v[80:83]
	v_mfma_f32_16x16x32_bf16 v[76:79], v[146:149], v[162:165], v[76:79]
	s_waitcnt lgkmcnt(4)
	v_mfma_f32_16x16x32_bf16 v[72:75], v[128:131], v[166:169], v[72:75]
	v_mfma_f32_16x16x32_bf16 v[68:71], v[136:139], v[166:169], v[68:71]
	v_mfma_f32_16x16x32_bf16 v[64:67], v[140:143], v[166:169], v[64:67]
	v_mfma_f32_16x16x32_bf16 v[60:63], v[146:149], v[166:169], v[60:63]
	v_add3_u32 v134, v134, v133, s2
	v_add3_u32 v144, v132, v133, s81
	ds_read_b128 v[154:157], v134
	ds_read_b128 v[158:161], v134 offset:2048
	ds_read_b128 v[162:165], v134 offset:4096
	ds_read_b128 v[166:169], v134 offset:6144
	ds_read_b128 v[132:135], v144
	ds_read_b128 v[186:189], v144 offset:2048
	ds_read_b128 v[206:209], v144 offset:4096
	ds_read_b128 v[216:219], v144 offset:6144
	s_waitcnt lgkmcnt(11)
	v_mfma_f32_16x16x32_bf16 v[56:59], v[128:131], v[170:173], v[56:59]
	v_mfma_f32_16x16x32_bf16 v[52:55], v[136:139], v[170:173], v[52:55]
	v_mfma_f32_16x16x32_bf16 v[48:51], v[140:143], v[170:173], v[48:51]
	v_mfma_f32_16x16x32_bf16 v[44:47], v[146:149], v[170:173], v[44:47]
	s_waitcnt lgkmcnt(10)
	v_mfma_f32_16x16x32_bf16 v[40:43], v[128:131], v[174:177], v[40:43]
	v_mfma_f32_16x16x32_bf16 v[36:39], v[136:139], v[174:177], v[36:39]
	v_mfma_f32_16x16x32_bf16 v[32:35], v[140:143], v[174:177], v[32:35]
	v_mfma_f32_16x16x32_bf16 v[28:31], v[146:149], v[174:177], v[28:31]
	s_waitcnt lgkmcnt(9)
	v_mfma_f32_16x16x32_bf16 v[24:27], v[128:131], v[178:181], v[24:27]
	v_mfma_f32_16x16x32_bf16 v[20:23], v[136:139], v[178:181], v[20:23]
	v_mfma_f32_16x16x32_bf16 v[16:19], v[140:143], v[178:181], v[16:19]
	v_mfma_f32_16x16x32_bf16 v[12:15], v[146:149], v[178:181], v[12:15]
	s_waitcnt lgkmcnt(8)
	v_mfma_f32_16x16x32_bf16 v[8:11], v[128:131], v[182:185], v[8:11]
	v_mfma_f32_16x16x32_bf16 v[4:7], v[136:139], v[182:185], v[4:7]
	v_mfma_f32_16x16x32_bf16 v[0:3], v[140:143], v[182:185], v[0:3]
	v_mfma_f32_16x16x32_bf16 v[128:131], v[146:149], v[182:185], v[88:91]
	ds_read_b128 v[136:139], v144 offset:8192
	ds_read_b128 v[140:143], v144 offset:10240
	ds_read_b128 v[146:149], v144 offset:12288
	ds_read_b128 v[170:173], v144 offset:14336
	s_waitcnt lgkmcnt(7)
	v_mfma_f32_16x16x32_bf16 v[124:127], v[154:157], v[132:135], v[124:127]
	v_mfma_f32_16x16x32_bf16 v[120:123], v[158:161], v[132:135], v[120:123]
	v_mfma_f32_16x16x32_bf16 v[116:119], v[162:165], v[132:135], v[116:119]
	v_mfma_f32_16x16x32_bf16 v[112:115], v[166:169], v[132:135], v[112:115]
	s_waitcnt lgkmcnt(6)
	v_mfma_f32_16x16x32_bf16 v[108:111], v[154:157], v[186:189], v[108:111]
	v_mfma_f32_16x16x32_bf16 v[132:135], v[158:161], v[186:189], v[104:107]
	v_mfma_f32_16x16x32_bf16 v[174:177], v[162:165], v[186:189], v[100:103]
	v_mfma_f32_16x16x32_bf16 v[96:99], v[166:169], v[186:189], v[96:99]
	s_waitcnt lgkmcnt(5)
	v_mfma_f32_16x16x32_bf16 v[92:95], v[154:157], v[206:209], v[92:95]
	v_mfma_f32_16x16x32_bf16 v[88:91], v[158:161], v[206:209], v[84:87]
	v_mfma_f32_16x16x32_bf16 v[84:87], v[162:165], v[206:209], v[80:83]
	v_mfma_f32_16x16x32_bf16 v[80:83], v[166:169], v[206:209], v[76:79]
	s_waitcnt lgkmcnt(4)
	v_mfma_f32_16x16x32_bf16 v[76:79], v[154:157], v[216:219], v[72:75]
	v_mfma_f32_16x16x32_bf16 v[72:75], v[158:161], v[216:219], v[68:71]
	v_mfma_f32_16x16x32_bf16 v[68:71], v[162:165], v[216:219], v[64:67]
	v_mfma_f32_16x16x32_bf16 v[64:67], v[166:169], v[216:219], v[60:63]
	v_mov_b32_e32 v101, v190
	s_lshl_b32 s2, s8, 8
	v_ashrrev_i32_e32 v100, 1, v101
	v_and_b32_e32 v103, 15, v101
	v_and_b32_e32 v104, 0xffffff80, v100
	v_or_b32_e32 v100, s6, v103
	v_or_b32_e32 v103, v104, v103
	v_add_u32_e32 v100, v100, v104
	v_lshl_add_u32 v104, v103, 2, v205
	s_ashr_i32 s3, s2, 31
	s_lshl_b64 s[2:3], s[2:3], 1
	ds_read_b32 v106, v104
	v_and_b32_e32 v102, 0xc0, v101
	s_add_u32 s2, s27, s2
	s_addc_u32 s3, s28, s3
	v_lshlrev_b32_e32 v144, 1, v102
	v_lshrrev_b32_e32 v101, 1, v101
	v_lshl_add_u64 v[102:103], s[2:3], 0, v[144:145]
	v_and_b32_e32 v144, 24, v101
	v_ashrrev_i32_e32 v101, 31, v100
	s_waitcnt lgkmcnt(4)
	v_mfma_f32_16x16x32_bf16 v[60:63], v[154:157], v[136:139], v[56:59]
	v_lshl_add_u64 v[102:103], v[102:103], 0, v[144:145]
	s_waitcnt lgkmcnt(0)
	v_pk_mul_f32 v[126:127], v[126:127], v[106:107] op_sel_hi:[1,0]
	v_pk_mul_f32 v[124:125], v[124:125], v[106:107] op_sel_hi:[1,0]
	v_mfma_f32_16x16x32_bf16 v[56:59], v[158:161], v[136:139], v[52:55]
	v_mul_f32_e64 v122, v122, v106
	v_mul_f32_e64 v123, v123, v106
	v_pk_mul_f32 v[120:121], v[120:121], v[106:107] op_sel_hi:[1,0]
	v_pk_mul_f32 v[118:119], v[118:119], v[106:107] op_sel_hi:[1,0]
	v_mfma_f32_16x16x32_bf16 v[52:55], v[162:165], v[136:139], v[48:51]
	v_mul_f32_e64 v116, v116, v106
	v_mul_f32_e64 v117, v117, v106
	v_pk_mul_f32 v[114:115], v[114:115], v[106:107] op_sel_hi:[1,0]
	v_pk_mul_f32 v[106:107], v[112:113], v[106:107] op_sel_hi:[1,0]
	v_mfma_f32_16x16x32_bf16 v[48:51], v[166:169], v[136:139], v[44:47]
	v_cvt_pk_bf16_f32 v124, v124, v125
	v_cvt_pk_bf16_f32 v125, v126, v127
	v_cvt_pk_bf16_f32 v120, v120, v121
	v_mfma_f32_16x16x32_bf16 v[44:47], v[154:157], v[140:143], v[40:43]
	v_cvt_pk_bf16_f32 v121, v122, v123
	v_cvt_pk_bf16_f32 v116, v116, v117
	v_cvt_pk_bf16_f32 v117, v118, v119
	v_mfma_f32_16x16x32_bf16 v[40:43], v[158:161], v[140:143], v[36:39]
	v_cvt_pk_bf16_f32 v106, v106, v107
	v_cvt_pk_bf16_f32 v107, v114, v115
	v_readlane_b32 s2, v255, 6
	v_mfma_f32_16x16x32_bf16 v[36:39], v[162:165], v[140:143], v[32:35]
	s_add_i32 s30, s30, s72
	s_add_i32 s29, s29, s2
	s_cmpk_gt_i32 s30, 0xff
	v_mfma_f32_16x16x32_bf16 v[32:35], v[166:169], v[140:143], v[28:31]
	v_readlane_b32 s3, v255, 7
	v_mfma_f32_16x16x32_bf16 v[28:31], v[154:157], v[146:149], v[24:27]
	v_mfma_f32_16x16x32_bf16 v[24:27], v[158:161], v[146:149], v[20:23]
	v_mfma_f32_16x16x32_bf16 v[20:23], v[162:165], v[146:149], v[16:19]
	v_mfma_f32_16x16x32_bf16 v[16:19], v[166:169], v[146:149], v[12:15]
	v_mfma_f32_16x16x32_bf16 v[12:15], v[154:157], v[170:173], v[8:11]
	v_mfma_f32_16x16x32_bf16 v[8:11], v[158:161], v[170:173], v[4:7]
	v_mfma_f32_16x16x32_bf16 v[4:7], v[162:165], v[170:173], v[0:3]
	v_mfma_f32_16x16x32_bf16 v[0:3], v[166:169], v[170:173], v[128:131]
	s_nop 2
	v_lshlrev_b64 v[128:129], 11, v[100:101]
	v_lshl_add_u64 v[128:129], v[102:103], 0, v[128:129]
	flat_store_dwordx2 v[128:129], v[124:125]
	flat_store_dwordx2 v[128:129], v[120:121] offset:32
	flat_store_dwordx2 v[128:129], v[116:117] offset:64
	flat_store_dwordx2 v[128:129], v[106:107] offset:96
	ds_read_b32 v112, v104 offset:64
	v_or_b32_e32 v106, 16, v100
	v_ashrrev_i32_e32 v107, 31, v106
	v_lshlrev_b64 v[106:107], 11, v[106:107]
	v_lshl_add_u64 v[106:107], v[102:103], 0, v[106:107]
	s_waitcnt lgkmcnt(0)
	v_pk_mul_f32 v[110:111], v[110:111], v[112:113] op_sel_hi:[1,0]
	v_pk_mul_f32 v[108:109], v[108:109], v[112:113] op_sel_hi:[1,0]
	v_pk_mul_f32 v[96:97], v[96:97], v[112:113] op_sel_hi:[1,0]
	v_cvt_pk_bf16_f32 v108, v108, v109
	v_cvt_pk_bf16_f32 v109, v110, v111
	v_pk_mul_f32 v[110:111], v[132:133], v[112:113] op_sel_hi:[1,0]
	flat_store_dwordx2 v[106:107], v[108:109]
	v_pk_mul_f32 v[108:109], v[134:135], v[112:113] op_sel_hi:[1,0]
	v_cvt_pk_bf16_f32 v110, v110, v111
	v_pk_mul_f32 v[98:99], v[98:99], v[112:113] op_sel_hi:[1,0]
	v_cvt_pk_bf16_f32 v111, v108, v109
	flat_store_dwordx2 v[106:107], v[110:111] offset:32
	v_pk_mul_f32 v[110:111], v[174:175], v[112:113] op_sel_hi:[1,0]
	v_pk_mul_f32 v[108:109], v[176:177], v[112:113] op_sel_hi:[1,0]
	v_cvt_pk_bf16_f32 v110, v110, v111
	v_cvt_pk_bf16_f32 v96, v96, v97
	v_cvt_pk_bf16_f32 v97, v98, v99
	flat_store_dwordx2 v[106:107], v[96:97] offset:96
	v_cvt_pk_bf16_f32 v111, v108, v109
	flat_store_dwordx2 v[106:107], v[110:111] offset:64
	ds_read_b32 v98, v104 offset:128
	v_or_b32_e32 v96, 32, v100
	v_ashrrev_i32_e32 v97, 31, v96
	v_lshlrev_b64 v[96:97], 11, v[96:97]
	v_lshl_add_u64 v[96:97], v[102:103], 0, v[96:97]
	s_waitcnt lgkmcnt(0)
	v_pk_mul_f32 v[92:93], v[92:93], v[98:99] op_sel_hi:[1,0]
	v_pk_mul_f32 v[88:89], v[88:89], v[98:99] op_sel_hi:[1,0]
	v_pk_mul_f32 v[84:85], v[84:85], v[98:99] op_sel_hi:[1,0]
	v_pk_mul_f32 v[80:81], v[80:81], v[98:99] op_sel_hi:[1,0]
	v_pk_mul_f32 v[94:95], v[94:95], v[98:99] op_sel_hi:[1,0]
	v_cvt_pk_bf16_f32 v92, v92, v93
	v_pk_mul_f32 v[90:91], v[90:91], v[98:99] op_sel_hi:[1,0]
	v_cvt_pk_bf16_f32 v93, v94, v95
	flat_store_dwordx2 v[96:97], v[92:93]
	v_cvt_pk_bf16_f32 v88, v88, v89
	v_cvt_pk_bf16_f32 v89, v90, v91
	flat_store_dwordx2 v[96:97], v[88:89] offset:32
	v_pk_mul_f32 v[86:87], v[86:87], v[98:99] op_sel_hi:[1,0]
	v_cvt_pk_bf16_f32 v84, v84, v85
	v_pk_mul_f32 v[82:83], v[82:83], v[98:99] op_sel_hi:[1,0]
	v_cvt_pk_bf16_f32 v85, v86, v87
	flat_store_dwordx2 v[96:97], v[84:85] offset:64
	v_cvt_pk_bf16_f32 v80, v80, v81
	v_cvt_pk_bf16_f32 v81, v82, v83
	flat_store_dwordx2 v[96:97], v[80:81] offset:96
	ds_read_b32 v82, v104 offset:192
	v_or_b32_e32 v80, 48, v100
	v_ashrrev_i32_e32 v81, 31, v80
	v_lshlrev_b64 v[80:81], 11, v[80:81]
	v_lshl_add_u64 v[80:81], v[102:103], 0, v[80:81]
	s_waitcnt lgkmcnt(0)
	v_pk_mul_f32 v[76:77], v[76:77], v[82:83] op_sel_hi:[1,0]
	v_pk_mul_f32 v[72:73], v[72:73], v[82:83] op_sel_hi:[1,0]
	v_pk_mul_f32 v[68:69], v[68:69], v[82:83] op_sel_hi:[1,0]
	v_pk_mul_f32 v[64:65], v[64:65], v[82:83] op_sel_hi:[1,0]
	v_pk_mul_f32 v[78:79], v[78:79], v[82:83] op_sel_hi:[1,0]
	v_cvt_pk_bf16_f32 v76, v76, v77
	v_pk_mul_f32 v[74:75], v[74:75], v[82:83] op_sel_hi:[1,0]
	v_cvt_pk_bf16_f32 v77, v78, v79
	flat_store_dwordx2 v[80:81], v[76:77]
	v_cvt_pk_bf16_f32 v72, v72, v73
	v_cvt_pk_bf16_f32 v73, v74, v75
	flat_store_dwordx2 v[80:81], v[72:73] offset:32
	v_pk_mul_f32 v[70:71], v[70:71], v[82:83] op_sel_hi:[1,0]
	v_cvt_pk_bf16_f32 v68, v68, v69
	v_pk_mul_f32 v[66:67], v[66:67], v[82:83] op_sel_hi:[1,0]
	v_cvt_pk_bf16_f32 v69, v70, v71
	flat_store_dwordx2 v[80:81], v[68:69] offset:64
	v_cvt_pk_bf16_f32 v64, v64, v65
	v_cvt_pk_bf16_f32 v65, v66, v67
	flat_store_dwordx2 v[80:81], v[64:65] offset:96
	ds_read_b32 v66, v104 offset:256
	v_or_b32_e32 v64, 64, v100
	v_ashrrev_i32_e32 v65, 31, v64
	v_lshlrev_b64 v[64:65], 11, v[64:65]
	v_lshl_add_u64 v[64:65], v[102:103], 0, v[64:65]
	s_waitcnt lgkmcnt(0)
	v_pk_mul_f32 v[60:61], v[60:61], v[66:67] op_sel_hi:[1,0]
	v_pk_mul_f32 v[56:57], v[56:57], v[66:67] op_sel_hi:[1,0]
	v_pk_mul_f32 v[52:53], v[52:53], v[66:67] op_sel_hi:[1,0]
	v_pk_mul_f32 v[48:49], v[48:49], v[66:67] op_sel_hi:[1,0]
	v_pk_mul_f32 v[62:63], v[62:63], v[66:67] op_sel_hi:[1,0]
	v_cvt_pk_bf16_f32 v60, v60, v61
	v_pk_mul_f32 v[58:59], v[58:59], v[66:67] op_sel_hi:[1,0]
	v_cvt_pk_bf16_f32 v61, v62, v63
	flat_store_dwordx2 v[64:65], v[60:61]
	v_cvt_pk_bf16_f32 v56, v56, v57
	v_cvt_pk_bf16_f32 v57, v58, v59
	flat_store_dwordx2 v[64:65], v[56:57] offset:32
	v_pk_mul_f32 v[54:55], v[54:55], v[66:67] op_sel_hi:[1,0]
	v_cvt_pk_bf16_f32 v52, v52, v53
	v_pk_mul_f32 v[50:51], v[50:51], v[66:67] op_sel_hi:[1,0]
	v_cvt_pk_bf16_f32 v53, v54, v55
	flat_store_dwordx2 v[64:65], v[52:53] offset:64
	v_cvt_pk_bf16_f32 v48, v48, v49
	v_cvt_pk_bf16_f32 v49, v50, v51
	flat_store_dwordx2 v[64:65], v[48:49] offset:96
	ds_read_b32 v50, v104 offset:320
	v_or_b32_e32 v48, 0x50, v100
	v_ashrrev_i32_e32 v49, 31, v48
	v_lshlrev_b64 v[48:49], 11, v[48:49]
	v_lshl_add_u64 v[48:49], v[102:103], 0, v[48:49]
	s_waitcnt lgkmcnt(0)
	v_pk_mul_f32 v[44:45], v[44:45], v[50:51] op_sel_hi:[1,0]
	v_pk_mul_f32 v[40:41], v[40:41], v[50:51] op_sel_hi:[1,0]
	v_pk_mul_f32 v[36:37], v[36:37], v[50:51] op_sel_hi:[1,0]
	v_pk_mul_f32 v[32:33], v[32:33], v[50:51] op_sel_hi:[1,0]
	v_pk_mul_f32 v[46:47], v[46:47], v[50:51] op_sel_hi:[1,0]
	v_cvt_pk_bf16_f32 v44, v44, v45
	v_pk_mul_f32 v[42:43], v[42:43], v[50:51] op_sel_hi:[1,0]
	v_cvt_pk_bf16_f32 v45, v46, v47
	flat_store_dwordx2 v[48:49], v[44:45]
	v_cvt_pk_bf16_f32 v40, v40, v41
	v_cvt_pk_bf16_f32 v41, v42, v43
	flat_store_dwordx2 v[48:49], v[40:41] offset:32
	v_pk_mul_f32 v[38:39], v[38:39], v[50:51] op_sel_hi:[1,0]
	v_cvt_pk_bf16_f32 v36, v36, v37
	v_pk_mul_f32 v[34:35], v[34:35], v[50:51] op_sel_hi:[1,0]
	v_cvt_pk_bf16_f32 v37, v38, v39
	flat_store_dwordx2 v[48:49], v[36:37] offset:64
	v_cvt_pk_bf16_f32 v32, v32, v33
	v_cvt_pk_bf16_f32 v33, v34, v35
	flat_store_dwordx2 v[48:49], v[32:33] offset:96
	ds_read_b32 v34, v104 offset:384
	v_or_b32_e32 v32, 0x60, v100
	v_ashrrev_i32_e32 v33, 31, v32
	v_lshlrev_b64 v[32:33], 11, v[32:33]
	v_lshl_add_u64 v[32:33], v[102:103], 0, v[32:33]
	s_waitcnt lgkmcnt(0)
	v_pk_mul_f32 v[28:29], v[28:29], v[34:35] op_sel_hi:[1,0]
	v_pk_mul_f32 v[24:25], v[24:25], v[34:35] op_sel_hi:[1,0]
	v_pk_mul_f32 v[20:21], v[20:21], v[34:35] op_sel_hi:[1,0]
	v_pk_mul_f32 v[16:17], v[16:17], v[34:35] op_sel_hi:[1,0]
	v_pk_mul_f32 v[30:31], v[30:31], v[34:35] op_sel_hi:[1,0]
	v_cvt_pk_bf16_f32 v28, v28, v29
	v_pk_mul_f32 v[26:27], v[26:27], v[34:35] op_sel_hi:[1,0]
	v_cvt_pk_bf16_f32 v29, v30, v31
	flat_store_dwordx2 v[32:33], v[28:29]
	v_cvt_pk_bf16_f32 v24, v24, v25
	v_cvt_pk_bf16_f32 v25, v26, v27
	flat_store_dwordx2 v[32:33], v[24:25] offset:32
	v_pk_mul_f32 v[22:23], v[22:23], v[34:35] op_sel_hi:[1,0]
	v_cvt_pk_bf16_f32 v20, v20, v21
	v_pk_mul_f32 v[18:19], v[18:19], v[34:35] op_sel_hi:[1,0]
	v_cvt_pk_bf16_f32 v21, v22, v23
	flat_store_dwordx2 v[32:33], v[20:21] offset:64
	v_cvt_pk_bf16_f32 v16, v16, v17
	v_cvt_pk_bf16_f32 v17, v18, v19
	flat_store_dwordx2 v[32:33], v[16:17] offset:96
	ds_read_b32 v18, v104 offset:448
	v_or_b32_e32 v16, 0x70, v100
	v_ashrrev_i32_e32 v17, 31, v16
	v_lshlrev_b64 v[16:17], 11, v[16:17]
	v_lshl_add_u64 v[16:17], v[102:103], 0, v[16:17]
	s_waitcnt lgkmcnt(0)
	v_pk_mul_f32 v[12:13], v[12:13], v[18:19] op_sel_hi:[1,0]
	v_pk_mul_f32 v[8:9], v[8:9], v[18:19] op_sel_hi:[1,0]
	v_pk_mul_f32 v[4:5], v[4:5], v[18:19] op_sel_hi:[1,0]
	v_pk_mul_f32 v[0:1], v[0:1], v[18:19] op_sel_hi:[1,0]
	v_pk_mul_f32 v[14:15], v[14:15], v[18:19] op_sel_hi:[1,0]
	v_cvt_pk_bf16_f32 v12, v12, v13
	v_pk_mul_f32 v[10:11], v[10:11], v[18:19] op_sel_hi:[1,0]
	v_cvt_pk_bf16_f32 v13, v14, v15
	flat_store_dwordx2 v[16:17], v[12:13]
	v_cvt_pk_bf16_f32 v8, v8, v9
	v_cvt_pk_bf16_f32 v9, v10, v11
	flat_store_dwordx2 v[16:17], v[8:9] offset:32
	v_pk_mul_f32 v[6:7], v[6:7], v[18:19] op_sel_hi:[1,0]
	v_cvt_pk_bf16_f32 v4, v4, v5
	v_pk_mul_f32 v[2:3], v[2:3], v[18:19] op_sel_hi:[1,0]
	v_cvt_pk_bf16_f32 v5, v6, v7
	flat_store_dwordx2 v[16:17], v[4:5] offset:64
	v_cvt_pk_bf16_f32 v0, v0, v1
	v_cvt_pk_bf16_f32 v1, v2, v3
	flat_store_dwordx2 v[16:17], v[0:1] offset:96
	s_cbranch_scc0 .LBB0_235

.LBB0_245:
	s_ashr_i32 s2, s28, 5
	s_lshr_b32 s3, s2, 30
	s_add_i32 s3, s2, s3
	s_and_b32 s31, s3, -4
	s_sub_i32 s18, s2, s31
	s_lshl_b32 s2, s28, 3
	s_and_b32 s2, s2, 56
	s_bfe_u32 s30, s28, 0x20003
	s_add_i32 s2, s31, s2
	s_or_b32 s22, s2, s30
	s_ashr_i32 s23, s22, 31
	s_and_b32 s29, s27, 56
	s_lshl_b64 s[2:3], s[22:23], 19
	s_add_u32 s2, s6, s2
	s_addc_u32 s3, s7, s3
	s_ashr_i32 s19, s18, 31
	v_mov_b32_e32 v6, v190
	s_lshl_b64 s[24:25], s[18:19], 19
	s_mov_b32 s19, 0x1ffff80
	v_and_b32_e32 v0, 15, v6
	v_lshrrev_b32_e32 v2, 1, v6
	v_and_or_b32 v0, v2, s19, v0
	s_waitcnt lgkmcnt(0)
	v_bfe_u32 v1, v6, 4, 2
	v_lshlrev_b32_e32 v132, 7, v0
	v_bfe_u32 v0, v6, 1, 3
	v_bitop3_b32 v0, v1, v0, 4 bitop3:0x36
	v_lshlrev_b32_e32 v133, 4, v0
	v_lshlrev_b32_e32 v0, 7, v6
	v_and_b32_e32 v134, 0x6780, v0
	v_ashrrev_i32_e32 v0, 3, v6
	v_bitop3_b32 v2, v2, v1, 7 bitop3:0x6c
	v_ashrrev_i32_e32 v1, 31, v0
	v_lshrrev_b32_e32 v7, 4, v6
	v_lshlrev_b64 v[0:1], 11, v[0:1]
	s_add_u32 s24, s0, s24
	v_lshlrev_b32_e32 v135, 4, v2
	v_xor_b32_e32 v4, v7, v6
	v_lshl_add_u64 v[2:3], s[2:3], 0, v[0:1]
	v_readfirstlane_b32 s2, v6
	s_addc_u32 s25, s26, s25
	v_lshlrev_b32_e32 v4, 4, v4
	s_lshl_b32 s2, s2, 4
	v_and_b32_e32 v144, 0x70, v4
	s_and_b32 s2, s2, 0xfffffc00
	v_lshl_add_u64 v[2:3], v[2:3], 0, v[144:145]
	v_lshl_add_u64 v[4:5], s[24:25], 0, v[0:1]
	s_mov_b32 m0, s2
	s_mov_b64 s[34:35], 0x20000
	v_lshl_add_u64 v[128:129], v[4:5], 0, v[144:145]
	s_waitcnt lgkmcnt(0)
	s_barrier
	global_load_lds_dwordx4 v[2:3], off
	v_lshl_add_u64 v[4:5], v[2:3], 0, s[34:35]
	s_add_i32 m0, s2, 0x2000
	s_mov_b64 s[24:25], 0x40000
	global_load_lds_dwordx4 v[4:5], off
	v_lshl_add_u64 v[4:5], v[2:3], 0, s[24:25]
	s_add_i32 m0, s2, 0x4000
	s_mov_b64 s[36:37], 0x60000
	global_load_lds_dwordx4 v[4:5], off
	v_lshl_add_u64 v[2:3], v[2:3], 0, s[36:37]
	s_add_i32 m0, s2, 0x6000
	s_add_i32 s29, s29, s31
	global_load_lds_dwordx4 v[2:3], off
	s_add_i32 m0, s2, 0x8000
	v_lshl_add_u64 v[2:3], v[128:129], 0, s[34:35]
	global_load_lds_dwordx4 v[128:129], off
	s_add_i32 m0, s2, 0xa000
	v_mov_b32_e32 v88, 0
	global_load_lds_dwordx4 v[2:3], off
	v_lshl_add_u64 v[2:3], v[128:129], 0, s[24:25]
	s_add_i32 m0, s2, 0xc000
	s_or_b32 s24, s29, s30
	global_load_lds_dwordx4 v[2:3], off
	v_lshl_add_u64 v[2:3], v[128:129], 0, s[36:37]
	s_add_i32 m0, s2, 0xe000
	s_ashr_i32 s25, s24, 31
	global_load_lds_dwordx4 v[2:3], off
	s_lshl_b64 s[24:25], s[24:25], 19
	s_waitcnt vmcnt(0)
	v_lshl_add_u64 v[0:1], s[24:25], 0, v[0:1]
	v_bitop3_b32 v2, v7, 7, v6 bitop3:0x48
	v_lshl_or_b32 v0, v2, 4, v0
	s_mov_b64 s[86:87], 0x20000
	v_lshl_add_u64 v[130:131], s[6:7], 0, v[0:1]
	s_mov_b64 s[24:25], 0
	s_mov_b32 s3, 0
	v_mov_b32_e32 v89, v88
	v_mov_b32_e32 v90, v88
	v_mov_b32_e32 v91, v88
	v_mov_b32_e32 v0, v88
	v_mov_b32_e32 v1, v88
	v_mov_b32_e32 v2, v88
	v_mov_b32_e32 v3, v88
	v_mov_b32_e32 v4, v88
	v_mov_b32_e32 v5, v88
	v_mov_b32_e32 v6, v88
	v_mov_b32_e32 v7, v88
	v_mov_b32_e32 v8, v88
	v_mov_b32_e32 v9, v88
	v_mov_b32_e32 v10, v88
	v_mov_b32_e32 v11, v88
	v_mov_b32_e32 v12, v88
	v_mov_b32_e32 v13, v88
	v_mov_b32_e32 v14, v88
	v_mov_b32_e32 v15, v88
	v_mov_b32_e32 v16, v88
	v_mov_b32_e32 v17, v88
	v_mov_b32_e32 v18, v88
	v_mov_b32_e32 v19, v88
	v_mov_b32_e32 v20, v88
	v_mov_b32_e32 v21, v88
	v_mov_b32_e32 v22, v88
	v_mov_b32_e32 v23, v88
	v_mov_b32_e32 v24, v88
	v_mov_b32_e32 v25, v88
	v_mov_b32_e32 v26, v88
	v_mov_b32_e32 v27, v88
	v_mov_b32_e32 v28, v88
	v_mov_b32_e32 v29, v88
	v_mov_b32_e32 v30, v88
	v_mov_b32_e32 v31, v88
	v_mov_b32_e32 v32, v88
	v_mov_b32_e32 v33, v88
	v_mov_b32_e32 v34, v88
	v_mov_b32_e32 v35, v88
	v_mov_b32_e32 v36, v88
	v_mov_b32_e32 v37, v88
	v_mov_b32_e32 v38, v88
	v_mov_b32_e32 v39, v88
	v_mov_b32_e32 v40, v88
	v_mov_b32_e32 v41, v88
	v_mov_b32_e32 v42, v88
	v_mov_b32_e32 v43, v88
	v_mov_b32_e32 v44, v88
	v_mov_b32_e32 v45, v88
	v_mov_b32_e32 v46, v88
	v_mov_b32_e32 v47, v88
	v_mov_b32_e32 v48, v88
	v_mov_b32_e32 v49, v88
	v_mov_b32_e32 v50, v88
	v_mov_b32_e32 v51, v88
	v_mov_b32_e32 v52, v88
	v_mov_b32_e32 v53, v88
	v_mov_b32_e32 v54, v88
	v_mov_b32_e32 v55, v88
	v_mov_b32_e32 v56, v88
	v_mov_b32_e32 v57, v88
	v_mov_b32_e32 v58, v88
	v_mov_b32_e32 v59, v88
	v_mov_b32_e32 v60, v88
	v_mov_b32_e32 v61, v88
	v_mov_b32_e32 v62, v88
	v_mov_b32_e32 v63, v88
	v_mov_b32_e32 v64, v88
	v_mov_b32_e32 v65, v88
	v_mov_b32_e32 v66, v88
	v_mov_b32_e32 v67, v88
	v_mov_b32_e32 v68, v88
	v_mov_b32_e32 v69, v88
	v_mov_b32_e32 v70, v88
	v_mov_b32_e32 v71, v88
	v_mov_b32_e32 v72, v88
	v_mov_b32_e32 v73, v88
	v_mov_b32_e32 v74, v88
	v_mov_b32_e32 v75, v88
	v_mov_b32_e32 v76, v88
	v_mov_b32_e32 v77, v88
	v_mov_b32_e32 v78, v88
	v_mov_b32_e32 v79, v88
	v_mov_b32_e32 v80, v88
	v_mov_b32_e32 v81, v88
	v_mov_b32_e32 v82, v88
	v_mov_b32_e32 v83, v88
	v_mov_b32_e32 v84, v88
	v_mov_b32_e32 v85, v88
	v_mov_b32_e32 v86, v88
	v_mov_b32_e32 v87, v88
	v_mov_b32_e32 v92, v88
	v_mov_b32_e32 v93, v88
	v_mov_b32_e32 v94, v88
	v_mov_b32_e32 v95, v88
	v_mov_b32_e32 v96, v88
	v_mov_b32_e32 v97, v88
	v_mov_b32_e32 v98, v88
	v_mov_b32_e32 v99, v88
	v_mov_b32_e32 v100, v88
	v_mov_b32_e32 v101, v88
	v_mov_b32_e32 v102, v88
	v_mov_b32_e32 v103, v88
	v_mov_b32_e32 v104, v88
	v_mov_b32_e32 v105, v88
	v_mov_b32_e32 v106, v88
	v_mov_b32_e32 v107, v88
	v_mov_b32_e32 v108, v88
	v_mov_b32_e32 v109, v88
	v_mov_b32_e32 v110, v88
	v_mov_b32_e32 v111, v88
	v_mov_b32_e32 v112, v88
	v_mov_b32_e32 v113, v88
	v_mov_b32_e32 v114, v88
	v_mov_b32_e32 v115, v88
	v_mov_b32_e32 v116, v88
	v_mov_b32_e32 v117, v88
	v_mov_b32_e32 v118, v88
	v_mov_b32_e32 v119, v88
	v_mov_b32_e32 v120, v88
	v_mov_b32_e32 v121, v88
	v_mov_b32_e32 v122, v88
	v_mov_b32_e32 v123, v88
	v_mov_b32_e32 v124, v88
	v_mov_b32_e32 v125, v88
	v_mov_b32_e32 v126, v88
	v_mov_b32_e32 v127, v88
	s_waitcnt vmcnt(0) lgkmcnt(0)
	s_barrier
	s_bitcmp1_b32 s2, 12
	s_cbranch_scc1 .Lkb_246
.LBB0_246:
	s_add_i32 s19, s3, 0x10000
	s_and_b32 s23, s19, 0x10000
	s_add_i32 s23, s2, s23
	v_lshl_add_u64 v[136:137], v[130:131], 0, s[24:25]
	v_lshl_add_u64 v[138:139], v[136:137], 0, s[10:11]
	s_mov_b32 m0, s23
	s_nop 0
	global_load_lds_dwordx4 v[138:139], off
	v_lshl_add_u64 v[138:139], v[136:137], 0, s[4:5]
	s_add_i32 m0, s23, 0x2000
	s_nop 0
	global_load_lds_dwordx4 v[138:139], off
	v_lshl_add_u64 v[138:139], v[136:137], 0, s[92:93]
	s_add_i32 m0, s23, 0x4000
	v_lshl_add_u64 v[136:137], v[136:137], 0, s[94:95]
	global_load_lds_dwordx4 v[138:139], off
	s_add_i32 m0, s23, 0x6000
	s_nop 0
	global_load_lds_dwordx4 v[136:137], off
	v_lshl_add_u64 v[136:137], v[128:129], 0, s[24:25]
	v_lshl_add_u64 v[138:139], v[136:137], 0, s[10:11]
	s_add_i32 m0, s23, 0x8000
	s_nop 0
	global_load_lds_dwordx4 v[138:139], off
	v_lshl_add_u64 v[138:139], v[136:137], 0, s[4:5]
	s_add_i32 m0, s23, 0xa000
	s_nop 0
	global_load_lds_dwordx4 v[138:139], off
	v_lshl_add_u64 v[138:139], v[136:137], 0, s[92:93]
	s_add_i32 m0, s23, 0xc000
	v_lshl_add_u64 v[136:137], v[136:137], 0, s[94:95]
	global_load_lds_dwordx4 v[138:139], off
	s_add_i32 m0, s23, 0xe000
	s_nop 0
	global_load_lds_dwordx4 v[136:137], off
	s_and_b32 s3, s3, 0x10000
	v_or_b32_e32 v144, s3, v135
	v_add_u32_e32 v151, v144, v134
	v_add_u32_e32 v144, v144, v132
	ds_read_b128 v[136:139], v151 offset:32768
	ds_read_b128 v[140:143], v151 offset:34816
	ds_read_b128 v[146:149], v151 offset:36864
	ds_read_b128 v[154:157], v151 offset:38912
	ds_read_b128 v[158:161], v144
	ds_read_b128 v[162:165], v144 offset:2048
	ds_read_b128 v[166:169], v144 offset:4096
	ds_read_b128 v[170:173], v144 offset:6144
	ds_read_b128 v[174:177], v144 offset:8192
	ds_read_b128 v[178:181], v144 offset:10240
	ds_read_b128 v[182:185], v144 offset:12288
	ds_read_b128 v[186:189], v144 offset:14336
	s_waitcnt lgkmcnt(0)
	v_mfma_f32_16x16x32_bf16 v[124:127], v[136:139], v[158:161], v[124:127]
	v_mfma_f32_16x16x32_bf16 v[120:123], v[140:143], v[158:161], v[120:123]
	v_mfma_f32_16x16x32_bf16 v[116:119], v[146:149], v[158:161], v[116:119]
	v_mfma_f32_16x16x32_bf16 v[112:115], v[154:157], v[158:161], v[112:115]
	v_mfma_f32_16x16x32_bf16 v[108:111], v[136:139], v[162:165], v[108:111]
	v_mfma_f32_16x16x32_bf16 v[104:107], v[140:143], v[162:165], v[104:107]
	v_mfma_f32_16x16x32_bf16 v[100:103], v[146:149], v[162:165], v[100:103]
	v_mfma_f32_16x16x32_bf16 v[96:99], v[154:157], v[162:165], v[96:99]
	v_mfma_f32_16x16x32_bf16 v[92:95], v[136:139], v[166:169], v[92:95]
	v_mfma_f32_16x16x32_bf16 v[84:87], v[140:143], v[166:169], v[84:87]
	v_mfma_f32_16x16x32_bf16 v[80:83], v[146:149], v[166:169], v[80:83]
	v_mfma_f32_16x16x32_bf16 v[76:79], v[154:157], v[166:169], v[76:79]
	v_mfma_f32_16x16x32_bf16 v[72:75], v[136:139], v[170:173], v[72:75]
	v_mfma_f32_16x16x32_bf16 v[68:71], v[140:143], v[170:173], v[68:71]
	v_mfma_f32_16x16x32_bf16 v[64:67], v[146:149], v[170:173], v[64:67]
	v_mfma_f32_16x16x32_bf16 v[60:63], v[154:157], v[170:173], v[60:63]
	v_or_b32_e32 v144, s3, v133
	v_add_u32_e32 v151, v144, v134
	v_add_u32_e32 v144, v144, v132
	ds_read_b128 v[158:161], v151 offset:32768
	ds_read_b128 v[162:165], v151 offset:34816
	ds_read_b128 v[166:169], v151 offset:36864
	ds_read_b128 v[170:173], v151 offset:38912
	ds_read_b128 v[206:209], v144
	ds_read_b128 v[216:219], v144 offset:2048
	ds_read_b128 v[220:223], v144 offset:4096
	ds_read_b128 v[224:227], v144 offset:6144
	v_mfma_f32_16x16x32_bf16 v[56:59], v[136:139], v[174:177], v[56:59]
	v_mfma_f32_16x16x32_bf16 v[52:55], v[140:143], v[174:177], v[52:55]
	v_mfma_f32_16x16x32_bf16 v[48:51], v[146:149], v[174:177], v[48:51]
	v_mfma_f32_16x16x32_bf16 v[44:47], v[154:157], v[174:177], v[44:47]
	v_mfma_f32_16x16x32_bf16 v[40:43], v[136:139], v[178:181], v[40:43]
	v_mfma_f32_16x16x32_bf16 v[36:39], v[140:143], v[178:181], v[36:39]
	v_mfma_f32_16x16x32_bf16 v[32:35], v[146:149], v[178:181], v[32:35]
	v_mfma_f32_16x16x32_bf16 v[28:31], v[154:157], v[178:181], v[28:31]
	v_mfma_f32_16x16x32_bf16 v[24:27], v[136:139], v[182:185], v[24:27]
	v_mfma_f32_16x16x32_bf16 v[20:23], v[140:143], v[182:185], v[20:23]
	v_mfma_f32_16x16x32_bf16 v[16:19], v[146:149], v[182:185], v[16:19]
	v_mfma_f32_16x16x32_bf16 v[12:15], v[154:157], v[182:185], v[12:15]
	v_mfma_f32_16x16x32_bf16 v[8:11], v[136:139], v[186:189], v[8:11]
	v_mfma_f32_16x16x32_bf16 v[4:7], v[140:143], v[186:189], v[4:7]
	v_mfma_f32_16x16x32_bf16 v[0:3], v[146:149], v[186:189], v[0:3]
	v_mfma_f32_16x16x32_bf16 v[88:91], v[154:157], v[186:189], v[88:91]
	ds_read_b128 v[136:139], v144 offset:8192
	ds_read_b128 v[140:143], v144 offset:10240
	ds_read_b128 v[146:149], v144 offset:12288
	ds_read_b128 v[154:157], v144 offset:14336
	s_waitcnt lgkmcnt(0)
	v_mfma_f32_16x16x32_bf16 v[124:127], v[158:161], v[206:209], v[124:127]
	v_mfma_f32_16x16x32_bf16 v[120:123], v[162:165], v[206:209], v[120:123]
	v_mfma_f32_16x16x32_bf16 v[116:119], v[166:169], v[206:209], v[116:119]
	v_mfma_f32_16x16x32_bf16 v[112:115], v[170:173], v[206:209], v[112:115]
	v_mfma_f32_16x16x32_bf16 v[108:111], v[158:161], v[216:219], v[108:111]
	v_mfma_f32_16x16x32_bf16 v[104:107], v[162:165], v[216:219], v[104:107]
	v_mfma_f32_16x16x32_bf16 v[100:103], v[166:169], v[216:219], v[100:103]
	v_mfma_f32_16x16x32_bf16 v[96:99], v[170:173], v[216:219], v[96:99]
	v_mfma_f32_16x16x32_bf16 v[92:95], v[158:161], v[220:223], v[92:95]
	v_mfma_f32_16x16x32_bf16 v[84:87], v[162:165], v[220:223], v[84:87]
	v_mfma_f32_16x16x32_bf16 v[80:83], v[166:169], v[220:223], v[80:83]
	v_mfma_f32_16x16x32_bf16 v[76:79], v[170:173], v[220:223], v[76:79]
	v_mfma_f32_16x16x32_bf16 v[72:75], v[158:161], v[224:227], v[72:75]
	v_mfma_f32_16x16x32_bf16 v[68:71], v[162:165], v[224:227], v[68:71]
	v_mfma_f32_16x16x32_bf16 v[64:67], v[166:169], v[224:227], v[64:67]
	v_mfma_f32_16x16x32_bf16 v[60:63], v[170:173], v[224:227], v[60:63]
	v_mfma_f32_16x16x32_bf16 v[56:59], v[158:161], v[136:139], v[56:59]
	s_waitcnt vmcnt(0)
	s_add_u32 s24, s24, 0x80
	s_addc_u32 s25, s25, 0
	v_mfma_f32_16x16x32_bf16 v[52:55], v[162:165], v[136:139], v[52:55]
	s_cmpk_eq_i32 s24, 0x780
	s_mov_b32 s3, s19
	s_waitcnt vmcnt(0)
	v_mfma_f32_16x16x32_bf16 v[48:51], v[166:169], v[136:139], v[48:51]
	s_barrier
	v_mfma_f32_16x16x32_bf16 v[44:47], v[170:173], v[136:139], v[44:47]
	v_mfma_f32_16x16x32_bf16 v[40:43], v[158:161], v[140:143], v[40:43]
	v_mfma_f32_16x16x32_bf16 v[36:39], v[162:165], v[140:143], v[36:39]
	v_mfma_f32_16x16x32_bf16 v[32:35], v[166:169], v[140:143], v[32:35]
	v_mfma_f32_16x16x32_bf16 v[28:31], v[170:173], v[140:143], v[28:31]
	v_mfma_f32_16x16x32_bf16 v[24:27], v[158:161], v[146:149], v[24:27]
	v_mfma_f32_16x16x32_bf16 v[20:23], v[162:165], v[146:149], v[20:23]
	v_mfma_f32_16x16x32_bf16 v[16:19], v[166:169], v[146:149], v[16:19]
	v_mfma_f32_16x16x32_bf16 v[12:15], v[170:173], v[146:149], v[12:15]
	v_mfma_f32_16x16x32_bf16 v[8:11], v[158:161], v[154:157], v[8:11]
	v_mfma_f32_16x16x32_bf16 v[4:7], v[162:165], v[154:157], v[4:7]
	v_mfma_f32_16x16x32_bf16 v[0:3], v[166:169], v[154:157], v[0:3]
	v_mfma_f32_16x16x32_bf16 v[88:91], v[170:173], v[154:157], v[88:91]
	s_cbranch_scc0 .LBB0_246
	s_branch .Lkx_246
.Lkb_246:
	s_add_i32 s19, s3, 0x10000
	s_and_b32 s23, s19, 0x10000
	s_add_i32 s23, s2, s23
	s_and_b32 s3, s3, 0x10000
	v_or_b32_e32 v144, s3, v135
	v_add_u32_e32 v151, v144, v134
	v_add_u32_e32 v144, v144, v132
	ds_read_b128 v[136:139], v151 offset:32768
	ds_read_b128 v[140:143], v151 offset:34816
	ds_read_b128 v[146:149], v151 offset:36864
	ds_read_b128 v[154:157], v151 offset:38912
	ds_read_b128 v[158:161], v144
	ds_read_b128 v[162:165], v144 offset:2048
	ds_read_b128 v[166:169], v144 offset:4096
	ds_read_b128 v[170:173], v144 offset:6144
	ds_read_b128 v[174:177], v144 offset:8192
	ds_read_b128 v[178:181], v144 offset:10240
	ds_read_b128 v[182:185], v144 offset:12288
	ds_read_b128 v[186:189], v144 offset:14336
	s_waitcnt lgkmcnt(0)
	v_mfma_f32_16x16x32_bf16 v[124:127], v[136:139], v[158:161], v[124:127]
	v_mfma_f32_16x16x32_bf16 v[120:123], v[140:143], v[158:161], v[120:123]
	v_mfma_f32_16x16x32_bf16 v[116:119], v[146:149], v[158:161], v[116:119]
	v_mfma_f32_16x16x32_bf16 v[112:115], v[154:157], v[158:161], v[112:115]
	v_mfma_f32_16x16x32_bf16 v[108:111], v[136:139], v[162:165], v[108:111]
	v_mfma_f32_16x16x32_bf16 v[104:107], v[140:143], v[162:165], v[104:107]
	v_mfma_f32_16x16x32_bf16 v[100:103], v[146:149], v[162:165], v[100:103]
	v_mfma_f32_16x16x32_bf16 v[96:99], v[154:157], v[162:165], v[96:99]
	v_mfma_f32_16x16x32_bf16 v[92:95], v[136:139], v[166:169], v[92:95]
	v_mfma_f32_16x16x32_bf16 v[84:87], v[140:143], v[166:169], v[84:87]
	v_mfma_f32_16x16x32_bf16 v[80:83], v[146:149], v[166:169], v[80:83]
	v_mfma_f32_16x16x32_bf16 v[76:79], v[154:157], v[166:169], v[76:79]
	v_mfma_f32_16x16x32_bf16 v[72:75], v[136:139], v[170:173], v[72:75]
	v_mfma_f32_16x16x32_bf16 v[68:71], v[140:143], v[170:173], v[68:71]
	v_mfma_f32_16x16x32_bf16 v[64:67], v[146:149], v[170:173], v[64:67]
	v_mfma_f32_16x16x32_bf16 v[60:63], v[154:157], v[170:173], v[60:63]
	v_or_b32_e32 v144, s3, v133
	v_add_u32_e32 v151, v144, v134
	v_add_u32_e32 v144, v144, v132
	ds_read_b128 v[158:161], v151 offset:32768
	ds_read_b128 v[162:165], v151 offset:34816
	ds_read_b128 v[166:169], v151 offset:36864
	ds_read_b128 v[170:173], v151 offset:38912
	ds_read_b128 v[206:209], v144
	ds_read_b128 v[216:219], v144 offset:2048
	ds_read_b128 v[220:223], v144 offset:4096
	ds_read_b128 v[224:227], v144 offset:6144
	v_mfma_f32_16x16x32_bf16 v[56:59], v[136:139], v[174:177], v[56:59]
	v_mfma_f32_16x16x32_bf16 v[52:55], v[140:143], v[174:177], v[52:55]
	v_mfma_f32_16x16x32_bf16 v[48:51], v[146:149], v[174:177], v[48:51]
	v_mfma_f32_16x16x32_bf16 v[44:47], v[154:157], v[174:177], v[44:47]
	v_mfma_f32_16x16x32_bf16 v[40:43], v[136:139], v[178:181], v[40:43]
	v_mfma_f32_16x16x32_bf16 v[36:39], v[140:143], v[178:181], v[36:39]
	v_mfma_f32_16x16x32_bf16 v[32:35], v[146:149], v[178:181], v[32:35]
	v_mfma_f32_16x16x32_bf16 v[28:31], v[154:157], v[178:181], v[28:31]
	v_mfma_f32_16x16x32_bf16 v[24:27], v[136:139], v[182:185], v[24:27]
	v_mfma_f32_16x16x32_bf16 v[20:23], v[140:143], v[182:185], v[20:23]
	v_mfma_f32_16x16x32_bf16 v[16:19], v[146:149], v[182:185], v[16:19]
	v_mfma_f32_16x16x32_bf16 v[12:15], v[154:157], v[182:185], v[12:15]
	v_mfma_f32_16x16x32_bf16 v[8:11], v[136:139], v[186:189], v[8:11]
	v_mfma_f32_16x16x32_bf16 v[4:7], v[140:143], v[186:189], v[4:7]
	v_mfma_f32_16x16x32_bf16 v[0:3], v[146:149], v[186:189], v[0:3]
	v_mfma_f32_16x16x32_bf16 v[88:91], v[154:157], v[186:189], v[88:91]
	v_lshl_add_u64 v[244:245], v[130:131], 0, s[24:25]
	v_lshl_add_u64 v[246:247], v[244:245], 0, s[10:11]
	s_mov_b32 m0, s23
	s_nop 0
	global_load_lds_dwordx4 v[246:247], off
	v_lshl_add_u64 v[246:247], v[244:245], 0, s[4:5]
	s_add_i32 m0, s23, 0x2000
	s_nop 0
	global_load_lds_dwordx4 v[246:247], off
	v_lshl_add_u64 v[246:247], v[244:245], 0, s[92:93]
	s_add_i32 m0, s23, 0x4000
	v_lshl_add_u64 v[244:245], v[244:245], 0, s[94:95]
	global_load_lds_dwordx4 v[246:247], off
	s_add_i32 m0, s23, 0x6000
	s_nop 0
	global_load_lds_dwordx4 v[244:245], off
	v_lshl_add_u64 v[244:245], v[128:129], 0, s[24:25]
	v_lshl_add_u64 v[246:247], v[244:245], 0, s[10:11]
	s_add_i32 m0, s23, 0x8000
	s_nop 0
	global_load_lds_dwordx4 v[246:247], off
	v_lshl_add_u64 v[246:247], v[244:245], 0, s[4:5]
	s_add_i32 m0, s23, 0xa000
	s_nop 0
	global_load_lds_dwordx4 v[246:247], off
	v_lshl_add_u64 v[246:247], v[244:245], 0, s[92:93]
	s_add_i32 m0, s23, 0xc000
	v_lshl_add_u64 v[244:245], v[244:245], 0, s[94:95]
	global_load_lds_dwordx4 v[246:247], off
	s_add_i32 m0, s23, 0xe000
	s_nop 0
	global_load_lds_dwordx4 v[244:245], off
	ds_read_b128 v[136:139], v144 offset:8192
	ds_read_b128 v[140:143], v144 offset:10240
	ds_read_b128 v[146:149], v144 offset:12288
	ds_read_b128 v[154:157], v144 offset:14336
	s_waitcnt lgkmcnt(0)
	v_mfma_f32_16x16x32_bf16 v[124:127], v[158:161], v[206:209], v[124:127]
	v_mfma_f32_16x16x32_bf16 v[120:123], v[162:165], v[206:209], v[120:123]
	v_mfma_f32_16x16x32_bf16 v[116:119], v[166:169], v[206:209], v[116:119]
	v_mfma_f32_16x16x32_bf16 v[112:115], v[170:173], v[206:209], v[112:115]
	v_mfma_f32_16x16x32_bf16 v[108:111], v[158:161], v[216:219], v[108:111]
	v_mfma_f32_16x16x32_bf16 v[104:107], v[162:165], v[216:219], v[104:107]
	v_mfma_f32_16x16x32_bf16 v[100:103], v[166:169], v[216:219], v[100:103]
	v_mfma_f32_16x16x32_bf16 v[96:99], v[170:173], v[216:219], v[96:99]
	v_mfma_f32_16x16x32_bf16 v[92:95], v[158:161], v[220:223], v[92:95]
	v_mfma_f32_16x16x32_bf16 v[84:87], v[162:165], v[220:223], v[84:87]
	v_mfma_f32_16x16x32_bf16 v[80:83], v[166:169], v[220:223], v[80:83]
	v_mfma_f32_16x16x32_bf16 v[76:79], v[170:173], v[220:223], v[76:79]
	v_mfma_f32_16x16x32_bf16 v[72:75], v[158:161], v[224:227], v[72:75]
	v_mfma_f32_16x16x32_bf16 v[68:71], v[162:165], v[224:227], v[68:71]
	v_mfma_f32_16x16x32_bf16 v[64:67], v[166:169], v[224:227], v[64:67]
	v_mfma_f32_16x16x32_bf16 v[60:63], v[170:173], v[224:227], v[60:63]
	v_mfma_f32_16x16x32_bf16 v[56:59], v[158:161], v[136:139], v[56:59]
	s_add_u32 s24, s24, 0x80
	s_addc_u32 s25, s25, 0
	v_mfma_f32_16x16x32_bf16 v[52:55], v[162:165], v[136:139], v[52:55]
	s_cmpk_eq_i32 s24, 0x780
	s_mov_b32 s3, s19
	s_waitcnt vmcnt(0)
	v_mfma_f32_16x16x32_bf16 v[48:51], v[166:169], v[136:139], v[48:51]
	s_barrier
	v_mfma_f32_16x16x32_bf16 v[44:47], v[170:173], v[136:139], v[44:47]
	v_mfma_f32_16x16x32_bf16 v[40:43], v[158:161], v[140:143], v[40:43]
	v_mfma_f32_16x16x32_bf16 v[36:39], v[162:165], v[140:143], v[36:39]
	v_mfma_f32_16x16x32_bf16 v[32:35], v[166:169], v[140:143], v[32:35]
	v_mfma_f32_16x16x32_bf16 v[28:31], v[170:173], v[140:143], v[28:31]
	v_mfma_f32_16x16x32_bf16 v[24:27], v[158:161], v[146:149], v[24:27]
	v_mfma_f32_16x16x32_bf16 v[20:23], v[162:165], v[146:149], v[20:23]
	v_mfma_f32_16x16x32_bf16 v[16:19], v[166:169], v[146:149], v[16:19]
	v_mfma_f32_16x16x32_bf16 v[12:15], v[170:173], v[146:149], v[12:15]
	v_mfma_f32_16x16x32_bf16 v[8:11], v[158:161], v[154:157], v[8:11]
	v_mfma_f32_16x16x32_bf16 v[4:7], v[162:165], v[154:157], v[4:7]
	v_mfma_f32_16x16x32_bf16 v[0:3], v[166:169], v[154:157], v[0:3]
	v_mfma_f32_16x16x32_bf16 v[88:91], v[170:173], v[154:157], v[88:91]
	s_cbranch_scc0 .Lkb_246
.Lkx_246:
	s_mov_b32 s2, 0x18000
	v_add3_u32 v144, v134, v135, s2
	v_add3_u32 v135, v132, v135, s81
	ds_read_b128 v[128:131], v144
	ds_read_b128 v[136:139], v144 offset:2048
	ds_read_b128 v[140:143], v144 offset:4096
	ds_read_b128 v[146:149], v144 offset:6144
	ds_read_b128 v[154:157], v135
	ds_read_b128 v[158:161], v135 offset:2048
	ds_read_b128 v[162:165], v135 offset:4096
	ds_read_b128 v[166:169], v135 offset:6144
	ds_read_b128 v[170:173], v135 offset:8192
	ds_read_b128 v[174:177], v135 offset:10240
	ds_read_b128 v[178:181], v135 offset:12288
	ds_read_b128 v[182:185], v135 offset:14336
	s_waitcnt lgkmcnt(7)
	v_mfma_f32_16x16x32_bf16 v[120:123], v[136:139], v[154:157], v[120:123]
	v_mfma_f32_16x16x32_bf16 v[116:119], v[140:143], v[154:157], v[116:119]
	v_mfma_f32_16x16x32_bf16 v[112:115], v[146:149], v[154:157], v[112:115]
	s_waitcnt lgkmcnt(6)
	v_mfma_f32_16x16x32_bf16 v[108:111], v[128:131], v[158:161], v[108:111]
	v_mfma_f32_16x16x32_bf16 v[104:107], v[136:139], v[158:161], v[104:107]
	v_mfma_f32_16x16x32_bf16 v[100:103], v[140:143], v[158:161], v[100:103]
	v_mfma_f32_16x16x32_bf16 v[96:99], v[146:149], v[158:161], v[96:99]
	s_waitcnt lgkmcnt(5)
	v_mfma_f32_16x16x32_bf16 v[92:95], v[128:131], v[162:165], v[92:95]
	v_mfma_f32_16x16x32_bf16 v[84:87], v[136:139], v[162:165], v[84:87]
	v_mfma_f32_16x16x32_bf16 v[80:83], v[140:143], v[162:165], v[80:83]
	v_mfma_f32_16x16x32_bf16 v[76:79], v[146:149], v[162:165], v[76:79]
	s_waitcnt lgkmcnt(4)
	v_mfma_f32_16x16x32_bf16 v[72:75], v[128:131], v[166:169], v[72:75]
	v_mfma_f32_16x16x32_bf16 v[68:71], v[136:139], v[166:169], v[68:71]
	v_mfma_f32_16x16x32_bf16 v[64:67], v[140:143], v[166:169], v[64:67]
	v_mfma_f32_16x16x32_bf16 v[60:63], v[146:149], v[166:169], v[60:63]
	v_mfma_f32_16x16x32_bf16 v[124:127], v[128:131], v[154:157], v[124:127]
	v_add3_u32 v134, v134, v133, s2
	v_add3_u32 v144, v132, v133, s81
	ds_read_b128 v[154:157], v134
	ds_read_b128 v[158:161], v134 offset:2048
	ds_read_b128 v[162:165], v134 offset:4096
	ds_read_b128 v[166:169], v134 offset:6144
	ds_read_b128 v[132:135], v144
	ds_read_b128 v[186:189], v144 offset:2048
	ds_read_b128 v[206:209], v144 offset:4096
	ds_read_b128 v[216:219], v144 offset:6144
	s_waitcnt lgkmcnt(11)
	v_mfma_f32_16x16x32_bf16 v[56:59], v[128:131], v[170:173], v[56:59]
	v_mfma_f32_16x16x32_bf16 v[52:55], v[136:139], v[170:173], v[52:55]
	v_mfma_f32_16x16x32_bf16 v[48:51], v[140:143], v[170:173], v[48:51]
	v_mfma_f32_16x16x32_bf16 v[44:47], v[146:149], v[170:173], v[44:47]
	s_waitcnt lgkmcnt(10)
	v_mfma_f32_16x16x32_bf16 v[40:43], v[128:131], v[174:177], v[40:43]
	v_mfma_f32_16x16x32_bf16 v[36:39], v[136:139], v[174:177], v[36:39]
	v_mfma_f32_16x16x32_bf16 v[32:35], v[140:143], v[174:177], v[32:35]
	v_mfma_f32_16x16x32_bf16 v[28:31], v[146:149], v[174:177], v[28:31]
	s_waitcnt lgkmcnt(9)
	v_mfma_f32_16x16x32_bf16 v[24:27], v[128:131], v[178:181], v[24:27]
	v_mfma_f32_16x16x32_bf16 v[20:23], v[136:139], v[178:181], v[20:23]
	v_mfma_f32_16x16x32_bf16 v[16:19], v[140:143], v[178:181], v[16:19]
	v_mfma_f32_16x16x32_bf16 v[12:15], v[146:149], v[178:181], v[12:15]
	s_waitcnt lgkmcnt(8)
	v_mfma_f32_16x16x32_bf16 v[8:11], v[128:131], v[182:185], v[8:11]
	v_mfma_f32_16x16x32_bf16 v[4:7], v[136:139], v[182:185], v[4:7]
	v_mfma_f32_16x16x32_bf16 v[0:3], v[140:143], v[182:185], v[0:3]
	v_mfma_f32_16x16x32_bf16 v[128:131], v[146:149], v[182:185], v[88:91]
	ds_read_b128 v[136:139], v144 offset:8192
	ds_read_b128 v[140:143], v144 offset:10240
	ds_read_b128 v[146:149], v144 offset:12288
	ds_read_b128 v[170:173], v144 offset:14336
	s_waitcnt lgkmcnt(7)
	v_mfma_f32_16x16x32_bf16 v[120:123], v[158:161], v[132:135], v[120:123]
	s_waitcnt lgkmcnt(6)
	v_mfma_f32_16x16x32_bf16 v[108:111], v[154:157], v[186:189], v[108:111]
	v_mfma_f32_16x16x32_bf16 v[104:107], v[158:161], v[186:189], v[104:107]
	v_mfma_f32_16x16x32_bf16 v[100:103], v[162:165], v[186:189], v[100:103]
	v_mfma_f32_16x16x32_bf16 v[96:99], v[166:169], v[186:189], v[96:99]
	s_waitcnt lgkmcnt(5)
	v_mfma_f32_16x16x32_bf16 v[92:95], v[154:157], v[206:209], v[92:95]
	v_mfma_f32_16x16x32_bf16 v[88:91], v[158:161], v[206:209], v[84:87]
	v_mfma_f32_16x16x32_bf16 v[84:87], v[162:165], v[206:209], v[80:83]
	v_mfma_f32_16x16x32_bf16 v[80:83], v[166:169], v[206:209], v[76:79]
	s_waitcnt lgkmcnt(4)
	v_mfma_f32_16x16x32_bf16 v[76:79], v[154:157], v[216:219], v[72:75]
	v_mfma_f32_16x16x32_bf16 v[72:75], v[158:161], v[216:219], v[68:71]
	v_mfma_f32_16x16x32_bf16 v[68:71], v[162:165], v[216:219], v[64:67]
	v_mfma_f32_16x16x32_bf16 v[64:67], v[166:169], v[216:219], v[60:63]
	v_mfma_f32_16x16x32_bf16 v[124:127], v[154:157], v[132:135], v[124:127]
	v_mfma_f32_16x16x32_bf16 v[174:177], v[162:165], v[132:135], v[116:119]
	v_mfma_f32_16x16x32_bf16 v[132:135], v[166:169], v[132:135], v[112:115]
	s_nop 2
	v_mov_b32_e32 v112, v190
	s_lshl_b32 s2, s22, 8
	s_waitcnt lgkmcnt(3)
	v_mfma_f32_16x16x32_bf16 v[60:63], v[154:157], v[136:139], v[56:59]
	v_ashrrev_i32_e32 v113, 1, v112
	s_lshl_b32 s3, s18, 8
	v_bfe_u32 v144, v112, 6, 2
	v_mfma_f32_16x16x32_bf16 v[56:59], v[158:161], v[136:139], v[52:55]
	v_bfe_u32 v151, v112, 4, 2
	v_mfma_f32_16x16x32_bf16 v[52:55], v[162:165], v[136:139], v[48:51]
	v_mfma_f32_16x16x32_bf16 v[48:51], v[166:169], v[136:139], v[44:47]
	s_waitcnt lgkmcnt(2)
	v_mfma_f32_16x16x32_bf16 v[44:47], v[154:157], v[140:143], v[40:43]
	v_mfma_f32_16x16x32_bf16 v[40:43], v[158:161], v[140:143], v[36:39]
	v_mfma_f32_16x16x32_bf16 v[36:39], v[162:165], v[140:143], v[32:35]
	v_mfma_f32_16x16x32_bf16 v[32:35], v[166:169], v[140:143], v[28:31]
	s_nop 2
	v_and_b32_e32 v28, 0xffffff80, v113
	v_and_or_b32 v29, v112, 15, s2
	v_add_u32_e32 v114, v29, v28
	s_ashr_i32 s2, s3, 31
	v_lshlrev_b32_e32 v112, 6, v144
	v_lshlrev_b32_e32 v113, 2, v151
	v_ashrrev_i32_e32 v115, 31, v114
	s_waitcnt lgkmcnt(1)
	v_mfma_f32_16x16x32_bf16 v[28:31], v[154:157], v[146:149], v[24:27]
	v_or3_b32 v116, s3, v112, v113
	v_mov_b32_e32 v117, s2
	v_mfma_f32_16x16x32_bf16 v[24:27], v[158:161], v[146:149], v[20:23]
	v_mfma_f32_16x16x32_bf16 v[20:23], v[162:165], v[146:149], v[16:19]
	s_nop 2
	v_lshlrev_b64 v[16:17], 10, v[114:115]
	v_lshl_add_u64 v[112:113], v[116:117], 0, v[16:17]
	v_lshl_add_u64 v[178:179], v[112:113], 2, s[90:91]
	global_load_dwordx4 v[136:139], v[178:179], off
	v_lshlrev_b64 v[112:113], 1, v[112:113]
	v_mfma_f32_16x16x32_bf16 v[16:19], v[166:169], v[146:149], v[12:15]
	s_waitcnt vmcnt(0)
	v_pk_add_f32 v[126:127], v[126:127], v[138:139]
	s_waitcnt lgkmcnt(0)
	v_mfma_f32_16x16x32_bf16 v[12:15], v[154:157], v[170:173], v[8:11]
	v_add_f32_e64 v124, v124, v136
	v_add_f32_e64 v125, v125, v137
	global_store_dwordx4 v[178:179], v[124:127], off
	v_cvt_pk_bf16_f32 v10, v124, v125
	v_cvt_pk_bf16_f32 v11, v126, v127
	v_lshl_add_u64 v[8:9], s[16:17], 0, v[112:113]
	flat_store_dwordx2 v[8:9], v[10:11]
	global_load_dwordx4 v[136:139], v[178:179], off offset:64
	v_mfma_f32_16x16x32_bf16 v[8:11], v[158:161], v[170:173], v[4:7]
	s_waitcnt vmcnt(0)
	v_pk_add_f32 v[138:139], v[122:123], v[138:139]
	s_nop 0
	v_or_b32_e32 v4, 32, v112
	v_mov_b32_e32 v5, v113
	v_lshl_add_u64 v[4:5], s[16:17], 0, v[4:5]
	v_pk_add_f32 v[136:137], v[120:121], v[136:137]
	global_store_dwordx4 v[178:179], v[136:139], off offset:64
	v_cvt_pk_bf16_f32 v6, v136, v137
	v_cvt_pk_bf16_f32 v7, v138, v139
	flat_store_dwordx2 v[4:5], v[6:7]
	global_load_dwordx4 v[118:121], v[178:179], off offset:128
	v_mfma_f32_16x16x32_bf16 v[4:7], v[162:165], v[170:173], v[0:3]
	v_mul_f32_e32 v122, v137, v137
	v_fmac_f32_e32 v122, v136, v136
	v_fmac_f32_e32 v122, v138, v138
	v_or_b32_e32 v0, 64, v112
	v_mov_b32_e32 v1, v113
	v_lshl_add_u64 v[0:1], s[16:17], 0, v[0:1]
	v_fmac_f32_e32 v122, v139, v139
	v_or_b32_e32 v112, 0x60, v112
	v_lshl_add_u64 v[112:113], s[16:17], 0, v[112:113]
	s_waitcnt vmcnt(0)
	v_pk_add_f32 v[142:143], v[176:177], v[120:121]
	v_pk_add_f32 v[140:141], v[174:175], v[118:119]
	global_store_dwordx4 v[178:179], v[140:143], off offset:128
	v_cvt_pk_bf16_f32 v2, v140, v141
	v_cvt_pk_bf16_f32 v3, v142, v143
	flat_store_dwordx2 v[0:1], v[2:3]
	global_load_dwordx4 v[146:149], v[178:179], off offset:192
	v_and_b32_e32 v119, 64, v194
	v_xor_b32_e32 v118, 16, v194
	v_add_u32_e32 v119, 64, v119
	v_xor_b32_e32 v120, 32, v194
	v_cmp_lt_i32_e32 vcc, v118, v119
	v_mfma_f32_16x16x32_bf16 v[0:3], v[166:169], v[170:173], v[128:131]
	s_nop 0
	v_cndmask_b32_e32 v121, v194, v118, vcc
	v_cmp_lt_i32_e32 vcc, v120, v119
	v_lshl_or_b32 v118, s18, 2, v144
	v_ashrrev_i32_e32 v119, 31, v118
	v_cndmask_b32_e32 v128, v194, v120, vcc
	v_lshlrev_b32_e32 v120, 2, v121
	v_mul_f32_e32 v121, v125, v125
	v_fmac_f32_e32 v121, v124, v124
	v_fmac_f32_e32 v121, v126, v126
	v_fmac_f32_e32 v121, v127, v127
	v_add_f32_e32 v121, v121, v122
	v_mul_f32_e32 v122, v141, v141
	v_fmac_f32_e32 v122, v140, v140
	v_fmac_f32_e32 v122, v142, v142
	v_fmac_f32_e32 v122, v143, v143
	v_add_f32_e32 v121, v121, v122
	v_lshlrev_b64 v[118:119], 16, v[118:119]
	v_cmp_eq_u32_e32 vcc, 0, v151
	s_waitcnt vmcnt(0)
	v_pk_add_f32 v[122:123], v[132:133], v[146:147]
	s_nop 0
	v_mul_f32_e32 v126, v123, v123
	v_pk_add_f32 v[124:125], v[134:135], v[148:149]
	v_fmac_f32_e32 v126, v122, v122
	v_fmac_f32_e32 v126, v124, v124
	v_fmac_f32_e32 v126, v125, v125
	v_add_f32_e32 v121, v121, v126
	ds_bpermute_b32 v129, v120, v121
	v_lshl_add_u64 v[126:127], s[8:9], 0, v[118:119]
	global_store_dwordx4 v[178:179], v[122:125], off offset:192
	s_waitcnt lgkmcnt(0)
	v_add_f32_e32 v118, v121, v129
	v_lshlrev_b32_e32 v121, 2, v128
	ds_bpermute_b32 v119, v121, v118
	v_cvt_pk_bf16_f32 v122, v122, v123
	v_cvt_pk_bf16_f32 v123, v124, v125
	flat_store_dwordx2 v[112:113], v[122:123]
	v_lshl_add_u64 v[112:113], v[114:115], 2, v[126:127]
	s_and_saveexec_b64 s[2:3], vcc
	s_cbranch_execz .LBB0_249
	s_waitcnt lgkmcnt(0)
	v_add_f32_e32 v115, v118, v119
	flat_store_dword v[112:113], v115

.LBB0_419:
	v_and_b32_e32 v5, 15, v3
	v_lshrrev_b32_e32 v6, 1, v3
	s_mov_b32 s3, 0x1ffff80
	s_lshr_b32 s2, s57, 3
	v_and_or_b32 v5, v6, s3, v5
	s_and_b32 s3, s36, 56
	s_and_b32 s2, s2, 3
	s_add_i32 s3, s3, s61
	s_add_i32 s2, s3, s2
	v_and_b32_e32 v4, 3, v4
	v_lshlrev_b32_e32 v136, 7, v5
	v_bfe_u32 v5, v3, 1, 3
	s_ashr_i32 s3, s2, 31
	v_bitop3_b32 v6, v6, v4, 7 bitop3:0x6c
	v_bitop3_b32 v4, v4, v5, 4 bitop3:0x36
	v_lshlrev_b64 v[0:1], 11, v[0:1]
	v_lshlrev_b32_e32 v2, 4, v2
	s_lshl_b64 s[2:3], s[2:3], 19
	v_lshlrev_b32_e32 v137, 4, v4
	v_lshlrev_b32_e32 v3, 7, v3
	s_waitcnt vmcnt(0)
	v_lshl_add_u64 v[4:5], s[26:27], 0, v[0:1]
	v_and_b32_e32 v144, 0x70, v2
	v_lshl_add_u64 v[0:1], s[2:3], 0, v[0:1]
	v_and_b32_e32 v138, 0x6780, v3
	v_lshl_add_u64 v[2:3], v[4:5], 0, v[144:145]
	v_or_b32_e32 v0, v0, v144
	v_mov_b32_e32 v88, 0
	v_lshlrev_b32_e32 v139, 4, v6
	v_lshl_add_u64 v[132:133], s[14:15], 0, v[2:3]
	v_lshl_add_u64 v[134:135], s[14:15], 0, v[0:1]
	s_mov_b64 s[26:27], 0
	s_mov_b32 s2, 0
	v_mov_b32_e32 v89, v88
	v_mov_b32_e32 v90, v88
	v_mov_b32_e32 v91, v88
	v_mov_b32_e32 v0, v88
	v_mov_b32_e32 v1, v88
	v_mov_b32_e32 v2, v88
	v_mov_b32_e32 v3, v88
	v_mov_b32_e32 v4, v88
	v_mov_b32_e32 v5, v88
	v_mov_b32_e32 v6, v88
	v_mov_b32_e32 v7, v88
	v_mov_b32_e32 v8, v88
	v_mov_b32_e32 v9, v88
	v_mov_b32_e32 v10, v88
	v_mov_b32_e32 v11, v88
	v_mov_b32_e32 v12, v88
	v_mov_b32_e32 v13, v88
	v_mov_b32_e32 v14, v88
	v_mov_b32_e32 v15, v88
	v_mov_b32_e32 v16, v88
	v_mov_b32_e32 v17, v88
	v_mov_b32_e32 v18, v88
	v_mov_b32_e32 v19, v88
	v_mov_b32_e32 v20, v88
	v_mov_b32_e32 v21, v88
	v_mov_b32_e32 v22, v88
	v_mov_b32_e32 v23, v88
	v_mov_b32_e32 v24, v88
	v_mov_b32_e32 v25, v88
	v_mov_b32_e32 v26, v88
	v_mov_b32_e32 v27, v88
	v_mov_b32_e32 v28, v88
	v_mov_b32_e32 v29, v88
	v_mov_b32_e32 v30, v88
	v_mov_b32_e32 v31, v88
	v_mov_b32_e32 v32, v88
	v_mov_b32_e32 v33, v88
	v_mov_b32_e32 v34, v88
	v_mov_b32_e32 v35, v88
	v_mov_b32_e32 v36, v88
	v_mov_b32_e32 v37, v88
	v_mov_b32_e32 v38, v88
	v_mov_b32_e32 v39, v88
	v_mov_b32_e32 v40, v88
	v_mov_b32_e32 v41, v88
	v_mov_b32_e32 v42, v88
	v_mov_b32_e32 v43, v88
	v_mov_b32_e32 v44, v88
	v_mov_b32_e32 v45, v88
	v_mov_b32_e32 v46, v88
	v_mov_b32_e32 v47, v88
	v_mov_b32_e32 v48, v88
	v_mov_b32_e32 v49, v88
	v_mov_b32_e32 v50, v88
	v_mov_b32_e32 v51, v88
	v_mov_b32_e32 v52, v88
	v_mov_b32_e32 v53, v88
	v_mov_b32_e32 v54, v88
	v_mov_b32_e32 v55, v88
	v_mov_b32_e32 v56, v88
	v_mov_b32_e32 v57, v88
	v_mov_b32_e32 v58, v88
	v_mov_b32_e32 v59, v88
	v_mov_b32_e32 v60, v88
	v_mov_b32_e32 v61, v88
	v_mov_b32_e32 v62, v88
	v_mov_b32_e32 v63, v88
	v_mov_b32_e32 v64, v88
	v_mov_b32_e32 v65, v88
	v_mov_b32_e32 v66, v88
	v_mov_b32_e32 v67, v88
	v_mov_b32_e32 v68, v88
	v_mov_b32_e32 v69, v88
	v_mov_b32_e32 v70, v88
	v_mov_b32_e32 v71, v88
	v_mov_b32_e32 v72, v88
	v_mov_b32_e32 v73, v88
	v_mov_b32_e32 v74, v88
	v_mov_b32_e32 v75, v88
	v_mov_b32_e32 v76, v88
	v_mov_b32_e32 v77, v88
	v_mov_b32_e32 v78, v88
	v_mov_b32_e32 v79, v88
	v_mov_b32_e32 v80, v88
	v_mov_b32_e32 v81, v88
	v_mov_b32_e32 v82, v88
	v_mov_b32_e32 v83, v88
	v_mov_b32_e32 v84, v88
	v_mov_b32_e32 v85, v88
	v_mov_b32_e32 v86, v88
	v_mov_b32_e32 v87, v88
	v_mov_b32_e32 v92, v88
	v_mov_b32_e32 v93, v88
	v_mov_b32_e32 v94, v88
	v_mov_b32_e32 v95, v88
	v_mov_b32_e32 v96, v88
	v_mov_b32_e32 v97, v88
	v_mov_b32_e32 v98, v88
	v_mov_b32_e32 v99, v88
	v_mov_b32_e32 v100, v88
	v_mov_b32_e32 v101, v88
	v_mov_b32_e32 v102, v88
	v_mov_b32_e32 v103, v88
	v_mov_b32_e32 v104, v88
	v_mov_b32_e32 v105, v88
	v_mov_b32_e32 v106, v88
	v_mov_b32_e32 v107, v88
	v_mov_b32_e32 v108, v88
	v_mov_b32_e32 v109, v88
	v_mov_b32_e32 v110, v88
	v_mov_b32_e32 v111, v88
	v_mov_b32_e32 v112, v88
	v_mov_b32_e32 v113, v88
	v_mov_b32_e32 v114, v88
	v_mov_b32_e32 v115, v88
	v_mov_b32_e32 v116, v88
	v_mov_b32_e32 v117, v88
	v_mov_b32_e32 v118, v88
	v_mov_b32_e32 v119, v88
	v_mov_b32_e32 v120, v88
	v_mov_b32_e32 v121, v88
	v_mov_b32_e32 v122, v88
	v_mov_b32_e32 v123, v88
	v_mov_b32_e32 v124, v88
	v_mov_b32_e32 v125, v88
	v_mov_b32_e32 v126, v88
	v_mov_b32_e32 v127, v88
	s_mov_b64 s[38:39], 0x3a20080
	s_mov_b64 s[40:41], 0x3a40080
	s_waitcnt vmcnt(0) lgkmcnt(0)
	s_barrier
	s_bitcmp1_b32 s0, 12
	s_cbranch_scc1 .Lkb_420
.LBB0_420:
	s_add_i32 s3, s2, 0x10000
	s_and_b32 s7, s3, 0x10000
	s_add_i32 s7, s0, s7
	v_lshl_add_u64 v[140:141], v[134:135], 0, s[26:27]
	v_lshl_add_u64 v[142:143], v[140:141], 0, s[64:65]
	s_mov_b32 m0, s7
	s_mov_b64 s[62:63], 0x1080080
	global_load_lds_dwordx4 v[142:143], off
	v_lshl_add_u64 v[142:143], v[140:141], 0, s[68:69]
	s_add_i32 m0, s7, 0x2000
	s_nop 0
	global_load_lds_dwordx4 v[142:143], off
	v_lshl_add_u64 v[142:143], v[140:141], 0, s[38:39]
	s_add_i32 m0, s7, 0x4000
	v_lshl_add_u64 v[140:141], v[140:141], 0, s[40:41]
	global_load_lds_dwordx4 v[142:143], off
	s_add_i32 m0, s7, 0x6000
	s_nop 0
	global_load_lds_dwordx4 v[140:141], off
	v_lshl_add_u64 v[140:141], v[132:133], 0, s[26:27]
	v_lshl_add_u64 v[142:143], v[140:141], 0, s[62:63]
	s_add_i32 m0, s7, 0x8000
	s_mov_b64 s[62:63], 0x10a0080
	global_load_lds_dwordx4 v[142:143], off
	v_lshl_add_u64 v[142:143], v[140:141], 0, s[62:63]
	s_add_i32 m0, s7, 0xa000
	s_mov_b64 s[62:63], 0x10c0080
	global_load_lds_dwordx4 v[142:143], off
	v_lshl_add_u64 v[142:143], v[140:141], 0, s[62:63]
	s_add_i32 m0, s7, 0xc000
	s_mov_b64 s[62:63], 0x10e0080
	global_load_lds_dwordx4 v[142:143], off
	v_lshl_add_u64 v[140:141], v[140:141], 0, s[62:63]
	s_add_i32 m0, s7, 0xe000
	s_nop 0
	global_load_lds_dwordx4 v[140:141], off
	s_and_b32 s2, s2, 0x10000
	v_or_b32_e32 v129, s2, v139
	v_add_u32_e32 v144, v129, v138
	v_add_u32_e32 v129, v129, v136
	ds_read_b128 v[140:143], v144 offset:32768
	ds_read_b128 v[146:149], v144 offset:34816
	ds_read_b128 v[154:157], v144 offset:36864
	ds_read_b128 v[158:161], v144 offset:38912
	ds_read_b128 v[162:165], v129
	ds_read_b128 v[166:169], v129 offset:2048
	ds_read_b128 v[170:173], v129 offset:4096
	ds_read_b128 v[174:177], v129 offset:6144
	ds_read_b128 v[178:181], v129 offset:8192
	ds_read_b128 v[182:185], v129 offset:10240
	ds_read_b128 v[186:189], v129 offset:12288
	ds_read_b128 v[206:209], v129 offset:14336
	s_waitcnt lgkmcnt(0)
	v_mfma_f32_16x16x32_bf16 v[124:127], v[140:143], v[162:165], v[124:127]
	v_mfma_f32_16x16x32_bf16 v[120:123], v[146:149], v[162:165], v[120:123]
	v_mfma_f32_16x16x32_bf16 v[116:119], v[154:157], v[162:165], v[116:119]
	v_mfma_f32_16x16x32_bf16 v[112:115], v[158:161], v[162:165], v[112:115]
	v_mfma_f32_16x16x32_bf16 v[108:111], v[140:143], v[166:169], v[108:111]
	v_mfma_f32_16x16x32_bf16 v[104:107], v[146:149], v[166:169], v[104:107]
	v_mfma_f32_16x16x32_bf16 v[100:103], v[154:157], v[166:169], v[100:103]
	v_mfma_f32_16x16x32_bf16 v[96:99], v[158:161], v[166:169], v[96:99]
	v_mfma_f32_16x16x32_bf16 v[92:95], v[140:143], v[170:173], v[92:95]
	v_mfma_f32_16x16x32_bf16 v[84:87], v[146:149], v[170:173], v[84:87]
	v_mfma_f32_16x16x32_bf16 v[80:83], v[154:157], v[170:173], v[80:83]
	v_mfma_f32_16x16x32_bf16 v[76:79], v[158:161], v[170:173], v[76:79]
	v_mfma_f32_16x16x32_bf16 v[72:75], v[140:143], v[174:177], v[72:75]
	v_mfma_f32_16x16x32_bf16 v[68:71], v[146:149], v[174:177], v[68:71]
	v_mfma_f32_16x16x32_bf16 v[64:67], v[154:157], v[174:177], v[64:67]
	v_mfma_f32_16x16x32_bf16 v[60:63], v[158:161], v[174:177], v[60:63]
	v_or_b32_e32 v129, s2, v137
	v_add_u32_e32 v144, v129, v138
	v_add_u32_e32 v129, v129, v136
	ds_read_b128 v[162:165], v144 offset:32768
	ds_read_b128 v[166:169], v144 offset:34816
	ds_read_b128 v[170:173], v144 offset:36864
	ds_read_b128 v[174:177], v144 offset:38912
	ds_read_b128 v[216:219], v129
	ds_read_b128 v[220:223], v129 offset:2048
	ds_read_b128 v[224:227], v129 offset:4096
	ds_read_b128 v[228:231], v129 offset:6144
	v_mfma_f32_16x16x32_bf16 v[56:59], v[140:143], v[178:181], v[56:59]
	v_mfma_f32_16x16x32_bf16 v[52:55], v[146:149], v[178:181], v[52:55]
	v_mfma_f32_16x16x32_bf16 v[48:51], v[154:157], v[178:181], v[48:51]
	v_mfma_f32_16x16x32_bf16 v[44:47], v[158:161], v[178:181], v[44:47]
	v_mfma_f32_16x16x32_bf16 v[40:43], v[140:143], v[182:185], v[40:43]
	v_mfma_f32_16x16x32_bf16 v[36:39], v[146:149], v[182:185], v[36:39]
	v_mfma_f32_16x16x32_bf16 v[32:35], v[154:157], v[182:185], v[32:35]
	v_mfma_f32_16x16x32_bf16 v[28:31], v[158:161], v[182:185], v[28:31]
	v_mfma_f32_16x16x32_bf16 v[24:27], v[140:143], v[186:189], v[24:27]
	v_mfma_f32_16x16x32_bf16 v[20:23], v[146:149], v[186:189], v[20:23]
	v_mfma_f32_16x16x32_bf16 v[16:19], v[154:157], v[186:189], v[16:19]
	v_mfma_f32_16x16x32_bf16 v[12:15], v[158:161], v[186:189], v[12:15]
	v_mfma_f32_16x16x32_bf16 v[8:11], v[140:143], v[206:209], v[8:11]
	v_mfma_f32_16x16x32_bf16 v[4:7], v[146:149], v[206:209], v[4:7]
	v_mfma_f32_16x16x32_bf16 v[0:3], v[154:157], v[206:209], v[0:3]
	v_mfma_f32_16x16x32_bf16 v[88:91], v[158:161], v[206:209], v[88:91]
	ds_read_b128 v[140:143], v129 offset:8192
	ds_read_b128 v[146:149], v129 offset:10240
	ds_read_b128 v[154:157], v129 offset:12288
	ds_read_b128 v[158:161], v129 offset:14336
	s_waitcnt lgkmcnt(0)
	v_mfma_f32_16x16x32_bf16 v[124:127], v[162:165], v[216:219], v[124:127]
	v_mfma_f32_16x16x32_bf16 v[120:123], v[166:169], v[216:219], v[120:123]
	v_mfma_f32_16x16x32_bf16 v[116:119], v[170:173], v[216:219], v[116:119]
	v_mfma_f32_16x16x32_bf16 v[112:115], v[174:177], v[216:219], v[112:115]
	v_mfma_f32_16x16x32_bf16 v[108:111], v[162:165], v[220:223], v[108:111]
	v_mfma_f32_16x16x32_bf16 v[104:107], v[166:169], v[220:223], v[104:107]
	v_mfma_f32_16x16x32_bf16 v[100:103], v[170:173], v[220:223], v[100:103]
	v_mfma_f32_16x16x32_bf16 v[96:99], v[174:177], v[220:223], v[96:99]
	v_mfma_f32_16x16x32_bf16 v[92:95], v[162:165], v[224:227], v[92:95]
	v_mfma_f32_16x16x32_bf16 v[84:87], v[166:169], v[224:227], v[84:87]
	v_mfma_f32_16x16x32_bf16 v[80:83], v[170:173], v[224:227], v[80:83]
	v_mfma_f32_16x16x32_bf16 v[76:79], v[174:177], v[224:227], v[76:79]
	v_mfma_f32_16x16x32_bf16 v[72:75], v[162:165], v[228:231], v[72:75]
	v_mfma_f32_16x16x32_bf16 v[68:71], v[166:169], v[228:231], v[68:71]
	v_mfma_f32_16x16x32_bf16 v[64:67], v[170:173], v[228:231], v[64:67]
	v_mfma_f32_16x16x32_bf16 v[60:63], v[174:177], v[228:231], v[60:63]
	v_mfma_f32_16x16x32_bf16 v[56:59], v[162:165], v[140:143], v[56:59]
	s_waitcnt vmcnt(0)
	s_add_u32 s26, s26, 0x80
	s_addc_u32 s27, s27, 0
	v_mfma_f32_16x16x32_bf16 v[52:55], v[166:169], v[140:143], v[52:55]
	s_cmpk_eq_i32 s26, 0x780
	s_mov_b32 s2, s3
	s_waitcnt vmcnt(0)
	v_mfma_f32_16x16x32_bf16 v[48:51], v[170:173], v[140:143], v[48:51]
	s_barrier
	v_mfma_f32_16x16x32_bf16 v[44:47], v[174:177], v[140:143], v[44:47]
	v_mfma_f32_16x16x32_bf16 v[40:43], v[162:165], v[146:149], v[40:43]
	v_mfma_f32_16x16x32_bf16 v[36:39], v[166:169], v[146:149], v[36:39]
	v_mfma_f32_16x16x32_bf16 v[32:35], v[170:173], v[146:149], v[32:35]
	v_mfma_f32_16x16x32_bf16 v[28:31], v[174:177], v[146:149], v[28:31]
	v_mfma_f32_16x16x32_bf16 v[24:27], v[162:165], v[154:157], v[24:27]
	v_mfma_f32_16x16x32_bf16 v[20:23], v[166:169], v[154:157], v[20:23]
	v_mfma_f32_16x16x32_bf16 v[16:19], v[170:173], v[154:157], v[16:19]
	v_mfma_f32_16x16x32_bf16 v[12:15], v[174:177], v[154:157], v[12:15]
	v_mfma_f32_16x16x32_bf16 v[8:11], v[162:165], v[158:161], v[8:11]
	v_mfma_f32_16x16x32_bf16 v[4:7], v[166:169], v[158:161], v[4:7]
	v_mfma_f32_16x16x32_bf16 v[0:3], v[170:173], v[158:161], v[0:3]
	v_mfma_f32_16x16x32_bf16 v[88:91], v[174:177], v[158:161], v[88:91]
	s_cbranch_scc0 .LBB0_420
	s_branch .Lkx_420
.Lkb_420:
	s_add_i32 s3, s2, 0x10000
	s_and_b32 s7, s3, 0x10000
	s_add_i32 s7, s0, s7
	s_and_b32 s2, s2, 0x10000
	v_or_b32_e32 v129, s2, v139
	v_add_u32_e32 v144, v129, v138
	v_add_u32_e32 v129, v129, v136
	ds_read_b128 v[140:143], v144 offset:32768
	ds_read_b128 v[146:149], v144 offset:34816
	ds_read_b128 v[154:157], v144 offset:36864
	ds_read_b128 v[158:161], v144 offset:38912
	ds_read_b128 v[162:165], v129
	ds_read_b128 v[166:169], v129 offset:2048
	ds_read_b128 v[170:173], v129 offset:4096
	ds_read_b128 v[174:177], v129 offset:6144
	ds_read_b128 v[178:181], v129 offset:8192
	ds_read_b128 v[182:185], v129 offset:10240
	ds_read_b128 v[186:189], v129 offset:12288
	ds_read_b128 v[206:209], v129 offset:14336
	s_waitcnt lgkmcnt(0)
	v_mfma_f32_16x16x32_bf16 v[124:127], v[140:143], v[162:165], v[124:127]
	v_mfma_f32_16x16x32_bf16 v[120:123], v[146:149], v[162:165], v[120:123]
	v_mfma_f32_16x16x32_bf16 v[116:119], v[154:157], v[162:165], v[116:119]
	v_mfma_f32_16x16x32_bf16 v[112:115], v[158:161], v[162:165], v[112:115]
	v_mfma_f32_16x16x32_bf16 v[108:111], v[140:143], v[166:169], v[108:111]
	v_mfma_f32_16x16x32_bf16 v[104:107], v[146:149], v[166:169], v[104:107]
	v_mfma_f32_16x16x32_bf16 v[100:103], v[154:157], v[166:169], v[100:103]
	v_mfma_f32_16x16x32_bf16 v[96:99], v[158:161], v[166:169], v[96:99]
	v_mfma_f32_16x16x32_bf16 v[92:95], v[140:143], v[170:173], v[92:95]
	v_mfma_f32_16x16x32_bf16 v[84:87], v[146:149], v[170:173], v[84:87]
	v_mfma_f32_16x16x32_bf16 v[80:83], v[154:157], v[170:173], v[80:83]
	v_mfma_f32_16x16x32_bf16 v[76:79], v[158:161], v[170:173], v[76:79]
	v_mfma_f32_16x16x32_bf16 v[72:75], v[140:143], v[174:177], v[72:75]
	v_mfma_f32_16x16x32_bf16 v[68:71], v[146:149], v[174:177], v[68:71]
	v_mfma_f32_16x16x32_bf16 v[64:67], v[154:157], v[174:177], v[64:67]
	v_mfma_f32_16x16x32_bf16 v[60:63], v[158:161], v[174:177], v[60:63]
	v_or_b32_e32 v129, s2, v137
	v_add_u32_e32 v144, v129, v138
	v_add_u32_e32 v129, v129, v136
	ds_read_b128 v[162:165], v144 offset:32768
	ds_read_b128 v[166:169], v144 offset:34816
	ds_read_b128 v[170:173], v144 offset:36864
	ds_read_b128 v[174:177], v144 offset:38912
	ds_read_b128 v[216:219], v129
	ds_read_b128 v[220:223], v129 offset:2048
	ds_read_b128 v[224:227], v129 offset:4096
	ds_read_b128 v[228:231], v129 offset:6144
	v_mfma_f32_16x16x32_bf16 v[56:59], v[140:143], v[178:181], v[56:59]
	v_mfma_f32_16x16x32_bf16 v[52:55], v[146:149], v[178:181], v[52:55]
	v_mfma_f32_16x16x32_bf16 v[48:51], v[154:157], v[178:181], v[48:51]
	v_mfma_f32_16x16x32_bf16 v[44:47], v[158:161], v[178:181], v[44:47]
	v_mfma_f32_16x16x32_bf16 v[40:43], v[140:143], v[182:185], v[40:43]
	v_mfma_f32_16x16x32_bf16 v[36:39], v[146:149], v[182:185], v[36:39]
	v_mfma_f32_16x16x32_bf16 v[32:35], v[154:157], v[182:185], v[32:35]
	v_mfma_f32_16x16x32_bf16 v[28:31], v[158:161], v[182:185], v[28:31]
	v_mfma_f32_16x16x32_bf16 v[24:27], v[140:143], v[186:189], v[24:27]
	v_mfma_f32_16x16x32_bf16 v[20:23], v[146:149], v[186:189], v[20:23]
	v_mfma_f32_16x16x32_bf16 v[16:19], v[154:157], v[186:189], v[16:19]
	v_mfma_f32_16x16x32_bf16 v[12:15], v[158:161], v[186:189], v[12:15]
	v_mfma_f32_16x16x32_bf16 v[8:11], v[140:143], v[206:209], v[8:11]
	v_mfma_f32_16x16x32_bf16 v[4:7], v[146:149], v[206:209], v[4:7]
	v_mfma_f32_16x16x32_bf16 v[0:3], v[154:157], v[206:209], v[0:3]
	v_mfma_f32_16x16x32_bf16 v[88:91], v[158:161], v[206:209], v[88:91]
	v_lshl_add_u64 v[244:245], v[134:135], 0, s[26:27]
	v_lshl_add_u64 v[246:247], v[244:245], 0, s[64:65]
	s_mov_b32 m0, s7
	s_mov_b64 s[62:63], 0x1080080
	global_load_lds_dwordx4 v[246:247], off
	v_lshl_add_u64 v[246:247], v[244:245], 0, s[68:69]
	s_add_i32 m0, s7, 0x2000
	s_nop 0
	global_load_lds_dwordx4 v[246:247], off
	v_lshl_add_u64 v[246:247], v[244:245], 0, s[38:39]
	s_add_i32 m0, s7, 0x4000
	v_lshl_add_u64 v[244:245], v[244:245], 0, s[40:41]
	global_load_lds_dwordx4 v[246:247], off
	s_add_i32 m0, s7, 0x6000
	s_nop 0
	global_load_lds_dwordx4 v[244:245], off
	v_lshl_add_u64 v[244:245], v[132:133], 0, s[26:27]
	v_lshl_add_u64 v[246:247], v[244:245], 0, s[62:63]
	s_add_i32 m0, s7, 0x8000
	s_mov_b64 s[62:63], 0x10a0080
	global_load_lds_dwordx4 v[246:247], off
	v_lshl_add_u64 v[246:247], v[244:245], 0, s[62:63]
	s_add_i32 m0, s7, 0xa000
	s_mov_b64 s[62:63], 0x10c0080
	global_load_lds_dwordx4 v[246:247], off
	v_lshl_add_u64 v[246:247], v[244:245], 0, s[62:63]
	s_add_i32 m0, s7, 0xc000
	s_mov_b64 s[62:63], 0x10e0080
	global_load_lds_dwordx4 v[246:247], off
	v_lshl_add_u64 v[244:245], v[244:245], 0, s[62:63]
	s_add_i32 m0, s7, 0xe000
	s_nop 0
	global_load_lds_dwordx4 v[244:245], off
	ds_read_b128 v[140:143], v129 offset:8192
	ds_read_b128 v[146:149], v129 offset:10240
	ds_read_b128 v[154:157], v129 offset:12288
	ds_read_b128 v[158:161], v129 offset:14336
	s_waitcnt lgkmcnt(0)
	v_mfma_f32_16x16x32_bf16 v[124:127], v[162:165], v[216:219], v[124:127]
	v_mfma_f32_16x16x32_bf16 v[120:123], v[166:169], v[216:219], v[120:123]
	v_mfma_f32_16x16x32_bf16 v[116:119], v[170:173], v[216:219], v[116:119]
	v_mfma_f32_16x16x32_bf16 v[112:115], v[174:177], v[216:219], v[112:115]
	v_mfma_f32_16x16x32_bf16 v[108:111], v[162:165], v[220:223], v[108:111]
	v_mfma_f32_16x16x32_bf16 v[104:107], v[166:169], v[220:223], v[104:107]
	v_mfma_f32_16x16x32_bf16 v[100:103], v[170:173], v[220:223], v[100:103]
	v_mfma_f32_16x16x32_bf16 v[96:99], v[174:177], v[220:223], v[96:99]
	v_mfma_f32_16x16x32_bf16 v[92:95], v[162:165], v[224:227], v[92:95]
	v_mfma_f32_16x16x32_bf16 v[84:87], v[166:169], v[224:227], v[84:87]
	v_mfma_f32_16x16x32_bf16 v[80:83], v[170:173], v[224:227], v[80:83]
	v_mfma_f32_16x16x32_bf16 v[76:79], v[174:177], v[224:227], v[76:79]
	v_mfma_f32_16x16x32_bf16 v[72:75], v[162:165], v[228:231], v[72:75]
	v_mfma_f32_16x16x32_bf16 v[68:71], v[166:169], v[228:231], v[68:71]
	v_mfma_f32_16x16x32_bf16 v[64:67], v[170:173], v[228:231], v[64:67]
	v_mfma_f32_16x16x32_bf16 v[60:63], v[174:177], v[228:231], v[60:63]
	v_mfma_f32_16x16x32_bf16 v[56:59], v[162:165], v[140:143], v[56:59]
	s_add_u32 s26, s26, 0x80
	s_addc_u32 s27, s27, 0
	v_mfma_f32_16x16x32_bf16 v[52:55], v[166:169], v[140:143], v[52:55]
	s_cmpk_eq_i32 s26, 0x780
	s_mov_b32 s2, s3
	s_waitcnt vmcnt(0)
	v_mfma_f32_16x16x32_bf16 v[48:51], v[170:173], v[140:143], v[48:51]
	s_barrier
	v_mfma_f32_16x16x32_bf16 v[44:47], v[174:177], v[140:143], v[44:47]
	v_mfma_f32_16x16x32_bf16 v[40:43], v[162:165], v[146:149], v[40:43]
	v_mfma_f32_16x16x32_bf16 v[36:39], v[166:169], v[146:149], v[36:39]
	v_mfma_f32_16x16x32_bf16 v[32:35], v[170:173], v[146:149], v[32:35]
	v_mfma_f32_16x16x32_bf16 v[28:31], v[174:177], v[146:149], v[28:31]
	v_mfma_f32_16x16x32_bf16 v[24:27], v[162:165], v[154:157], v[24:27]
	v_mfma_f32_16x16x32_bf16 v[20:23], v[166:169], v[154:157], v[20:23]
	v_mfma_f32_16x16x32_bf16 v[16:19], v[170:173], v[154:157], v[16:19]
	v_mfma_f32_16x16x32_bf16 v[12:15], v[174:177], v[154:157], v[12:15]
	v_mfma_f32_16x16x32_bf16 v[8:11], v[162:165], v[158:161], v[8:11]
	v_mfma_f32_16x16x32_bf16 v[4:7], v[166:169], v[158:161], v[4:7]
	v_mfma_f32_16x16x32_bf16 v[0:3], v[170:173], v[158:161], v[0:3]
	v_mfma_f32_16x16x32_bf16 v[88:91], v[174:177], v[158:161], v[88:91]
	s_cbranch_scc0 .Lkb_420
.Lkx_420:
	s_cmp_eq_u64 s[22:23], 0
	s_cbranch_scc1 .LBB0_423
	v_lshl_add_u64 v[132:133], s[22:23], 0, v[130:131]
	v_mov_b32_e32 v129, v145
	v_lshl_add_u64 v[130:131], s[20:21], 0, v[130:131]
	v_lshl_add_u64 v[132:133], v[132:133], 0, v[128:129]
	v_lshl_add_u64 v[128:129], v[130:131], 0, v[128:129]
	s_mov_b64 s[20:21], 0x20000
	s_mov_b64 s[2:3], 0x40000
	s_mov_b64 s[22:23], 0x60000
	s_mov_b32 m0, s0
	v_lshl_add_u64 v[130:131], v[132:133], 0, s[20:21]
	v_lshl_add_u64 v[134:135], v[132:133], 0, s[2:3]
	v_lshl_add_u64 v[140:141], v[132:133], 0, s[22:23]
	v_lshl_add_u64 v[142:143], v[128:129], 0, s[20:21]
	v_lshl_add_u64 v[146:147], v[128:129], 0, s[2:3]
	v_lshl_add_u64 v[148:149], v[128:129], 0, s[22:23]
	s_add_i32 s2, s0, 0xe000
	s_add_i32 s3, s0, 0xc000
	s_add_i32 s7, s0, 0xa000
	s_add_i32 s20, s0, 0x8000
	s_add_i32 s21, s0, 0x6000
	s_add_i32 s22, s0, 0x4000
	s_addk_i32 s0, 0x2000
	global_load_lds_dwordx4 v[132:133], off
	s_mov_b32 m0, s0
	s_mov_b64 s[86:87], 0x20000
	global_load_lds_dwordx4 v[130:131], off
	s_mov_b32 m0, s22
	s_nop 0
	global_load_lds_dwordx4 v[134:135], off
	s_mov_b32 m0, s21
	s_nop 0
	global_load_lds_dwordx4 v[140:141], off
	s_mov_b32 m0, s20
	s_nop 0
	global_load_lds_dwordx4 v[128:129], off
	s_mov_b32 m0, s7
	s_nop 0
	global_load_lds_dwordx4 v[142:143], off
	s_mov_b32 m0, s3
	s_nop 0
	global_load_lds_dwordx4 v[146:147], off
	s_mov_b32 m0, s2
	s_nop 0
	global_load_lds_dwordx4 v[148:149], off

.LBB0_499:
	s_ashr_i32 s2, s34, 5
	s_lshr_b32 s3, s2, 30
	s_add_i32 s3, s2, s3
	s_and_b32 s36, s3, -4
	s_sub_i32 s35, s2, s36
	s_lshl_b32 s2, s34, 3
	s_and_b32 s2, s2, 56
	s_bfe_u32 s27, s34, 0x20003
	s_add_i32 s2, s36, s2
	s_or_b32 s2, s2, s27
	s_and_b32 s26, s31, 56
	s_mul_i32 s6, s2, 0x160000
	s_mul_hi_i32 s3, s2, 0x160000
	s_add_u32 s6, s29, s6
	s_addc_u32 s7, s30, s3
	s_mul_i32 s3, s35, 0x160000
	s_ashr_i32 s9, s3, 31
	s_waitcnt vmcnt(0) lgkmcnt(0)
	v_mov_b32_e32 v4, v190
	s_add_u32 s8, s0, s3
	s_mov_b32 s3, 0x1ffff80
	v_and_b32_e32 v0, 15, v4
	v_lshrrev_b32_e32 v2, 1, v4
	v_and_or_b32 v0, v2, s3, v0
	v_bfe_u32 v1, v4, 4, 2
	v_lshlrev_b32_e32 v132, 7, v0
	v_bfe_u32 v0, v4, 1, 3
	v_lshrrev_b32_e32 v5, 4, v4
	v_bitop3_b32 v2, v2, v1, 7 bitop3:0x6c
	v_bitop3_b32 v0, v1, v0, 4 bitop3:0x36
	v_lshlrev_b32_e32 v135, 4, v2
	v_lshlrev_b32_e32 v133, 4, v0
	v_lshlrev_b32_e32 v0, 7, v4
	v_xor_b32_e32 v2, v5, v4
	v_readfirstlane_b32 s3, v4
	s_addc_u32 s9, s28, s9
	v_and_b32_e32 v134, 0x6780, v0
	v_ashrrev_i32_e32 v6, 3, v4
	v_mov_b64_e32 v[0:1], s[6:7]
	v_lshlrev_b32_e32 v2, 4, v2
	s_lshl_b32 s3, s3, 4
	v_mad_i64_i32 v[0:1], s[6:7], v6, s33, v[0:1]
	v_and_b32_e32 v144, 0x70, v2
	v_mov_b64_e32 v[2:3], s[8:9]
	s_and_b32 s3, s3, 0xfffffc00
	v_lshl_add_u64 v[0:1], v[0:1], 0, v[144:145]
	v_mad_i64_i32 v[2:3], s[6:7], v6, s33, v[2:3]
	s_mov_b32 m0, s3
	v_lshl_add_u64 v[128:129], v[2:3], 0, v[144:145]
	s_barrier
	global_load_lds_dwordx4 v[0:1], off
	v_lshl_add_u64 v[2:3], v[0:1], 0, s[54:55]
	s_add_i32 m0, s3, 0x2000
	s_add_i32 s26, s26, s36
	global_load_lds_dwordx4 v[2:3], off
	v_lshl_add_u64 v[2:3], v[0:1], 0, s[56:57]
	s_add_i32 m0, s3, 0x4000
	v_lshl_add_u64 v[0:1], v[0:1], 0, s[62:63]
	global_load_lds_dwordx4 v[2:3], off
	s_add_i32 m0, s3, 0x6000
	s_or_b32 s8, s26, s27
	global_load_lds_dwordx4 v[0:1], off
	s_add_i32 m0, s3, 0x8000
	v_lshl_add_u64 v[0:1], v[128:129], 0, s[54:55]
	global_load_lds_dwordx4 v[128:129], off
	s_add_i32 m0, s3, 0xa000
	v_bitop3_b32 v2, v5, 7, v4 bitop3:0x48
	global_load_lds_dwordx4 v[0:1], off
	v_lshl_add_u64 v[0:1], v[128:129], 0, s[56:57]
	s_add_i32 m0, s3, 0xc000
	v_mov_b32_e32 v88, 0
	global_load_lds_dwordx4 v[0:1], off
	v_lshl_add_u64 v[0:1], v[128:129], 0, s[62:63]
	s_add_i32 m0, s3, 0xe000
	v_mov_b32_e32 v89, v88
	global_load_lds_dwordx4 v[0:1], off
	v_mad_i64_i32 v[0:1], s[6:7], v6, s33, 0
	s_waitcnt vmcnt(0)
	v_mad_i64_i32 v[0:1], s[6:7], s8, v210, v[0:1]
	v_lshl_or_b32 v0, v2, 4, v0
	v_lshl_add_u64 v[130:131], s[14:15], 0, v[0:1]
	s_mov_b64 s[6:7], 0
	s_mov_b32 s8, 0
	v_mov_b32_e32 v90, v88
	v_mov_b32_e32 v91, v88
	v_mov_b32_e32 v0, v88
	v_mov_b32_e32 v1, v88
	v_mov_b32_e32 v2, v88
	v_mov_b32_e32 v3, v88
	v_mov_b32_e32 v4, v88
	v_mov_b32_e32 v5, v88
	v_mov_b32_e32 v6, v88
	v_mov_b32_e32 v7, v88
	v_mov_b32_e32 v8, v88
	v_mov_b32_e32 v9, v88
	v_mov_b32_e32 v10, v88
	v_mov_b32_e32 v11, v88
	v_mov_b32_e32 v12, v88
	v_mov_b32_e32 v13, v88
	v_mov_b32_e32 v14, v88
	v_mov_b32_e32 v15, v88
	v_mov_b32_e32 v16, v88
	v_mov_b32_e32 v17, v88
	v_mov_b32_e32 v18, v88
	v_mov_b32_e32 v19, v88
	v_mov_b32_e32 v20, v88
	v_mov_b32_e32 v21, v88
	v_mov_b32_e32 v22, v88
	v_mov_b32_e32 v23, v88
	v_mov_b32_e32 v24, v88
	v_mov_b32_e32 v25, v88
	v_mov_b32_e32 v26, v88
	v_mov_b32_e32 v27, v88
	v_mov_b32_e32 v28, v88
	v_mov_b32_e32 v29, v88
	v_mov_b32_e32 v30, v88
	v_mov_b32_e32 v31, v88
	v_mov_b32_e32 v32, v88
	v_mov_b32_e32 v33, v88
	v_mov_b32_e32 v34, v88
	v_mov_b32_e32 v35, v88
	v_mov_b32_e32 v36, v88
	v_mov_b32_e32 v37, v88
	v_mov_b32_e32 v38, v88
	v_mov_b32_e32 v39, v88
	v_mov_b32_e32 v40, v88
	v_mov_b32_e32 v41, v88
	v_mov_b32_e32 v42, v88
	v_mov_b32_e32 v43, v88
	v_mov_b32_e32 v44, v88
	v_mov_b32_e32 v45, v88
	v_mov_b32_e32 v46, v88
	v_mov_b32_e32 v47, v88
	v_mov_b32_e32 v48, v88
	v_mov_b32_e32 v49, v88
	v_mov_b32_e32 v50, v88
	v_mov_b32_e32 v51, v88
	v_mov_b32_e32 v52, v88
	v_mov_b32_e32 v53, v88
	v_mov_b32_e32 v54, v88
	v_mov_b32_e32 v55, v88
	v_mov_b32_e32 v56, v88
	v_mov_b32_e32 v57, v88
	v_mov_b32_e32 v58, v88
	v_mov_b32_e32 v59, v88
	v_mov_b32_e32 v60, v88
	v_mov_b32_e32 v61, v88
	v_mov_b32_e32 v62, v88
	v_mov_b32_e32 v63, v88
	v_mov_b32_e32 v64, v88
	v_mov_b32_e32 v65, v88
	v_mov_b32_e32 v66, v88
	v_mov_b32_e32 v67, v88
	v_mov_b32_e32 v68, v88
	v_mov_b32_e32 v69, v88
	v_mov_b32_e32 v70, v88
	v_mov_b32_e32 v71, v88
	v_mov_b32_e32 v72, v88
	v_mov_b32_e32 v73, v88
	v_mov_b32_e32 v74, v88
	v_mov_b32_e32 v75, v88
	v_mov_b32_e32 v76, v88
	v_mov_b32_e32 v77, v88
	v_mov_b32_e32 v78, v88
	v_mov_b32_e32 v79, v88
	v_mov_b32_e32 v80, v88
	v_mov_b32_e32 v81, v88
	v_mov_b32_e32 v82, v88
	v_mov_b32_e32 v83, v88
	v_mov_b32_e32 v84, v88
	v_mov_b32_e32 v85, v88
	v_mov_b32_e32 v86, v88
	v_mov_b32_e32 v87, v88
	v_mov_b32_e32 v92, v88
	v_mov_b32_e32 v93, v88
	v_mov_b32_e32 v94, v88
	v_mov_b32_e32 v95, v88
	v_mov_b32_e32 v96, v88
	v_mov_b32_e32 v97, v88
	v_mov_b32_e32 v98, v88
	v_mov_b32_e32 v99, v88
	v_mov_b32_e32 v100, v88
	v_mov_b32_e32 v101, v88
	v_mov_b32_e32 v102, v88
	v_mov_b32_e32 v103, v88
	v_mov_b32_e32 v104, v88
	v_mov_b32_e32 v105, v88
	v_mov_b32_e32 v106, v88
	v_mov_b32_e32 v107, v88
	v_mov_b32_e32 v108, v88
	v_mov_b32_e32 v109, v88
	v_mov_b32_e32 v110, v88
	v_mov_b32_e32 v111, v88
	v_mov_b32_e32 v112, v88
	v_mov_b32_e32 v113, v88
	v_mov_b32_e32 v114, v88
	v_mov_b32_e32 v115, v88
	v_mov_b32_e32 v116, v88
	v_mov_b32_e32 v117, v88
	v_mov_b32_e32 v118, v88
	v_mov_b32_e32 v119, v88
	v_mov_b32_e32 v120, v88
	v_mov_b32_e32 v121, v88
	v_mov_b32_e32 v122, v88
	v_mov_b32_e32 v123, v88
	v_mov_b32_e32 v124, v88
	v_mov_b32_e32 v125, v88
	v_mov_b32_e32 v126, v88
	v_mov_b32_e32 v127, v88
	s_waitcnt vmcnt(0) lgkmcnt(0)
	s_barrier
	s_bitcmp1_b32 s3, 12
	s_cbranch_scc1 .Lkb_500
.LBB0_500:
	s_add_i32 s9, s8, 0x10000
	s_and_b32 s26, s9, 0x10000
	s_add_i32 s36, s3, s26
	v_lshl_add_u64 v[136:137], v[130:131], 0, s[6:7]
	s_mov_b64 s[26:27], 0x59e0080
	v_lshl_add_u64 v[138:139], v[136:137], 0, s[26:27]
	s_mov_b32 m0, s36
	s_mov_b64 s[26:27], 0x5a38080
	global_load_lds_dwordx4 v[138:139], off
	v_lshl_add_u64 v[138:139], v[136:137], 0, s[26:27]
	s_add_i32 m0, s36, 0x2000
	s_mov_b64 s[26:27], 0x5a90080
	global_load_lds_dwordx4 v[138:139], off
	v_lshl_add_u64 v[138:139], v[136:137], 0, s[26:27]
	s_add_i32 m0, s36, 0x4000
	s_mov_b64 s[26:27], 0x5ae8080
	global_load_lds_dwordx4 v[138:139], off
	v_lshl_add_u64 v[136:137], v[136:137], 0, s[26:27]
	s_add_i32 m0, s36, 0x6000
	s_mov_b64 s[26:27], 0x58080
	global_load_lds_dwordx4 v[136:137], off
	v_lshl_add_u64 v[136:137], v[128:129], 0, s[6:7]
	v_lshl_add_u64 v[138:139], v[136:137], 0, s[10:11]
	s_add_i32 m0, s36, 0x8000
	s_nop 0
	global_load_lds_dwordx4 v[138:139], off
	v_lshl_add_u64 v[138:139], v[136:137], 0, s[26:27]
	s_add_i32 m0, s36, 0xa000
	s_mov_b64 s[26:27], 0xb0080
	global_load_lds_dwordx4 v[138:139], off
	v_lshl_add_u64 v[138:139], v[136:137], 0, s[26:27]
	s_add_i32 m0, s36, 0xc000
	s_mov_b64 s[26:27], 0x108080
	global_load_lds_dwordx4 v[138:139], off
	v_lshl_add_u64 v[136:137], v[136:137], 0, s[26:27]
	s_add_i32 m0, s36, 0xe000
	s_nop 0
	global_load_lds_dwordx4 v[136:137], off
	s_and_b32 s8, s8, 0x10000
	v_or_b32_e32 v144, s8, v135
	v_add_u32_e32 v151, v144, v134
	v_add_u32_e32 v144, v144, v132
	ds_read_b128 v[136:139], v151 offset:32768
	ds_read_b128 v[140:143], v151 offset:34816
	ds_read_b128 v[146:149], v151 offset:36864
	ds_read_b128 v[154:157], v151 offset:38912
	ds_read_b128 v[158:161], v144
	ds_read_b128 v[162:165], v144 offset:2048
	ds_read_b128 v[166:169], v144 offset:4096
	ds_read_b128 v[170:173], v144 offset:6144
	ds_read_b128 v[174:177], v144 offset:8192
	ds_read_b128 v[178:181], v144 offset:10240
	ds_read_b128 v[182:185], v144 offset:12288
	ds_read_b128 v[186:189], v144 offset:14336
	s_waitcnt lgkmcnt(0)
	v_mfma_f32_16x16x32_bf16 v[124:127], v[136:139], v[158:161], v[124:127]
	v_mfma_f32_16x16x32_bf16 v[120:123], v[140:143], v[158:161], v[120:123]
	v_mfma_f32_16x16x32_bf16 v[116:119], v[146:149], v[158:161], v[116:119]
	v_mfma_f32_16x16x32_bf16 v[112:115], v[154:157], v[158:161], v[112:115]
	v_mfma_f32_16x16x32_bf16 v[108:111], v[136:139], v[162:165], v[108:111]
	v_mfma_f32_16x16x32_bf16 v[104:107], v[140:143], v[162:165], v[104:107]
	v_mfma_f32_16x16x32_bf16 v[100:103], v[146:149], v[162:165], v[100:103]
	v_mfma_f32_16x16x32_bf16 v[96:99], v[154:157], v[162:165], v[96:99]
	v_mfma_f32_16x16x32_bf16 v[92:95], v[136:139], v[166:169], v[92:95]
	v_mfma_f32_16x16x32_bf16 v[84:87], v[140:143], v[166:169], v[84:87]
	v_mfma_f32_16x16x32_bf16 v[80:83], v[146:149], v[166:169], v[80:83]
	v_mfma_f32_16x16x32_bf16 v[76:79], v[154:157], v[166:169], v[76:79]
	v_mfma_f32_16x16x32_bf16 v[72:75], v[136:139], v[170:173], v[72:75]
	v_mfma_f32_16x16x32_bf16 v[68:71], v[140:143], v[170:173], v[68:71]
	v_mfma_f32_16x16x32_bf16 v[64:67], v[146:149], v[170:173], v[64:67]
	v_mfma_f32_16x16x32_bf16 v[60:63], v[154:157], v[170:173], v[60:63]
	v_or_b32_e32 v144, s8, v133
	v_add_u32_e32 v151, v144, v134
	v_add_u32_e32 v144, v144, v132
	ds_read_b128 v[158:161], v151 offset:32768
	ds_read_b128 v[162:165], v151 offset:34816
	ds_read_b128 v[166:169], v151 offset:36864
	ds_read_b128 v[170:173], v151 offset:38912
	ds_read_b128 v[206:209], v144
	ds_read_b128 v[216:219], v144 offset:2048
	ds_read_b128 v[220:223], v144 offset:4096
	ds_read_b128 v[224:227], v144 offset:6144
	v_mfma_f32_16x16x32_bf16 v[56:59], v[136:139], v[174:177], v[56:59]
	v_mfma_f32_16x16x32_bf16 v[52:55], v[140:143], v[174:177], v[52:55]
	v_mfma_f32_16x16x32_bf16 v[48:51], v[146:149], v[174:177], v[48:51]
	v_mfma_f32_16x16x32_bf16 v[44:47], v[154:157], v[174:177], v[44:47]
	v_mfma_f32_16x16x32_bf16 v[40:43], v[136:139], v[178:181], v[40:43]
	v_mfma_f32_16x16x32_bf16 v[36:39], v[140:143], v[178:181], v[36:39]
	v_mfma_f32_16x16x32_bf16 v[32:35], v[146:149], v[178:181], v[32:35]
	v_mfma_f32_16x16x32_bf16 v[28:31], v[154:157], v[178:181], v[28:31]
	v_mfma_f32_16x16x32_bf16 v[24:27], v[136:139], v[182:185], v[24:27]
	v_mfma_f32_16x16x32_bf16 v[20:23], v[140:143], v[182:185], v[20:23]
	v_mfma_f32_16x16x32_bf16 v[16:19], v[146:149], v[182:185], v[16:19]
	v_mfma_f32_16x16x32_bf16 v[12:15], v[154:157], v[182:185], v[12:15]
	v_mfma_f32_16x16x32_bf16 v[8:11], v[136:139], v[186:189], v[8:11]
	v_mfma_f32_16x16x32_bf16 v[4:7], v[140:143], v[186:189], v[4:7]
	v_mfma_f32_16x16x32_bf16 v[0:3], v[146:149], v[186:189], v[0:3]
	v_mfma_f32_16x16x32_bf16 v[88:91], v[154:157], v[186:189], v[88:91]
	ds_read_b128 v[136:139], v144 offset:8192
	ds_read_b128 v[140:143], v144 offset:10240
	ds_read_b128 v[146:149], v144 offset:12288
	ds_read_b128 v[154:157], v144 offset:14336
	s_waitcnt lgkmcnt(0)
	v_mfma_f32_16x16x32_bf16 v[124:127], v[158:161], v[206:209], v[124:127]
	v_mfma_f32_16x16x32_bf16 v[120:123], v[162:165], v[206:209], v[120:123]
	v_mfma_f32_16x16x32_bf16 v[116:119], v[166:169], v[206:209], v[116:119]
	v_mfma_f32_16x16x32_bf16 v[112:115], v[170:173], v[206:209], v[112:115]
	v_mfma_f32_16x16x32_bf16 v[108:111], v[158:161], v[216:219], v[108:111]
	v_mfma_f32_16x16x32_bf16 v[104:107], v[162:165], v[216:219], v[104:107]
	v_mfma_f32_16x16x32_bf16 v[100:103], v[166:169], v[216:219], v[100:103]
	v_mfma_f32_16x16x32_bf16 v[96:99], v[170:173], v[216:219], v[96:99]
	v_mfma_f32_16x16x32_bf16 v[92:95], v[158:161], v[220:223], v[92:95]
	v_mfma_f32_16x16x32_bf16 v[84:87], v[162:165], v[220:223], v[84:87]
	v_mfma_f32_16x16x32_bf16 v[80:83], v[166:169], v[220:223], v[80:83]
	v_mfma_f32_16x16x32_bf16 v[76:79], v[170:173], v[220:223], v[76:79]
	v_mfma_f32_16x16x32_bf16 v[72:75], v[158:161], v[224:227], v[72:75]
	v_mfma_f32_16x16x32_bf16 v[68:71], v[162:165], v[224:227], v[68:71]
	v_mfma_f32_16x16x32_bf16 v[64:67], v[166:169], v[224:227], v[64:67]
	v_mfma_f32_16x16x32_bf16 v[60:63], v[170:173], v[224:227], v[60:63]
	v_mfma_f32_16x16x32_bf16 v[56:59], v[158:161], v[136:139], v[56:59]
	s_waitcnt vmcnt(0)
	s_add_u32 s6, s6, 0x80
	s_addc_u32 s7, s7, 0
	v_mfma_f32_16x16x32_bf16 v[52:55], v[162:165], v[136:139], v[52:55]
	s_cmpk_eq_i32 s6, 0x1580
	s_mov_b32 s8, s9
	s_waitcnt vmcnt(0)
	v_mfma_f32_16x16x32_bf16 v[48:51], v[166:169], v[136:139], v[48:51]
	s_barrier
	v_mfma_f32_16x16x32_bf16 v[44:47], v[170:173], v[136:139], v[44:47]
	v_mfma_f32_16x16x32_bf16 v[40:43], v[158:161], v[140:143], v[40:43]
	v_mfma_f32_16x16x32_bf16 v[36:39], v[162:165], v[140:143], v[36:39]
	v_mfma_f32_16x16x32_bf16 v[32:35], v[166:169], v[140:143], v[32:35]
	v_mfma_f32_16x16x32_bf16 v[28:31], v[170:173], v[140:143], v[28:31]
	v_mfma_f32_16x16x32_bf16 v[24:27], v[158:161], v[146:149], v[24:27]
	v_mfma_f32_16x16x32_bf16 v[20:23], v[162:165], v[146:149], v[20:23]
	v_mfma_f32_16x16x32_bf16 v[16:19], v[166:169], v[146:149], v[16:19]
	v_mfma_f32_16x16x32_bf16 v[12:15], v[170:173], v[146:149], v[12:15]
	v_mfma_f32_16x16x32_bf16 v[8:11], v[158:161], v[154:157], v[8:11]
	v_mfma_f32_16x16x32_bf16 v[4:7], v[162:165], v[154:157], v[4:7]
	v_mfma_f32_16x16x32_bf16 v[0:3], v[166:169], v[154:157], v[0:3]
	v_mfma_f32_16x16x32_bf16 v[88:91], v[170:173], v[154:157], v[88:91]
	s_cbranch_scc0 .LBB0_500
	s_branch .Lkx_500
.Lkb_500:
	s_add_i32 s9, s8, 0x10000
	s_and_b32 s26, s9, 0x10000
	s_add_i32 s36, s3, s26
	s_and_b32 s8, s8, 0x10000
	v_or_b32_e32 v144, s8, v135
	v_add_u32_e32 v151, v144, v134
	v_add_u32_e32 v144, v144, v132
	ds_read_b128 v[136:139], v151 offset:32768
	ds_read_b128 v[140:143], v151 offset:34816
	ds_read_b128 v[146:149], v151 offset:36864
	ds_read_b128 v[154:157], v151 offset:38912
	ds_read_b128 v[158:161], v144
	ds_read_b128 v[162:165], v144 offset:2048
	ds_read_b128 v[166:169], v144 offset:4096
	ds_read_b128 v[170:173], v144 offset:6144
	ds_read_b128 v[174:177], v144 offset:8192
	ds_read_b128 v[178:181], v144 offset:10240
	ds_read_b128 v[182:185], v144 offset:12288
	ds_read_b128 v[186:189], v144 offset:14336
	s_waitcnt lgkmcnt(0)
	v_mfma_f32_16x16x32_bf16 v[124:127], v[136:139], v[158:161], v[124:127]
	v_mfma_f32_16x16x32_bf16 v[120:123], v[140:143], v[158:161], v[120:123]
	v_mfma_f32_16x16x32_bf16 v[116:119], v[146:149], v[158:161], v[116:119]
	v_mfma_f32_16x16x32_bf16 v[112:115], v[154:157], v[158:161], v[112:115]
	v_mfma_f32_16x16x32_bf16 v[108:111], v[136:139], v[162:165], v[108:111]
	v_mfma_f32_16x16x32_bf16 v[104:107], v[140:143], v[162:165], v[104:107]
	v_mfma_f32_16x16x32_bf16 v[100:103], v[146:149], v[162:165], v[100:103]
	v_mfma_f32_16x16x32_bf16 v[96:99], v[154:157], v[162:165], v[96:99]
	v_mfma_f32_16x16x32_bf16 v[92:95], v[136:139], v[166:169], v[92:95]
	v_mfma_f32_16x16x32_bf16 v[84:87], v[140:143], v[166:169], v[84:87]
	v_mfma_f32_16x16x32_bf16 v[80:83], v[146:149], v[166:169], v[80:83]
	v_mfma_f32_16x16x32_bf16 v[76:79], v[154:157], v[166:169], v[76:79]
	v_mfma_f32_16x16x32_bf16 v[72:75], v[136:139], v[170:173], v[72:75]
	v_mfma_f32_16x16x32_bf16 v[68:71], v[140:143], v[170:173], v[68:71]
	v_mfma_f32_16x16x32_bf16 v[64:67], v[146:149], v[170:173], v[64:67]
	v_mfma_f32_16x16x32_bf16 v[60:63], v[154:157], v[170:173], v[60:63]
	v_or_b32_e32 v144, s8, v133
	v_add_u32_e32 v151, v144, v134
	v_add_u32_e32 v144, v144, v132
	ds_read_b128 v[158:161], v151 offset:32768
	ds_read_b128 v[162:165], v151 offset:34816
	ds_read_b128 v[166:169], v151 offset:36864
	ds_read_b128 v[170:173], v151 offset:38912
	ds_read_b128 v[206:209], v144
	ds_read_b128 v[216:219], v144 offset:2048
	ds_read_b128 v[220:223], v144 offset:4096
	ds_read_b128 v[224:227], v144 offset:6144
	v_mfma_f32_16x16x32_bf16 v[56:59], v[136:139], v[174:177], v[56:59]
	v_mfma_f32_16x16x32_bf16 v[52:55], v[140:143], v[174:177], v[52:55]
	v_mfma_f32_16x16x32_bf16 v[48:51], v[146:149], v[174:177], v[48:51]
	v_mfma_f32_16x16x32_bf16 v[44:47], v[154:157], v[174:177], v[44:47]
	v_mfma_f32_16x16x32_bf16 v[40:43], v[136:139], v[178:181], v[40:43]
	v_mfma_f32_16x16x32_bf16 v[36:39], v[140:143], v[178:181], v[36:39]
	v_mfma_f32_16x16x32_bf16 v[32:35], v[146:149], v[178:181], v[32:35]
	v_mfma_f32_16x16x32_bf16 v[28:31], v[154:157], v[178:181], v[28:31]
	v_mfma_f32_16x16x32_bf16 v[24:27], v[136:139], v[182:185], v[24:27]
	v_mfma_f32_16x16x32_bf16 v[20:23], v[140:143], v[182:185], v[20:23]
	v_mfma_f32_16x16x32_bf16 v[16:19], v[146:149], v[182:185], v[16:19]
	v_mfma_f32_16x16x32_bf16 v[12:15], v[154:157], v[182:185], v[12:15]
	v_mfma_f32_16x16x32_bf16 v[8:11], v[136:139], v[186:189], v[8:11]
	v_mfma_f32_16x16x32_bf16 v[4:7], v[140:143], v[186:189], v[4:7]
	v_mfma_f32_16x16x32_bf16 v[0:3], v[146:149], v[186:189], v[0:3]
	v_mfma_f32_16x16x32_bf16 v[88:91], v[154:157], v[186:189], v[88:91]
	v_lshl_add_u64 v[244:245], v[130:131], 0, s[6:7]
	s_mov_b64 s[26:27], 0x59e0080
	v_lshl_add_u64 v[246:247], v[244:245], 0, s[26:27]
	s_mov_b32 m0, s36
	s_mov_b64 s[26:27], 0x5a38080
	global_load_lds_dwordx4 v[246:247], off
	v_lshl_add_u64 v[246:247], v[244:245], 0, s[26:27]
	s_add_i32 m0, s36, 0x2000
	s_mov_b64 s[26:27], 0x5a90080
	global_load_lds_dwordx4 v[246:247], off
	v_lshl_add_u64 v[246:247], v[244:245], 0, s[26:27]
	s_add_i32 m0, s36, 0x4000
	s_mov_b64 s[26:27], 0x5ae8080
	global_load_lds_dwordx4 v[246:247], off
	v_lshl_add_u64 v[244:245], v[244:245], 0, s[26:27]
	s_add_i32 m0, s36, 0x6000
	s_mov_b64 s[26:27], 0x58080
	global_load_lds_dwordx4 v[244:245], off
	v_lshl_add_u64 v[244:245], v[128:129], 0, s[6:7]
	v_lshl_add_u64 v[246:247], v[244:245], 0, s[10:11]
	s_add_i32 m0, s36, 0x8000
	s_nop 0
	global_load_lds_dwordx4 v[246:247], off
	v_lshl_add_u64 v[246:247], v[244:245], 0, s[26:27]
	s_add_i32 m0, s36, 0xa000
	s_mov_b64 s[26:27], 0xb0080
	global_load_lds_dwordx4 v[246:247], off
	v_lshl_add_u64 v[246:247], v[244:245], 0, s[26:27]
	s_add_i32 m0, s36, 0xc000
	s_mov_b64 s[26:27], 0x108080
	global_load_lds_dwordx4 v[246:247], off
	v_lshl_add_u64 v[244:245], v[244:245], 0, s[26:27]
	s_add_i32 m0, s36, 0xe000
	s_nop 0
	global_load_lds_dwordx4 v[244:245], off
	ds_read_b128 v[136:139], v144 offset:8192
	ds_read_b128 v[140:143], v144 offset:10240
	ds_read_b128 v[146:149], v144 offset:12288
	ds_read_b128 v[154:157], v144 offset:14336
	s_waitcnt lgkmcnt(0)
	v_mfma_f32_16x16x32_bf16 v[124:127], v[158:161], v[206:209], v[124:127]
	v_mfma_f32_16x16x32_bf16 v[120:123], v[162:165], v[206:209], v[120:123]
	v_mfma_f32_16x16x32_bf16 v[116:119], v[166:169], v[206:209], v[116:119]
	v_mfma_f32_16x16x32_bf16 v[112:115], v[170:173], v[206:209], v[112:115]
	v_mfma_f32_16x16x32_bf16 v[108:111], v[158:161], v[216:219], v[108:111]
	v_mfma_f32_16x16x32_bf16 v[104:107], v[162:165], v[216:219], v[104:107]
	v_mfma_f32_16x16x32_bf16 v[100:103], v[166:169], v[216:219], v[100:103]
	v_mfma_f32_16x16x32_bf16 v[96:99], v[170:173], v[216:219], v[96:99]
	v_mfma_f32_16x16x32_bf16 v[92:95], v[158:161], v[220:223], v[92:95]
	v_mfma_f32_16x16x32_bf16 v[84:87], v[162:165], v[220:223], v[84:87]
	v_mfma_f32_16x16x32_bf16 v[80:83], v[166:169], v[220:223], v[80:83]
	v_mfma_f32_16x16x32_bf16 v[76:79], v[170:173], v[220:223], v[76:79]
	v_mfma_f32_16x16x32_bf16 v[72:75], v[158:161], v[224:227], v[72:75]
	v_mfma_f32_16x16x32_bf16 v[68:71], v[162:165], v[224:227], v[68:71]
	v_mfma_f32_16x16x32_bf16 v[64:67], v[166:169], v[224:227], v[64:67]
	v_mfma_f32_16x16x32_bf16 v[60:63], v[170:173], v[224:227], v[60:63]
	v_mfma_f32_16x16x32_bf16 v[56:59], v[158:161], v[136:139], v[56:59]
	s_add_u32 s6, s6, 0x80
	s_addc_u32 s7, s7, 0
	v_mfma_f32_16x16x32_bf16 v[52:55], v[162:165], v[136:139], v[52:55]
	s_cmpk_eq_i32 s6, 0x1580
	s_mov_b32 s8, s9
	s_waitcnt vmcnt(0)
	v_mfma_f32_16x16x32_bf16 v[48:51], v[166:169], v[136:139], v[48:51]
	s_barrier
	v_mfma_f32_16x16x32_bf16 v[44:47], v[170:173], v[136:139], v[44:47]
	v_mfma_f32_16x16x32_bf16 v[40:43], v[158:161], v[140:143], v[40:43]
	v_mfma_f32_16x16x32_bf16 v[36:39], v[162:165], v[140:143], v[36:39]
	v_mfma_f32_16x16x32_bf16 v[32:35], v[166:169], v[140:143], v[32:35]
	v_mfma_f32_16x16x32_bf16 v[28:31], v[170:173], v[140:143], v[28:31]
	v_mfma_f32_16x16x32_bf16 v[24:27], v[158:161], v[146:149], v[24:27]
	v_mfma_f32_16x16x32_bf16 v[20:23], v[162:165], v[146:149], v[20:23]
	v_mfma_f32_16x16x32_bf16 v[16:19], v[166:169], v[146:149], v[16:19]
	v_mfma_f32_16x16x32_bf16 v[12:15], v[170:173], v[146:149], v[12:15]
	v_mfma_f32_16x16x32_bf16 v[8:11], v[158:161], v[154:157], v[8:11]
	v_mfma_f32_16x16x32_bf16 v[4:7], v[162:165], v[154:157], v[4:7]
	v_mfma_f32_16x16x32_bf16 v[0:3], v[166:169], v[154:157], v[0:3]
	v_mfma_f32_16x16x32_bf16 v[88:91], v[170:173], v[154:157], v[88:91]
	s_cbranch_scc0 .Lkb_500
.Lkx_500:
	v_add3_u32 v144, v134, v135, s52
	v_add3_u32 v135, v132, v135, s81
	ds_read_b128 v[128:131], v144
	ds_read_b128 v[136:139], v144 offset:2048
	ds_read_b128 v[140:143], v144 offset:4096
	ds_read_b128 v[146:149], v144 offset:6144
	ds_read_b128 v[154:157], v135
	ds_read_b128 v[158:161], v135 offset:2048
	ds_read_b128 v[162:165], v135 offset:4096
	ds_read_b128 v[166:169], v135 offset:6144
	ds_read_b128 v[170:173], v135 offset:8192
	ds_read_b128 v[174:177], v135 offset:10240
	ds_read_b128 v[178:181], v135 offset:12288
	ds_read_b128 v[182:185], v135 offset:14336
	s_waitcnt lgkmcnt(7)
	v_mfma_f32_16x16x32_bf16 v[124:127], v[128:131], v[154:157], v[124:127]
	v_mfma_f32_16x16x32_bf16 v[116:119], v[140:143], v[154:157], v[116:119]
	v_mfma_f32_16x16x32_bf16 v[112:115], v[146:149], v[154:157], v[112:115]
	s_waitcnt lgkmcnt(6)
	v_mfma_f32_16x16x32_bf16 v[108:111], v[128:131], v[158:161], v[108:111]
	v_mfma_f32_16x16x32_bf16 v[104:107], v[136:139], v[158:161], v[104:107]
	v_mfma_f32_16x16x32_bf16 v[100:103], v[140:143], v[158:161], v[100:103]
	v_mfma_f32_16x16x32_bf16 v[96:99], v[146:149], v[158:161], v[96:99]
	s_waitcnt lgkmcnt(5)
	v_mfma_f32_16x16x32_bf16 v[92:95], v[128:131], v[162:165], v[92:95]
	v_mfma_f32_16x16x32_bf16 v[84:87], v[136:139], v[162:165], v[84:87]
	v_mfma_f32_16x16x32_bf16 v[80:83], v[140:143], v[162:165], v[80:83]
	v_mfma_f32_16x16x32_bf16 v[76:79], v[146:149], v[162:165], v[76:79]
	s_waitcnt lgkmcnt(4)
	v_mfma_f32_16x16x32_bf16 v[72:75], v[128:131], v[166:169], v[72:75]
	v_mfma_f32_16x16x32_bf16 v[68:71], v[136:139], v[166:169], v[68:71]
	v_mfma_f32_16x16x32_bf16 v[64:67], v[140:143], v[166:169], v[64:67]
	v_mfma_f32_16x16x32_bf16 v[60:63], v[146:149], v[166:169], v[60:63]
	v_mfma_f32_16x16x32_bf16 v[186:189], v[136:139], v[154:157], v[120:123]
	s_nop 2
	v_add3_u32 v120, v134, v133, s52
	ds_read_b128 v[154:157], v120
	ds_read_b128 v[158:161], v120 offset:2048
	ds_read_b128 v[162:165], v120 offset:4096
	ds_read_b128 v[166:169], v120 offset:6144
	v_add3_u32 v120, v132, v133, s81
	ds_read_b128 v[132:135], v120
	ds_read_b128 v[206:209], v120 offset:2048
	ds_read_b128 v[216:219], v120 offset:4096
	ds_read_b128 v[220:223], v120 offset:6144
	s_waitcnt lgkmcnt(11)
	v_mfma_f32_16x16x32_bf16 v[56:59], v[128:131], v[170:173], v[56:59]
	v_mfma_f32_16x16x32_bf16 v[52:55], v[136:139], v[170:173], v[52:55]
	v_mfma_f32_16x16x32_bf16 v[48:51], v[140:143], v[170:173], v[48:51]
	v_mfma_f32_16x16x32_bf16 v[44:47], v[146:149], v[170:173], v[44:47]
	s_waitcnt lgkmcnt(10)
	v_mfma_f32_16x16x32_bf16 v[40:43], v[128:131], v[174:177], v[40:43]
	v_mfma_f32_16x16x32_bf16 v[36:39], v[136:139], v[174:177], v[36:39]
	v_mfma_f32_16x16x32_bf16 v[32:35], v[140:143], v[174:177], v[32:35]
	v_mfma_f32_16x16x32_bf16 v[28:31], v[146:149], v[174:177], v[28:31]
	s_waitcnt lgkmcnt(9)
	v_mfma_f32_16x16x32_bf16 v[24:27], v[128:131], v[178:181], v[24:27]
	v_mfma_f32_16x16x32_bf16 v[20:23], v[136:139], v[178:181], v[20:23]
	v_mfma_f32_16x16x32_bf16 v[16:19], v[140:143], v[178:181], v[16:19]
	v_mfma_f32_16x16x32_bf16 v[12:15], v[146:149], v[178:181], v[12:15]
	s_waitcnt lgkmcnt(8)
	v_mfma_f32_16x16x32_bf16 v[8:11], v[128:131], v[182:185], v[8:11]
	v_mfma_f32_16x16x32_bf16 v[4:7], v[136:139], v[182:185], v[4:7]
	v_mfma_f32_16x16x32_bf16 v[0:3], v[140:143], v[182:185], v[0:3]
	v_mfma_f32_16x16x32_bf16 v[128:131], v[146:149], v[182:185], v[88:91]
	ds_read_b128 v[136:139], v120 offset:8192
	ds_read_b128 v[140:143], v120 offset:10240
	ds_read_b128 v[146:149], v120 offset:12288
	ds_read_b128 v[170:173], v120 offset:14336
	s_waitcnt lgkmcnt(7)
	v_mfma_f32_16x16x32_bf16 v[120:123], v[154:157], v[132:135], v[124:127]
	v_mfma_f32_16x16x32_bf16 v[124:127], v[158:161], v[132:135], v[186:189]
	v_mfma_f32_16x16x32_bf16 v[116:119], v[162:165], v[132:135], v[116:119]
	v_mfma_f32_16x16x32_bf16 v[112:115], v[166:169], v[132:135], v[112:115]
	s_waitcnt lgkmcnt(6)
	v_mfma_f32_16x16x32_bf16 v[108:111], v[154:157], v[206:209], v[108:111]
	v_mfma_f32_16x16x32_bf16 v[104:107], v[158:161], v[206:209], v[104:107]
	v_mfma_f32_16x16x32_bf16 v[100:103], v[162:165], v[206:209], v[100:103]
	v_mfma_f32_16x16x32_bf16 v[96:99], v[166:169], v[206:209], v[96:99]
	s_waitcnt lgkmcnt(5)
	v_mfma_f32_16x16x32_bf16 v[92:95], v[154:157], v[216:219], v[92:95]
	v_mfma_f32_16x16x32_bf16 v[88:91], v[158:161], v[216:219], v[84:87]
	v_mfma_f32_16x16x32_bf16 v[84:87], v[162:165], v[216:219], v[80:83]
	v_mfma_f32_16x16x32_bf16 v[80:83], v[166:169], v[216:219], v[76:79]
	s_waitcnt lgkmcnt(4)
	v_mfma_f32_16x16x32_bf16 v[76:79], v[154:157], v[220:223], v[72:75]
	v_mfma_f32_16x16x32_bf16 v[72:75], v[158:161], v[220:223], v[68:71]
	v_mfma_f32_16x16x32_bf16 v[68:71], v[162:165], v[220:223], v[64:67]
	v_mfma_f32_16x16x32_bf16 v[64:67], v[166:169], v[220:223], v[60:63]
	s_waitcnt lgkmcnt(3)
	v_mfma_f32_16x16x32_bf16 v[60:63], v[154:157], v[136:139], v[56:59]
	s_and_b64 vcc, exec, s[22:23]
	s_mov_b64 s[26:27], s[90:91]
	v_mfma_f32_16x16x32_bf16 v[56:59], v[158:161], v[136:139], v[52:55]
	v_mfma_f32_16x16x32_bf16 v[52:55], v[162:165], v[136:139], v[48:51]
	v_mfma_f32_16x16x32_bf16 v[48:51], v[166:169], v[136:139], v[44:47]
	s_waitcnt lgkmcnt(2)
	v_mfma_f32_16x16x32_bf16 v[44:47], v[154:157], v[140:143], v[40:43]
	v_mfma_f32_16x16x32_bf16 v[40:43], v[158:161], v[140:143], v[36:39]
	v_mfma_f32_16x16x32_bf16 v[36:39], v[162:165], v[140:143], v[32:35]
	v_mfma_f32_16x16x32_bf16 v[32:35], v[166:169], v[140:143], v[28:31]
	s_waitcnt lgkmcnt(1)
	v_mfma_f32_16x16x32_bf16 v[28:31], v[154:157], v[146:149], v[24:27]
	v_mfma_f32_16x16x32_bf16 v[24:27], v[158:161], v[146:149], v[20:23]
	v_mfma_f32_16x16x32_bf16 v[20:23], v[162:165], v[146:149], v[16:19]
	v_mfma_f32_16x16x32_bf16 v[16:19], v[166:169], v[146:149], v[12:15]
	s_waitcnt lgkmcnt(0)
	v_mfma_f32_16x16x32_bf16 v[12:15], v[154:157], v[170:173], v[8:11]
	v_mfma_f32_16x16x32_bf16 v[8:11], v[158:161], v[170:173], v[4:7]
	v_mfma_f32_16x16x32_bf16 v[4:7], v[162:165], v[170:173], v[0:3]
	v_mfma_f32_16x16x32_bf16 v[0:3], v[166:169], v[170:173], v[128:131]
	s_cbranch_vccz .LBB0_503
	v_readlane_b32 s36, v255, 27
	v_readlane_b32 s37, v255, 28
	s_mov_b64 s[26:27], s[36:37]
	v_readlane_b32 s38, v255, 29
	v_readlane_b32 s39, v255, 30
	v_readlane_b32 s40, v255, 31
	v_readlane_b32 s41, v255, 32
	v_readlane_b32 s42, v255, 33
	v_readlane_b32 s43, v255, 34
	v_readlane_b32 s44, v255, 35
	v_readlane_b32 s45, v255, 36
	v_readlane_b32 s46, v255, 37
	v_readlane_b32 s47, v255, 38
	v_readlane_b32 s48, v255, 39
	v_readlane_b32 s49, v255, 40
	v_readlane_b32 s50, v255, 41
	v_readlane_b32 s51, v255, 42

.LBB0_669:
	v_lshlrev_b64 v[132:133], 10, v[0:1]
	v_and_b32_e32 v0, 15, v2
	v_and_b32_e32 v1, 3, v3
	v_lshrrev_b32_e32 v3, 1, v2
	s_mov_b32 s2, 0x1ffff80
	v_and_or_b32 v0, v3, s2, v0
	v_lshlrev_b32_e32 v134, 7, v0
	v_bfe_u32 v0, v2, 1, 3
	v_bitop3_b32 v0, v1, v0, 4 bitop3:0x36
	v_lshlrev_b32_e32 v135, 4, v0
	v_lshlrev_b32_e32 v0, 7, v2
	s_waitcnt vmcnt(0)
	v_bitop3_b32 v3, v3, v1, 7 bitop3:0x6c
	v_and_b32_e32 v136, 0x6780, v0
	v_mov_b32_e32 v0, 0
	v_lshlrev_b32_e32 v137, 4, v3
	s_mov_b64 s[34:35], 0
	s_mov_b32 s2, 0
	v_mov_b32_e32 v1, v0
	v_mov_b32_e32 v2, v0
	v_mov_b32_e32 v3, v0
	v_mov_b32_e32 v4, v0
	v_mov_b32_e32 v5, v0
	v_mov_b32_e32 v6, v0
	v_mov_b32_e32 v7, v0
	v_mov_b32_e32 v8, v0
	v_mov_b32_e32 v9, v0
	v_mov_b32_e32 v10, v0
	v_mov_b32_e32 v11, v0
	v_mov_b32_e32 v12, v0
	v_mov_b32_e32 v13, v0
	v_mov_b32_e32 v14, v0
	v_mov_b32_e32 v15, v0
	v_mov_b32_e32 v16, v0
	v_mov_b32_e32 v17, v0
	v_mov_b32_e32 v18, v0
	v_mov_b32_e32 v19, v0
	v_mov_b32_e32 v20, v0
	v_mov_b32_e32 v21, v0
	v_mov_b32_e32 v22, v0
	v_mov_b32_e32 v23, v0
	v_mov_b32_e32 v24, v0
	v_mov_b32_e32 v25, v0
	v_mov_b32_e32 v26, v0
	v_mov_b32_e32 v27, v0
	v_mov_b32_e32 v28, v0
	v_mov_b32_e32 v29, v0
	v_mov_b32_e32 v30, v0
	v_mov_b32_e32 v31, v0
	v_mov_b32_e32 v32, v0
	v_mov_b32_e32 v33, v0
	v_mov_b32_e32 v34, v0
	v_mov_b32_e32 v35, v0
	v_mov_b32_e32 v36, v0
	v_mov_b32_e32 v37, v0
	v_mov_b32_e32 v38, v0
	v_mov_b32_e32 v39, v0
	v_mov_b32_e32 v44, v0
	v_mov_b32_e32 v45, v0
	v_mov_b32_e32 v46, v0
	v_mov_b32_e32 v47, v0
	v_mov_b32_e32 v56, v0
	v_mov_b32_e32 v57, v0
	v_mov_b32_e32 v58, v0
	v_mov_b32_e32 v59, v0
	v_mov_b32_e32 v68, v0
	v_mov_b32_e32 v69, v0
	v_mov_b32_e32 v70, v0
	v_mov_b32_e32 v71, v0
	v_mov_b32_e32 v76, v0
	v_mov_b32_e32 v77, v0
	v_mov_b32_e32 v78, v0
	v_mov_b32_e32 v79, v0
	v_mov_b32_e32 v88, v0
	v_mov_b32_e32 v89, v0
	v_mov_b32_e32 v90, v0
	v_mov_b32_e32 v91, v0
	v_mov_b32_e32 v100, v0
	v_mov_b32_e32 v101, v0
	v_mov_b32_e32 v102, v0
	v_mov_b32_e32 v103, v0
	v_mov_b32_e32 v108, v0
	v_mov_b32_e32 v109, v0
	v_mov_b32_e32 v110, v0
	v_mov_b32_e32 v111, v0
	v_mov_b32_e32 v116, v0
	v_mov_b32_e32 v117, v0
	v_mov_b32_e32 v118, v0
	v_mov_b32_e32 v119, v0
	v_mov_b32_e32 v40, v0
	v_mov_b32_e32 v41, v0
	v_mov_b32_e32 v42, v0
	v_mov_b32_e32 v43, v0
	v_mov_b32_e32 v48, v0
	v_mov_b32_e32 v49, v0
	v_mov_b32_e32 v50, v0
	v_mov_b32_e32 v51, v0
	v_mov_b32_e32 v52, v0
	v_mov_b32_e32 v53, v0
	v_mov_b32_e32 v54, v0
	v_mov_b32_e32 v55, v0
	v_mov_b32_e32 v60, v0
	v_mov_b32_e32 v61, v0
	v_mov_b32_e32 v62, v0
	v_mov_b32_e32 v63, v0
	v_mov_b32_e32 v64, v0
	v_mov_b32_e32 v65, v0
	v_mov_b32_e32 v66, v0
	v_mov_b32_e32 v67, v0
	v_mov_b32_e32 v72, v0
	v_mov_b32_e32 v73, v0
	v_mov_b32_e32 v74, v0
	v_mov_b32_e32 v75, v0
	v_mov_b32_e32 v80, v0
	v_mov_b32_e32 v81, v0
	v_mov_b32_e32 v82, v0
	v_mov_b32_e32 v83, v0
	v_mov_b32_e32 v84, v0
	v_mov_b32_e32 v85, v0
	v_mov_b32_e32 v86, v0
	v_mov_b32_e32 v87, v0
	v_mov_b32_e32 v92, v0
	v_mov_b32_e32 v93, v0
	v_mov_b32_e32 v94, v0
	v_mov_b32_e32 v95, v0
	v_mov_b32_e32 v96, v0
	v_mov_b32_e32 v97, v0
	v_mov_b32_e32 v98, v0
	v_mov_b32_e32 v99, v0
	v_mov_b32_e32 v104, v0
	v_mov_b32_e32 v105, v0
	v_mov_b32_e32 v106, v0
	v_mov_b32_e32 v107, v0
	v_mov_b32_e32 v112, v0
	v_mov_b32_e32 v113, v0
	v_mov_b32_e32 v114, v0
	v_mov_b32_e32 v115, v0
	v_mov_b32_e32 v120, v0
	v_mov_b32_e32 v121, v0
	v_mov_b32_e32 v122, v0
	v_mov_b32_e32 v123, v0
	v_mov_b32_e32 v124, v0
	v_mov_b32_e32 v125, v0
	v_mov_b32_e32 v126, v0
	v_mov_b32_e32 v127, v0
	s_waitcnt vmcnt(0) lgkmcnt(0)
	s_barrier
	s_bitcmp1_b32 s0, 12
	s_cbranch_scc1 .Lkb_670
.LBB0_670:
	s_add_i32 s3, s2, 0x10000
	s_and_b32 s23, s3, 0x10000
	s_add_i32 s23, s0, s23
	v_lshl_add_u64 v[138:139], v[128:129], 0, s[34:35]
	v_lshl_add_u64 v[140:141], v[138:139], 0, s[10:11]
	s_mov_b32 m0, s23
	s_nop 0
	global_load_lds_dwordx4 v[140:141], off
	v_lshl_add_u64 v[140:141], v[138:139], 0, s[4:5]
	s_add_i32 m0, s23, 0x2000
	s_nop 0
	global_load_lds_dwordx4 v[140:141], off
	v_lshl_add_u64 v[140:141], v[138:139], 0, s[92:93]
	s_add_i32 m0, s23, 0x4000
	v_lshl_add_u64 v[138:139], v[138:139], 0, s[94:95]
	global_load_lds_dwordx4 v[140:141], off
	s_add_i32 m0, s23, 0x6000
	s_nop 0
	global_load_lds_dwordx4 v[138:139], off
	v_lshl_add_u64 v[138:139], v[130:131], 0, s[34:35]
	v_lshl_add_u64 v[140:141], v[138:139], 0, s[10:11]
	s_add_i32 m0, s23, 0x8000
	s_nop 0
	global_load_lds_dwordx4 v[140:141], off
	v_lshl_add_u64 v[140:141], v[138:139], 0, s[4:5]
	s_add_i32 m0, s23, 0xa000
	s_nop 0
	global_load_lds_dwordx4 v[140:141], off
	v_lshl_add_u64 v[140:141], v[138:139], 0, s[92:93]
	s_add_i32 m0, s23, 0xc000
	v_lshl_add_u64 v[138:139], v[138:139], 0, s[94:95]
	global_load_lds_dwordx4 v[140:141], off
	s_add_i32 m0, s23, 0xe000
	s_nop 0
	global_load_lds_dwordx4 v[138:139], off
	s_and_b32 s2, s2, 0x10000
	v_or_b32_e32 v142, s2, v137
	v_add_u32_e32 v143, v142, v136
	v_add_u32_e32 v142, v142, v134
	ds_read_b128 v[138:141], v143 offset:32768
	ds_read_b128 v[146:149], v143 offset:34816
	ds_read_b128 v[154:157], v143 offset:36864
	ds_read_b128 v[158:161], v143 offset:38912
	ds_read_b128 v[162:165], v142
	ds_read_b128 v[166:169], v142 offset:2048
	ds_read_b128 v[170:173], v142 offset:4096
	ds_read_b128 v[174:177], v142 offset:6144
	ds_read_b128 v[178:181], v142 offset:8192
	ds_read_b128 v[182:185], v142 offset:10240
	ds_read_b128 v[186:189], v142 offset:12288
	ds_read_b128 v[206:209], v142 offset:14336
	s_waitcnt lgkmcnt(0)
	v_mfma_f32_16x16x32_bf16 v[116:119], v[138:141], v[162:165], v[116:119]
	v_mfma_f32_16x16x32_bf16 v[108:111], v[146:149], v[162:165], v[108:111]
	v_mfma_f32_16x16x32_bf16 v[100:103], v[154:157], v[162:165], v[100:103]
	v_mfma_f32_16x16x32_bf16 v[88:91], v[158:161], v[162:165], v[88:91]
	v_mfma_f32_16x16x32_bf16 v[76:79], v[138:141], v[166:169], v[76:79]
	v_mfma_f32_16x16x32_bf16 v[68:71], v[146:149], v[166:169], v[68:71]
	v_mfma_f32_16x16x32_bf16 v[56:59], v[154:157], v[166:169], v[56:59]
	v_mfma_f32_16x16x32_bf16 v[44:47], v[158:161], v[166:169], v[44:47]
	v_mfma_f32_16x16x32_bf16 v[36:39], v[138:141], v[170:173], v[36:39]
	v_mfma_f32_16x16x32_bf16 v[32:35], v[146:149], v[170:173], v[32:35]
	v_mfma_f32_16x16x32_bf16 v[28:31], v[154:157], v[170:173], v[28:31]
	v_mfma_f32_16x16x32_bf16 v[24:27], v[158:161], v[170:173], v[24:27]
	v_mfma_f32_16x16x32_bf16 v[20:23], v[138:141], v[174:177], v[20:23]
	v_mfma_f32_16x16x32_bf16 v[16:19], v[146:149], v[174:177], v[16:19]
	v_mfma_f32_16x16x32_bf16 v[12:15], v[154:157], v[174:177], v[12:15]
	v_mfma_f32_16x16x32_bf16 v[8:11], v[158:161], v[174:177], v[8:11]
	v_or_b32_e32 v142, s2, v135
	v_add_u32_e32 v143, v142, v136
	v_add_u32_e32 v142, v142, v134
	ds_read_b128 v[162:165], v143 offset:32768
	ds_read_b128 v[166:169], v143 offset:34816
	ds_read_b128 v[170:173], v143 offset:36864
	ds_read_b128 v[174:177], v143 offset:38912
	ds_read_b128 v[216:219], v142
	ds_read_b128 v[220:223], v142 offset:2048
	ds_read_b128 v[224:227], v142 offset:4096
	ds_read_b128 v[228:231], v142 offset:6144
	v_mfma_f32_16x16x32_bf16 v[4:7], v[138:141], v[178:181], v[4:7]
	v_mfma_f32_16x16x32_bf16 v[0:3], v[146:149], v[178:181], v[0:3]
	v_mfma_f32_16x16x32_bf16 v[40:43], v[154:157], v[178:181], v[40:43]
	v_mfma_f32_16x16x32_bf16 v[48:51], v[158:161], v[178:181], v[48:51]
	v_mfma_f32_16x16x32_bf16 v[52:55], v[138:141], v[182:185], v[52:55]
	v_mfma_f32_16x16x32_bf16 v[60:63], v[146:149], v[182:185], v[60:63]
	v_mfma_f32_16x16x32_bf16 v[64:67], v[154:157], v[182:185], v[64:67]
	v_mfma_f32_16x16x32_bf16 v[72:75], v[158:161], v[182:185], v[72:75]
	v_mfma_f32_16x16x32_bf16 v[80:83], v[138:141], v[186:189], v[80:83]
	v_mfma_f32_16x16x32_bf16 v[84:87], v[146:149], v[186:189], v[84:87]
	v_mfma_f32_16x16x32_bf16 v[92:95], v[154:157], v[186:189], v[92:95]
	v_mfma_f32_16x16x32_bf16 v[96:99], v[158:161], v[186:189], v[96:99]
	v_mfma_f32_16x16x32_bf16 v[104:107], v[138:141], v[206:209], v[104:107]
	v_mfma_f32_16x16x32_bf16 v[112:115], v[146:149], v[206:209], v[112:115]
	v_mfma_f32_16x16x32_bf16 v[120:123], v[154:157], v[206:209], v[120:123]
	v_mfma_f32_16x16x32_bf16 v[124:127], v[158:161], v[206:209], v[124:127]
	ds_read_b128 v[138:141], v142 offset:8192
	ds_read_b128 v[146:149], v142 offset:10240
	ds_read_b128 v[154:157], v142 offset:12288
	ds_read_b128 v[158:161], v142 offset:14336
	s_waitcnt lgkmcnt(0)
	v_mfma_f32_16x16x32_bf16 v[116:119], v[162:165], v[216:219], v[116:119]
	v_mfma_f32_16x16x32_bf16 v[108:111], v[166:169], v[216:219], v[108:111]
	v_mfma_f32_16x16x32_bf16 v[100:103], v[170:173], v[216:219], v[100:103]
	v_mfma_f32_16x16x32_bf16 v[88:91], v[174:177], v[216:219], v[88:91]
	v_mfma_f32_16x16x32_bf16 v[76:79], v[162:165], v[220:223], v[76:79]
	v_mfma_f32_16x16x32_bf16 v[68:71], v[166:169], v[220:223], v[68:71]
	v_mfma_f32_16x16x32_bf16 v[56:59], v[170:173], v[220:223], v[56:59]
	v_mfma_f32_16x16x32_bf16 v[44:47], v[174:177], v[220:223], v[44:47]
	v_mfma_f32_16x16x32_bf16 v[36:39], v[162:165], v[224:227], v[36:39]
	v_mfma_f32_16x16x32_bf16 v[32:35], v[166:169], v[224:227], v[32:35]
	v_mfma_f32_16x16x32_bf16 v[28:31], v[170:173], v[224:227], v[28:31]
	v_mfma_f32_16x16x32_bf16 v[24:27], v[174:177], v[224:227], v[24:27]
	v_mfma_f32_16x16x32_bf16 v[20:23], v[162:165], v[228:231], v[20:23]
	v_mfma_f32_16x16x32_bf16 v[16:19], v[166:169], v[228:231], v[16:19]
	v_mfma_f32_16x16x32_bf16 v[12:15], v[170:173], v[228:231], v[12:15]
	v_mfma_f32_16x16x32_bf16 v[8:11], v[174:177], v[228:231], v[8:11]
	v_mfma_f32_16x16x32_bf16 v[4:7], v[162:165], v[138:141], v[4:7]
	s_waitcnt vmcnt(0)
	s_add_u32 s34, s34, 0x80
	s_addc_u32 s35, s35, 0
	v_mfma_f32_16x16x32_bf16 v[0:3], v[166:169], v[138:141], v[0:3]
	s_cmpk_eq_i32 s34, 0x780
	s_mov_b32 s2, s3
	s_waitcnt vmcnt(0)
	v_mfma_f32_16x16x32_bf16 v[40:43], v[170:173], v[138:141], v[40:43]
	s_barrier
	v_mfma_f32_16x16x32_bf16 v[48:51], v[174:177], v[138:141], v[48:51]
	v_mfma_f32_16x16x32_bf16 v[52:55], v[162:165], v[146:149], v[52:55]
	v_mfma_f32_16x16x32_bf16 v[60:63], v[166:169], v[146:149], v[60:63]
	v_mfma_f32_16x16x32_bf16 v[64:67], v[170:173], v[146:149], v[64:67]
	v_mfma_f32_16x16x32_bf16 v[72:75], v[174:177], v[146:149], v[72:75]
	v_mfma_f32_16x16x32_bf16 v[80:83], v[162:165], v[154:157], v[80:83]
	v_mfma_f32_16x16x32_bf16 v[84:87], v[166:169], v[154:157], v[84:87]
	v_mfma_f32_16x16x32_bf16 v[92:95], v[170:173], v[154:157], v[92:95]
	v_mfma_f32_16x16x32_bf16 v[96:99], v[174:177], v[154:157], v[96:99]
	v_mfma_f32_16x16x32_bf16 v[104:107], v[162:165], v[158:161], v[104:107]
	v_mfma_f32_16x16x32_bf16 v[112:115], v[166:169], v[158:161], v[112:115]
	v_mfma_f32_16x16x32_bf16 v[120:123], v[170:173], v[158:161], v[120:123]
	v_mfma_f32_16x16x32_bf16 v[124:127], v[174:177], v[158:161], v[124:127]
	s_cbranch_scc0 .LBB0_670
	s_branch .Lkx_670
.Lkb_670:
	s_add_i32 s3, s2, 0x10000
	s_and_b32 s23, s3, 0x10000
	s_add_i32 s23, s0, s23
	s_and_b32 s2, s2, 0x10000
	v_or_b32_e32 v142, s2, v137
	v_add_u32_e32 v143, v142, v136
	v_add_u32_e32 v142, v142, v134
	ds_read_b128 v[138:141], v143 offset:32768
	ds_read_b128 v[146:149], v143 offset:34816
	ds_read_b128 v[154:157], v143 offset:36864
	ds_read_b128 v[158:161], v143 offset:38912
	ds_read_b128 v[162:165], v142
	ds_read_b128 v[166:169], v142 offset:2048
	ds_read_b128 v[170:173], v142 offset:4096
	ds_read_b128 v[174:177], v142 offset:6144
	ds_read_b128 v[178:181], v142 offset:8192
	ds_read_b128 v[182:185], v142 offset:10240
	ds_read_b128 v[186:189], v142 offset:12288
	ds_read_b128 v[206:209], v142 offset:14336
	s_waitcnt lgkmcnt(0)
	v_mfma_f32_16x16x32_bf16 v[116:119], v[138:141], v[162:165], v[116:119]
	v_mfma_f32_16x16x32_bf16 v[108:111], v[146:149], v[162:165], v[108:111]
	v_mfma_f32_16x16x32_bf16 v[100:103], v[154:157], v[162:165], v[100:103]
	v_mfma_f32_16x16x32_bf16 v[88:91], v[158:161], v[162:165], v[88:91]
	v_mfma_f32_16x16x32_bf16 v[76:79], v[138:141], v[166:169], v[76:79]
	v_mfma_f32_16x16x32_bf16 v[68:71], v[146:149], v[166:169], v[68:71]
	v_mfma_f32_16x16x32_bf16 v[56:59], v[154:157], v[166:169], v[56:59]
	v_mfma_f32_16x16x32_bf16 v[44:47], v[158:161], v[166:169], v[44:47]
	v_mfma_f32_16x16x32_bf16 v[36:39], v[138:141], v[170:173], v[36:39]
	v_mfma_f32_16x16x32_bf16 v[32:35], v[146:149], v[170:173], v[32:35]
	v_mfma_f32_16x16x32_bf16 v[28:31], v[154:157], v[170:173], v[28:31]
	v_mfma_f32_16x16x32_bf16 v[24:27], v[158:161], v[170:173], v[24:27]
	v_mfma_f32_16x16x32_bf16 v[20:23], v[138:141], v[174:177], v[20:23]
	v_mfma_f32_16x16x32_bf16 v[16:19], v[146:149], v[174:177], v[16:19]
	v_mfma_f32_16x16x32_bf16 v[12:15], v[154:157], v[174:177], v[12:15]
	v_mfma_f32_16x16x32_bf16 v[8:11], v[158:161], v[174:177], v[8:11]
	v_or_b32_e32 v142, s2, v135
	v_add_u32_e32 v143, v142, v136
	v_add_u32_e32 v142, v142, v134
	ds_read_b128 v[162:165], v143 offset:32768
	ds_read_b128 v[166:169], v143 offset:34816
	ds_read_b128 v[170:173], v143 offset:36864
	ds_read_b128 v[174:177], v143 offset:38912
	ds_read_b128 v[216:219], v142
	ds_read_b128 v[220:223], v142 offset:2048
	ds_read_b128 v[224:227], v142 offset:4096
	ds_read_b128 v[228:231], v142 offset:6144
	v_mfma_f32_16x16x32_bf16 v[4:7], v[138:141], v[178:181], v[4:7]
	v_mfma_f32_16x16x32_bf16 v[0:3], v[146:149], v[178:181], v[0:3]
	v_mfma_f32_16x16x32_bf16 v[40:43], v[154:157], v[178:181], v[40:43]
	v_mfma_f32_16x16x32_bf16 v[48:51], v[158:161], v[178:181], v[48:51]
	v_mfma_f32_16x16x32_bf16 v[52:55], v[138:141], v[182:185], v[52:55]
	v_mfma_f32_16x16x32_bf16 v[60:63], v[146:149], v[182:185], v[60:63]
	v_mfma_f32_16x16x32_bf16 v[64:67], v[154:157], v[182:185], v[64:67]
	v_mfma_f32_16x16x32_bf16 v[72:75], v[158:161], v[182:185], v[72:75]
	v_mfma_f32_16x16x32_bf16 v[80:83], v[138:141], v[186:189], v[80:83]
	v_mfma_f32_16x16x32_bf16 v[84:87], v[146:149], v[186:189], v[84:87]
	v_mfma_f32_16x16x32_bf16 v[92:95], v[154:157], v[186:189], v[92:95]
	v_mfma_f32_16x16x32_bf16 v[96:99], v[158:161], v[186:189], v[96:99]
	v_mfma_f32_16x16x32_bf16 v[104:107], v[138:141], v[206:209], v[104:107]
	v_mfma_f32_16x16x32_bf16 v[112:115], v[146:149], v[206:209], v[112:115]
	v_mfma_f32_16x16x32_bf16 v[120:123], v[154:157], v[206:209], v[120:123]
	v_mfma_f32_16x16x32_bf16 v[124:127], v[158:161], v[206:209], v[124:127]
	v_lshl_add_u64 v[244:245], v[128:129], 0, s[34:35]
	v_lshl_add_u64 v[246:247], v[244:245], 0, s[10:11]
	s_mov_b32 m0, s23
	s_nop 0
	global_load_lds_dwordx4 v[246:247], off
	v_lshl_add_u64 v[246:247], v[244:245], 0, s[4:5]
	s_add_i32 m0, s23, 0x2000
	s_nop 0
	global_load_lds_dwordx4 v[246:247], off
	v_lshl_add_u64 v[246:247], v[244:245], 0, s[92:93]
	s_add_i32 m0, s23, 0x4000
	v_lshl_add_u64 v[244:245], v[244:245], 0, s[94:95]
	global_load_lds_dwordx4 v[246:247], off
	s_add_i32 m0, s23, 0x6000
	s_nop 0
	global_load_lds_dwordx4 v[244:245], off
	v_lshl_add_u64 v[244:245], v[130:131], 0, s[34:35]
	v_lshl_add_u64 v[246:247], v[244:245], 0, s[10:11]
	s_add_i32 m0, s23, 0x8000
	s_nop 0
	global_load_lds_dwordx4 v[246:247], off
	v_lshl_add_u64 v[246:247], v[244:245], 0, s[4:5]
	s_add_i32 m0, s23, 0xa000
	s_nop 0
	global_load_lds_dwordx4 v[246:247], off
	v_lshl_add_u64 v[246:247], v[244:245], 0, s[92:93]
	s_add_i32 m0, s23, 0xc000
	v_lshl_add_u64 v[244:245], v[244:245], 0, s[94:95]
	global_load_lds_dwordx4 v[246:247], off
	s_add_i32 m0, s23, 0xe000
	s_nop 0
	global_load_lds_dwordx4 v[244:245], off
	ds_read_b128 v[138:141], v142 offset:8192
	ds_read_b128 v[146:149], v142 offset:10240
	ds_read_b128 v[154:157], v142 offset:12288
	ds_read_b128 v[158:161], v142 offset:14336
	s_waitcnt lgkmcnt(0)
	v_mfma_f32_16x16x32_bf16 v[116:119], v[162:165], v[216:219], v[116:119]
	v_mfma_f32_16x16x32_bf16 v[108:111], v[166:169], v[216:219], v[108:111]
	v_mfma_f32_16x16x32_bf16 v[100:103], v[170:173], v[216:219], v[100:103]
	v_mfma_f32_16x16x32_bf16 v[88:91], v[174:177], v[216:219], v[88:91]
	v_mfma_f32_16x16x32_bf16 v[76:79], v[162:165], v[220:223], v[76:79]
	v_mfma_f32_16x16x32_bf16 v[68:71], v[166:169], v[220:223], v[68:71]
	v_mfma_f32_16x16x32_bf16 v[56:59], v[170:173], v[220:223], v[56:59]
	v_mfma_f32_16x16x32_bf16 v[44:47], v[174:177], v[220:223], v[44:47]
	v_mfma_f32_16x16x32_bf16 v[36:39], v[162:165], v[224:227], v[36:39]
	v_mfma_f32_16x16x32_bf16 v[32:35], v[166:169], v[224:227], v[32:35]
	v_mfma_f32_16x16x32_bf16 v[28:31], v[170:173], v[224:227], v[28:31]
	v_mfma_f32_16x16x32_bf16 v[24:27], v[174:177], v[224:227], v[24:27]
	v_mfma_f32_16x16x32_bf16 v[20:23], v[162:165], v[228:231], v[20:23]
	v_mfma_f32_16x16x32_bf16 v[16:19], v[166:169], v[228:231], v[16:19]
	v_mfma_f32_16x16x32_bf16 v[12:15], v[170:173], v[228:231], v[12:15]
	v_mfma_f32_16x16x32_bf16 v[8:11], v[174:177], v[228:231], v[8:11]
	v_mfma_f32_16x16x32_bf16 v[4:7], v[162:165], v[138:141], v[4:7]
	s_add_u32 s34, s34, 0x80
	s_addc_u32 s35, s35, 0
	v_mfma_f32_16x16x32_bf16 v[0:3], v[166:169], v[138:141], v[0:3]
	s_cmpk_eq_i32 s34, 0x780
	s_mov_b32 s2, s3
	s_waitcnt vmcnt(0)
	v_mfma_f32_16x16x32_bf16 v[40:43], v[170:173], v[138:141], v[40:43]
	s_barrier
	v_mfma_f32_16x16x32_bf16 v[48:51], v[174:177], v[138:141], v[48:51]
	v_mfma_f32_16x16x32_bf16 v[52:55], v[162:165], v[146:149], v[52:55]
	v_mfma_f32_16x16x32_bf16 v[60:63], v[166:169], v[146:149], v[60:63]
	v_mfma_f32_16x16x32_bf16 v[64:67], v[170:173], v[146:149], v[64:67]
	v_mfma_f32_16x16x32_bf16 v[72:75], v[174:177], v[146:149], v[72:75]
	v_mfma_f32_16x16x32_bf16 v[80:83], v[162:165], v[154:157], v[80:83]
	v_mfma_f32_16x16x32_bf16 v[84:87], v[166:169], v[154:157], v[84:87]
	v_mfma_f32_16x16x32_bf16 v[92:95], v[170:173], v[154:157], v[92:95]
	v_mfma_f32_16x16x32_bf16 v[96:99], v[174:177], v[154:157], v[96:99]
	v_mfma_f32_16x16x32_bf16 v[104:107], v[162:165], v[158:161], v[104:107]
	v_mfma_f32_16x16x32_bf16 v[112:115], v[166:169], v[158:161], v[112:115]
	v_mfma_f32_16x16x32_bf16 v[120:123], v[170:173], v[158:161], v[120:123]
	v_mfma_f32_16x16x32_bf16 v[124:127], v[174:177], v[158:161], v[124:127]
	s_cbranch_scc0 .Lkb_670
.Lkx_670:
	v_mov_b64_e32 v[252:253], 0x40000
	s_cmp_eq_u64 s[28:29], 0
	s_cbranch_scc1 .LBB0_673
	v_lshlrev_b64 v[128:129], 1, v[132:133]
	v_lshl_add_u64 v[130:131], s[28:29], 0, v[128:129]
	v_lshl_add_u64 v[128:129], s[30:31], 0, v[128:129]
	v_lshl_add_u64 v[130:131], v[130:131], 0, v[144:145]
	v_lshl_add_u64 v[128:129], v[128:129], 0, v[144:145]
	s_mov_b64 s[2:3], 0x20000
	s_mov_b32 m0, s0
	v_lshl_add_u64 v[132:133], v[130:131], 0, s[2:3]
	v_lshl_add_u64 v[142:143], v[128:129], 0, s[2:3]
	s_add_i32 s2, s0, 0xe000
	s_add_i32 s3, s0, 0xc000
	s_add_i32 s23, s0, 0xa000
	s_add_i32 s28, s0, 0x8000
	s_add_i32 s29, s0, 0x6000
	s_add_i32 s30, s0, 0x4000
	s_addk_i32 s0, 0x2000
	global_load_lds_dwordx4 v[130:131], off
	s_mov_b32 m0, s0
	v_lshl_add_u64 v[138:139], v[130:131], 0, s[42:43]
	global_load_lds_dwordx4 v[132:133], off
	s_mov_b32 m0, s30
	v_lshl_add_u64 v[140:141], v[130:131], 0, s[44:45]
	global_load_lds_dwordx4 v[138:139], off
	s_mov_b32 m0, s29
	v_lshl_add_u64 v[146:147], v[128:129], 0, s[42:43]
	global_load_lds_dwordx4 v[140:141], off
	s_mov_b32 m0, s28
	v_lshl_add_u64 v[148:149], v[128:129], 0, s[44:45]
	global_load_lds_dwordx4 v[128:129], off
	s_mov_b32 m0, s23
	s_mov_b64 s[86:87], 0x20000
	global_load_lds_dwordx4 v[142:143], off
	s_mov_b32 m0, s3
	s_nop 0
	global_load_lds_dwordx4 v[146:147], off
	s_mov_b32 m0, s2
	s_nop 0
	global_load_lds_dwordx4 v[148:149], off
